# v20 + LN loop waits re-placed + mixer sample-conv item first for blocks 0..127 + full-line f32 stores in the residual GEMM epilogue
# speedup vs baseline: 1.0098x; 1.0098x over previous
;     ...
;   for (int kt = 0; kt < nk; kt++) {
;     if (kt + 1 < nk) asm volatile("s_waitcnt vmcnt(6)" ::: "memory");
;     else asm volatile("s_waitcnt vmcnt(0)" ::: "memory");
;     __builtin_amdgcn_s_barrier();
;     asm volatile("" ::: "memory");
;     if (kt + 2 < nk) G2_STAGE(kt + 2);
;     const char* cS = smem + (kt % 3) * 24576;
;     bf16x8 xa[8], wb[4];
; #pragma unroll
;     for (int f = 0; f < 8; f++) xa[f] = *(const bf16x8*)(cS + aoff + f * 1024);
; #pragma unroll
;     for (int f = 0; f < 4; f++) wb[f] = *(const bf16x8*)(cS + boff + f * 1024);
; #pragma unroll
;     for (int nf = 0; nf < 4; nf++)
; #pragma unroll
;       for (int mf = 0; mf < 8; mf++)
;         acc[nf][mf] = __builtin_amdgcn_mfma_f32_16x16x32_bf16(wb[nf], xa[mf], acc[nf][mf], 0, 0, 0);
;   }
.Lt11_loop:
	.p2align 3
	s_waitcnt vmcnt(6) lgkmcnt(0)
	s_barrier
	s_setprio 1
	v_add_u32_e32 v144, s40, v136
	v_mfma_f32_16x16x32_bf16 v[126:129], v[184:187], v[146:149], v[126:129]
	ds_read_b128 v[200:203], v144 offset:0
	v_mfma_f32_16x16x32_bf16 v[122:125], v[184:187], v[152:155], v[122:125]
	ds_read_b128 v[204:207], v144 offset:1024
	v_mfma_f32_16x16x32_bf16 v[118:121], v[184:187], v[156:159], v[118:121]
	ds_read_b128 v[208:211], v144 offset:2048
	v_mfma_f32_16x16x32_bf16 v[114:117], v[184:187], v[162:165], v[114:117]
	ds_read_b128 v[212:215], v144 offset:3072
	v_mfma_f32_16x16x32_bf16 v[110:113], v[184:187], v[166:169], v[110:113]
	ds_read_b128 v[216:219], v144 offset:4096
	v_mfma_f32_16x16x32_bf16 v[106:109], v[184:187], v[170:173], v[106:109]
	ds_read_b128 v[220:223], v144 offset:5120
	v_mfma_f32_16x16x32_bf16 v[102:105], v[184:187], v[176:179], v[102:105]
	ds_read_b128 v[224:227], v144 offset:6144
	v_mfma_f32_16x16x32_bf16 v[98:101], v[184:187], v[180:183], v[98:101]
	ds_read_b128 v[228:231], v144 offset:7168
	v_mfma_f32_16x16x32_bf16 v[94:97], v[188:191], v[146:149], v[94:97]
	v_add_u32_e64 v144, s40, v137
	v_mfma_f32_16x16x32_bf16 v[90:93], v[188:191], v[152:155], v[90:93]
	v_mfma_f32_16x16x32_bf16 v[86:89], v[188:191], v[156:159], v[86:89]
	ds_read_b128 v[232:235], v144 offset:16384
	v_mfma_f32_16x16x32_bf16 v[82:85], v[188:191], v[162:165], v[82:85]
	ds_read_b128 v[236:239], v144 offset:17408
	v_mfma_f32_16x16x32_bf16 v[78:81], v[188:191], v[166:169], v[78:81]
	ds_read_b128 v[240:243], v144 offset:18432
	v_mfma_f32_16x16x32_bf16 v[74:77], v[188:191], v[170:173], v[74:77]
	ds_read_b128 v[244:247], v144 offset:19456
	v_mfma_f32_16x16x32_bf16 v[70:73], v[188:191], v[176:179], v[70:73]
	s_add_i32 s42, s46, s41
	s_mov_b32 m0, s42
	v_lshl_add_u64 v[142:143], v[132:133], 0, s[2:3]
	v_mfma_f32_16x16x32_bf16 v[66:69], v[188:191], v[180:183], v[66:69]
	global_load_lds_dwordx4 v[132:133], off
	s_add_i32 m0, m0, 0x1000
	v_mfma_f32_16x16x32_bf16 v[62:65], v[192:195], v[146:149], v[62:65]
	v_mfma_f32_16x16x32_bf16 v[58:61], v[192:195], v[152:155], v[58:61]
	v_mfma_f32_16x16x32_bf16 v[54:57], v[192:195], v[156:159], v[54:57]
	global_load_lds_dwordx4 v[142:143], off
	v_lshl_add_u64 v[142:143], v[142:143], 0, s[2:3]
	s_add_i32 m0, m0, 0x1000
	v_mfma_f32_16x16x32_bf16 v[50:53], v[192:195], v[162:165], v[50:53]
	v_mfma_f32_16x16x32_bf16 v[46:49], v[192:195], v[166:169], v[46:49]
	v_mfma_f32_16x16x32_bf16 v[42:45], v[192:195], v[170:173], v[42:45]
	global_load_lds_dwordx4 v[142:143], off
	v_lshl_add_u64 v[142:143], v[142:143], 0, s[2:3]
	s_add_i32 m0, m0, 0x1000
	v_mfma_f32_16x16x32_bf16 v[38:41], v[192:195], v[176:179], v[38:41]
	v_mfma_f32_16x16x32_bf16 v[34:37], v[192:195], v[180:183], v[34:37]
	v_mfma_f32_16x16x32_bf16 v[30:33], v[196:199], v[146:149], v[30:33]
	global_load_lds_dwordx4 v[142:143], off
	s_add_i32 m0, m0, 0x1000
	v_lshl_add_u64 v[142:143], v[134:135], 0, s[2:3]
	v_mfma_f32_16x16x32_bf16 v[26:29], v[196:199], v[152:155], v[26:29]
	v_mfma_f32_16x16x32_bf16 v[22:25], v[196:199], v[156:159], v[22:25]
	v_mfma_f32_16x16x32_bf16 v[18:21], v[196:199], v[162:165], v[18:21]
	global_load_lds_dwordx4 v[134:135], off
	s_add_i32 m0, m0, 0x1000
	v_lshl_add_u64 v[132:133], v[132:133], 0, s[12:13]
	v_mfma_f32_16x16x32_bf16 v[14:17], v[196:199], v[166:169], v[14:17]
	v_mfma_f32_16x16x32_bf16 v[10:13], v[196:199], v[170:173], v[10:13]
	v_mfma_f32_16x16x32_bf16 v[6:9], v[196:199], v[176:179], v[6:9]
	global_load_lds_dwordx4 v[142:143], off
	v_lshl_add_u64 v[134:135], v[134:135], 0, s[4:5]
	v_mfma_f32_16x16x32_bf16 v[2:5], v[196:199], v[180:183], v[2:5]
	s_setprio 0
	s_mov_b32 s41, s40
	s_add_i32 s40, s40, 0x6000
	s_cmp_eq_u32 s40, 0x12000
	s_cselect_b32 s40, 0, s40
	s_nop 0
	.p2align 3
	s_waitcnt vmcnt(6) lgkmcnt(0)
	s_barrier
	s_setprio 1
	v_add_u32_e32 v144, s40, v136
	v_mfma_f32_16x16x32_bf16 v[126:129], v[232:235], v[200:203], v[126:129]
	ds_read_b128 v[146:149], v144 offset:0
	v_mfma_f32_16x16x32_bf16 v[122:125], v[232:235], v[204:207], v[122:125]
	ds_read_b128 v[152:155], v144 offset:1024
	v_mfma_f32_16x16x32_bf16 v[118:121], v[232:235], v[208:211], v[118:121]
	ds_read_b128 v[156:159], v144 offset:2048
	v_mfma_f32_16x16x32_bf16 v[114:117], v[232:235], v[212:215], v[114:117]
	ds_read_b128 v[162:165], v144 offset:3072
	v_mfma_f32_16x16x32_bf16 v[110:113], v[232:235], v[216:219], v[110:113]
	ds_read_b128 v[166:169], v144 offset:4096
	v_mfma_f32_16x16x32_bf16 v[106:109], v[232:235], v[220:223], v[106:109]
	ds_read_b128 v[170:173], v144 offset:5120
	v_mfma_f32_16x16x32_bf16 v[102:105], v[232:235], v[224:227], v[102:105]
	ds_read_b128 v[176:179], v144 offset:6144
	v_mfma_f32_16x16x32_bf16 v[98:101], v[232:235], v[228:231], v[98:101]
	ds_read_b128 v[180:183], v144 offset:7168
	v_mfma_f32_16x16x32_bf16 v[94:97], v[236:239], v[200:203], v[94:97]
	v_add_u32_e64 v144, s40, v137
	v_mfma_f32_16x16x32_bf16 v[90:93], v[236:239], v[204:207], v[90:93]
	v_mfma_f32_16x16x32_bf16 v[86:89], v[236:239], v[208:211], v[86:89]
	ds_read_b128 v[184:187], v144 offset:16384
	v_mfma_f32_16x16x32_bf16 v[82:85], v[236:239], v[212:215], v[82:85]
	ds_read_b128 v[188:191], v144 offset:17408
	v_mfma_f32_16x16x32_bf16 v[78:81], v[236:239], v[216:219], v[78:81]
	ds_read_b128 v[192:195], v144 offset:18432
	v_mfma_f32_16x16x32_bf16 v[74:77], v[236:239], v[220:223], v[74:77]
	ds_read_b128 v[196:199], v144 offset:19456
	v_mfma_f32_16x16x32_bf16 v[70:73], v[236:239], v[224:227], v[70:73]
	s_add_i32 s42, s46, s41
	s_mov_b32 m0, s42
	v_lshl_add_u64 v[142:143], v[132:133], 0, s[2:3]
	v_mfma_f32_16x16x32_bf16 v[66:69], v[236:239], v[228:231], v[66:69]
	global_load_lds_dwordx4 v[132:133], off
;     ...
;   for (int kt = 0; kt < nk; kt++) {
;     if (kt + 1 < nk) asm volatile("s_waitcnt vmcnt(6)" ::: "memory");
;     else asm volatile("s_waitcnt vmcnt(0)" ::: "memory");
;     __builtin_amdgcn_s_barrier();
;     asm volatile("" ::: "memory");
;     if (kt + 2 < nk) G2_STAGE(kt + 2);
;     const char* cS = smem + (kt % 3) * 24576;
;     bf16x8 xa[8], wb[4];
; #pragma unroll
;     for (int f = 0; f < 8; f++) xa[f] = *(const bf16x8*)(cS + aoff + f * 1024);
; #pragma unroll
;     for (int f = 0; f < 4; f++) wb[f] = *(const bf16x8*)(cS + boff + f * 1024);
; #pragma unroll
;     for (int nf = 0; nf < 4; nf++)
; #pragma unroll
;       for (int mf = 0; mf < 8; mf++)
;         acc[nf][mf] = __builtin_amdgcn_mfma_f32_16x16x32_bf16(wb[nf], xa[mf], acc[nf][mf], 0, 0, 0);
;   }
	s_add_i32 m0, m0, 0x1000
	v_mfma_f32_16x16x32_bf16 v[62:65], v[240:243], v[200:203], v[62:65]
	v_mfma_f32_16x16x32_bf16 v[58:61], v[240:243], v[204:207], v[58:61]
	v_mfma_f32_16x16x32_bf16 v[54:57], v[240:243], v[208:211], v[54:57]
	global_load_lds_dwordx4 v[142:143], off
	v_lshl_add_u64 v[142:143], v[142:143], 0, s[2:3]
	s_add_i32 m0, m0, 0x1000
	v_mfma_f32_16x16x32_bf16 v[50:53], v[240:243], v[212:215], v[50:53]
	v_mfma_f32_16x16x32_bf16 v[46:49], v[240:243], v[216:219], v[46:49]
	v_mfma_f32_16x16x32_bf16 v[42:45], v[240:243], v[220:223], v[42:45]
	global_load_lds_dwordx4 v[142:143], off
	v_lshl_add_u64 v[142:143], v[142:143], 0, s[2:3]
	s_add_i32 m0, m0, 0x1000
	v_mfma_f32_16x16x32_bf16 v[38:41], v[240:243], v[224:227], v[38:41]
	v_mfma_f32_16x16x32_bf16 v[34:37], v[240:243], v[228:231], v[34:37]
	v_mfma_f32_16x16x32_bf16 v[30:33], v[244:247], v[200:203], v[30:33]
	global_load_lds_dwordx4 v[142:143], off
	s_add_i32 m0, m0, 0x1000
	v_lshl_add_u64 v[142:143], v[134:135], 0, s[2:3]
	v_mfma_f32_16x16x32_bf16 v[26:29], v[244:247], v[204:207], v[26:29]
	v_mfma_f32_16x16x32_bf16 v[22:25], v[244:247], v[208:211], v[22:25]
	v_mfma_f32_16x16x32_bf16 v[18:21], v[244:247], v[212:215], v[18:21]
	global_load_lds_dwordx4 v[134:135], off
	s_add_i32 m0, m0, 0x1000
	v_lshl_add_u64 v[132:133], v[132:133], 0, s[12:13]
	v_mfma_f32_16x16x32_bf16 v[14:17], v[244:247], v[216:219], v[14:17]
	v_mfma_f32_16x16x32_bf16 v[10:13], v[244:247], v[220:223], v[10:13]
	v_mfma_f32_16x16x32_bf16 v[6:9], v[244:247], v[224:227], v[6:9]
	global_load_lds_dwordx4 v[142:143], off
	v_lshl_add_u64 v[134:135], v[134:135], 0, s[4:5]
	v_mfma_f32_16x16x32_bf16 v[2:5], v[244:247], v[228:231], v[2:5]
	s_setprio 0
	s_mov_b32 s41, s40
	s_add_i32 s40, s40, 0x6000
	s_cmp_eq_u32 s40, 0x12000
	s_cselect_b32 s40, 0, s40
	s_nop 0
	s_sub_i32 s39, s39, 1
	s_cmp_lg_u32 s39, 0
	s_cbranch_scc1 .Lt11_loop
	.p2align 3
	s_waitcnt vmcnt(6) lgkmcnt(0)
	s_barrier
	s_setprio 1
	v_add_u32_e32 v144, s40, v136
	v_mfma_f32_16x16x32_bf16 v[126:129], v[184:187], v[146:149], v[126:129]
	ds_read_b128 v[200:203], v144 offset:0
	v_mfma_f32_16x16x32_bf16 v[122:125], v[184:187], v[152:155], v[122:125]
	ds_read_b128 v[204:207], v144 offset:1024
	v_mfma_f32_16x16x32_bf16 v[118:121], v[184:187], v[156:159], v[118:121]
	ds_read_b128 v[208:211], v144 offset:2048
	v_mfma_f32_16x16x32_bf16 v[114:117], v[184:187], v[162:165], v[114:117]
	ds_read_b128 v[212:215], v144 offset:3072
	v_mfma_f32_16x16x32_bf16 v[110:113], v[184:187], v[166:169], v[110:113]
	ds_read_b128 v[216:219], v144 offset:4096
	v_mfma_f32_16x16x32_bf16 v[106:109], v[184:187], v[170:173], v[106:109]
	ds_read_b128 v[220:223], v144 offset:5120
	v_mfma_f32_16x16x32_bf16 v[102:105], v[184:187], v[176:179], v[102:105]
	ds_read_b128 v[224:227], v144 offset:6144
	v_mfma_f32_16x16x32_bf16 v[98:101], v[184:187], v[180:183], v[98:101]
	ds_read_b128 v[228:231], v144 offset:7168
	v_mfma_f32_16x16x32_bf16 v[94:97], v[188:191], v[146:149], v[94:97]
	v_add_u32_e64 v144, s40, v137
	v_mfma_f32_16x16x32_bf16 v[90:93], v[188:191], v[152:155], v[90:93]
	v_mfma_f32_16x16x32_bf16 v[86:89], v[188:191], v[156:159], v[86:89]
	ds_read_b128 v[232:235], v144 offset:16384
	v_mfma_f32_16x16x32_bf16 v[82:85], v[188:191], v[162:165], v[82:85]
	ds_read_b128 v[236:239], v144 offset:17408
	v_mfma_f32_16x16x32_bf16 v[78:81], v[188:191], v[166:169], v[78:81]
	ds_read_b128 v[240:243], v144 offset:18432
	v_mfma_f32_16x16x32_bf16 v[74:77], v[188:191], v[170:173], v[74:77]
	ds_read_b128 v[244:247], v144 offset:19456
	v_mfma_f32_16x16x32_bf16 v[70:73], v[188:191], v[176:179], v[70:73]
	s_add_i32 s42, s46, s41
	s_mov_b32 m0, s42
	v_lshl_add_u64 v[142:143], v[132:133], 0, s[2:3]
	v_mfma_f32_16x16x32_bf16 v[66:69], v[188:191], v[180:183], v[66:69]
	global_load_lds_dwordx4 v[132:133], off
	s_add_i32 m0, m0, 0x1000
	v_mfma_f32_16x16x32_bf16 v[62:65], v[192:195], v[146:149], v[62:65]
	v_mfma_f32_16x16x32_bf16 v[58:61], v[192:195], v[152:155], v[58:61]
	v_mfma_f32_16x16x32_bf16 v[54:57], v[192:195], v[156:159], v[54:57]
	global_load_lds_dwordx4 v[142:143], off
	v_lshl_add_u64 v[142:143], v[142:143], 0, s[2:3]
	s_add_i32 m0, m0, 0x1000
	v_mfma_f32_16x16x32_bf16 v[50:53], v[192:195], v[162:165], v[50:53]
	v_mfma_f32_16x16x32_bf16 v[46:49], v[192:195], v[166:169], v[46:49]
	v_mfma_f32_16x16x32_bf16 v[42:45], v[192:195], v[170:173], v[42:45]
	global_load_lds_dwordx4 v[142:143], off
	v_lshl_add_u64 v[142:143], v[142:143], 0, s[2:3]
	s_add_i32 m0, m0, 0x1000
	v_mfma_f32_16x16x32_bf16 v[38:41], v[192:195], v[176:179], v[38:41]
	v_mfma_f32_16x16x32_bf16 v[34:37], v[192:195], v[180:183], v[34:37]
	v_mfma_f32_16x16x32_bf16 v[30:33], v[196:199], v[146:149], v[30:33]
	global_load_lds_dwordx4 v[142:143], off
	s_add_i32 m0, m0, 0x1000
	v_lshl_add_u64 v[142:143], v[134:135], 0, s[2:3]
	v_mfma_f32_16x16x32_bf16 v[26:29], v[196:199], v[152:155], v[26:29]
	v_mfma_f32_16x16x32_bf16 v[22:25], v[196:199], v[156:159], v[22:25]
	v_mfma_f32_16x16x32_bf16 v[18:21], v[196:199], v[162:165], v[18:21]
	global_load_lds_dwordx4 v[134:135], off
	s_add_i32 m0, m0, 0x1000
	v_lshl_add_u64 v[132:133], v[132:133], 0, s[12:13]
	v_mfma_f32_16x16x32_bf16 v[14:17], v[196:199], v[166:169], v[14:17]
	v_mfma_f32_16x16x32_bf16 v[10:13], v[196:199], v[170:173], v[10:13]
	v_mfma_f32_16x16x32_bf16 v[6:9], v[196:199], v[176:179], v[6:9]
	global_load_lds_dwordx4 v[142:143], off
	v_lshl_add_u64 v[134:135], v[134:135], 0, s[4:5]
	v_mfma_f32_16x16x32_bf16 v[2:5], v[196:199], v[180:183], v[2:5]
	s_setprio 0
	s_mov_b32 s41, s40
	s_add_i32 s40, s40, 0x6000
	s_cmp_eq_u32 s40, 0x12000
	s_cselect_b32 s40, 0, s40
	s_nop 0
	.p2align 3
	s_waitcnt vmcnt(6) lgkmcnt(0)
	s_barrier
;     ...
;   for (int kt = 0; kt < nk; kt++) {
;     if (kt + 1 < nk) asm volatile("s_waitcnt vmcnt(6)" ::: "memory");
;     else asm volatile("s_waitcnt vmcnt(0)" ::: "memory");
;     __builtin_amdgcn_s_barrier();
;     asm volatile("" ::: "memory");
;     if (kt + 2 < nk) G2_STAGE(kt + 2);
;     const char* cS = smem + (kt % 3) * 24576;
;     bf16x8 xa[8], wb[4];
; #pragma unroll
;     for (int f = 0; f < 8; f++) xa[f] = *(const bf16x8*)(cS + aoff + f * 1024);
; #pragma unroll
;     for (int f = 0; f < 4; f++) wb[f] = *(const bf16x8*)(cS + boff + f * 1024);
; #pragma unroll
;     for (int nf = 0; nf < 4; nf++)
; #pragma unroll
;       for (int mf = 0; mf < 8; mf++)
;         acc[nf][mf] = __builtin_amdgcn_mfma_f32_16x16x32_bf16(wb[nf], xa[mf], acc[nf][mf], 0, 0, 0);
;   }
	s_setprio 1
	v_add_u32_e32 v144, s40, v136
	v_mfma_f32_16x16x32_bf16 v[126:129], v[232:235], v[200:203], v[126:129]
	ds_read_b128 v[146:149], v144 offset:0
	v_mfma_f32_16x16x32_bf16 v[122:125], v[232:235], v[204:207], v[122:125]
	ds_read_b128 v[152:155], v144 offset:1024
	v_mfma_f32_16x16x32_bf16 v[118:121], v[232:235], v[208:211], v[118:121]
	ds_read_b128 v[156:159], v144 offset:2048
	v_mfma_f32_16x16x32_bf16 v[114:117], v[232:235], v[212:215], v[114:117]
	ds_read_b128 v[162:165], v144 offset:3072
	v_mfma_f32_16x16x32_bf16 v[110:113], v[232:235], v[216:219], v[110:113]
	ds_read_b128 v[166:169], v144 offset:4096
	v_mfma_f32_16x16x32_bf16 v[106:109], v[232:235], v[220:223], v[106:109]
	ds_read_b128 v[170:173], v144 offset:5120
	v_mfma_f32_16x16x32_bf16 v[102:105], v[232:235], v[224:227], v[102:105]
	ds_read_b128 v[176:179], v144 offset:6144
	v_mfma_f32_16x16x32_bf16 v[98:101], v[232:235], v[228:231], v[98:101]
	ds_read_b128 v[180:183], v144 offset:7168
	v_mfma_f32_16x16x32_bf16 v[94:97], v[236:239], v[200:203], v[94:97]
	v_add_u32_e64 v144, s40, v137
	v_mfma_f32_16x16x32_bf16 v[90:93], v[236:239], v[204:207], v[90:93]
	v_mfma_f32_16x16x32_bf16 v[86:89], v[236:239], v[208:211], v[86:89]
	ds_read_b128 v[184:187], v144 offset:16384
	v_mfma_f32_16x16x32_bf16 v[82:85], v[236:239], v[212:215], v[82:85]
	ds_read_b128 v[188:191], v144 offset:17408
	v_mfma_f32_16x16x32_bf16 v[78:81], v[236:239], v[216:219], v[78:81]
	ds_read_b128 v[192:195], v144 offset:18432
	v_mfma_f32_16x16x32_bf16 v[74:77], v[236:239], v[220:223], v[74:77]
	ds_read_b128 v[196:199], v144 offset:19456
	v_mfma_f32_16x16x32_bf16 v[70:73], v[236:239], v[224:227], v[70:73]
	v_mfma_f32_16x16x32_bf16 v[66:69], v[236:239], v[228:231], v[66:69]
	v_mfma_f32_16x16x32_bf16 v[62:65], v[240:243], v[200:203], v[62:65]
	v_mfma_f32_16x16x32_bf16 v[58:61], v[240:243], v[204:207], v[58:61]
	v_mfma_f32_16x16x32_bf16 v[54:57], v[240:243], v[208:211], v[54:57]
	v_mfma_f32_16x16x32_bf16 v[50:53], v[240:243], v[212:215], v[50:53]
	v_mfma_f32_16x16x32_bf16 v[46:49], v[240:243], v[216:219], v[46:49]
	v_mfma_f32_16x16x32_bf16 v[42:45], v[240:243], v[220:223], v[42:45]
	v_mfma_f32_16x16x32_bf16 v[38:41], v[240:243], v[224:227], v[38:41]
	v_mfma_f32_16x16x32_bf16 v[34:37], v[240:243], v[228:231], v[34:37]
	v_mfma_f32_16x16x32_bf16 v[30:33], v[244:247], v[200:203], v[30:33]
	v_mfma_f32_16x16x32_bf16 v[26:29], v[244:247], v[204:207], v[26:29]
	v_mfma_f32_16x16x32_bf16 v[22:25], v[244:247], v[208:211], v[22:25]
	v_mfma_f32_16x16x32_bf16 v[18:21], v[244:247], v[212:215], v[18:21]
	v_mfma_f32_16x16x32_bf16 v[14:17], v[244:247], v[216:219], v[14:17]
	v_mfma_f32_16x16x32_bf16 v[10:13], v[244:247], v[220:223], v[10:13]
	v_mfma_f32_16x16x32_bf16 v[6:9], v[244:247], v[224:227], v[6:9]
	v_mfma_f32_16x16x32_bf16 v[2:5], v[244:247], v[228:231], v[2:5]
	s_setprio 0
	s_mov_b32 s41, s40
	s_add_i32 s40, s40, 0x6000
	s_cmp_eq_u32 s40, 0x12000
	s_cselect_b32 s40, 0, s40
	s_nop 0
	.p2align 3
	s_waitcnt vmcnt(0) lgkmcnt(0)
	s_barrier
	s_setprio 1
	v_add_u32_e32 v144, s40, v136
	v_mfma_f32_16x16x32_bf16 v[126:129], v[184:187], v[146:149], v[126:129]
	ds_read_b128 v[200:203], v144 offset:0
	v_mfma_f32_16x16x32_bf16 v[122:125], v[184:187], v[152:155], v[122:125]
	ds_read_b128 v[204:207], v144 offset:1024
	v_mfma_f32_16x16x32_bf16 v[118:121], v[184:187], v[156:159], v[118:121]
	ds_read_b128 v[208:211], v144 offset:2048
	v_mfma_f32_16x16x32_bf16 v[114:117], v[184:187], v[162:165], v[114:117]
	ds_read_b128 v[212:215], v144 offset:3072
	v_mfma_f32_16x16x32_bf16 v[110:113], v[184:187], v[166:169], v[110:113]
	ds_read_b128 v[216:219], v144 offset:4096
	v_mfma_f32_16x16x32_bf16 v[106:109], v[184:187], v[170:173], v[106:109]
	ds_read_b128 v[220:223], v144 offset:5120
	v_mfma_f32_16x16x32_bf16 v[102:105], v[184:187], v[176:179], v[102:105]
	ds_read_b128 v[224:227], v144 offset:6144
	v_mfma_f32_16x16x32_bf16 v[98:101], v[184:187], v[180:183], v[98:101]
	ds_read_b128 v[228:231], v144 offset:7168
	v_mfma_f32_16x16x32_bf16 v[94:97], v[188:191], v[146:149], v[94:97]
	v_add_u32_e64 v144, s40, v137
	v_mfma_f32_16x16x32_bf16 v[90:93], v[188:191], v[152:155], v[90:93]
	v_mfma_f32_16x16x32_bf16 v[86:89], v[188:191], v[156:159], v[86:89]
	ds_read_b128 v[232:235], v144 offset:16384
	v_mfma_f32_16x16x32_bf16 v[82:85], v[188:191], v[162:165], v[82:85]
	ds_read_b128 v[236:239], v144 offset:17408
	v_mfma_f32_16x16x32_bf16 v[78:81], v[188:191], v[166:169], v[78:81]
	ds_read_b128 v[240:243], v144 offset:18432
	v_mfma_f32_16x16x32_bf16 v[74:77], v[188:191], v[170:173], v[74:77]
	ds_read_b128 v[244:247], v144 offset:19456
	v_mfma_f32_16x16x32_bf16 v[70:73], v[188:191], v[176:179], v[70:73]
	v_mfma_f32_16x16x32_bf16 v[66:69], v[188:191], v[180:183], v[66:69]
	v_mfma_f32_16x16x32_bf16 v[62:65], v[192:195], v[146:149], v[62:65]
	v_mfma_f32_16x16x32_bf16 v[58:61], v[192:195], v[152:155], v[58:61]
	v_mfma_f32_16x16x32_bf16 v[54:57], v[192:195], v[156:159], v[54:57]
	v_mfma_f32_16x16x32_bf16 v[50:53], v[192:195], v[162:165], v[50:53]
	v_mfma_f32_16x16x32_bf16 v[46:49], v[192:195], v[166:169], v[46:49]
	v_mfma_f32_16x16x32_bf16 v[42:45], v[192:195], v[170:173], v[42:45]
	v_mfma_f32_16x16x32_bf16 v[38:41], v[192:195], v[176:179], v[38:41]
	v_mfma_f32_16x16x32_bf16 v[34:37], v[192:195], v[180:183], v[34:37]
	v_mfma_f32_16x16x32_bf16 v[30:33], v[196:199], v[146:149], v[30:33]
	v_mfma_f32_16x16x32_bf16 v[26:29], v[196:199], v[152:155], v[26:29]
	v_mfma_f32_16x16x32_bf16 v[22:25], v[196:199], v[156:159], v[22:25]
	v_mfma_f32_16x16x32_bf16 v[18:21], v[196:199], v[162:165], v[18:21]
	v_mfma_f32_16x16x32_bf16 v[14:17], v[196:199], v[166:169], v[14:17]
	v_mfma_f32_16x16x32_bf16 v[10:13], v[196:199], v[170:173], v[10:13]
	v_mfma_f32_16x16x32_bf16 v[6:9], v[196:199], v[176:179], v[6:9]
	v_mfma_f32_16x16x32_bf16 v[2:5], v[196:199], v[180:183], v[2:5]
	s_setprio 0
	s_mov_b32 s41, s40
	s_add_i32 s40, s40, 0x6000
	s_cmp_eq_u32 s40, 0x12000
	s_cselect_b32 s40, 0, s40
	s_nop 0
	s_mov_b32 s4, 0x8000
	s_mov_b32 s5, 0
	s_mov_b32 s10, 0x10000
	s_mov_b32 s11, 0
	s_mov_b32 s44, 0x3fd744fd
	.p2align 3
	s_waitcnt lgkmcnt(0)
; DEVI float blo(unsigned u) { return __uint_as_float(u << 16); }
; DEVI float bhi(unsigned u) { return __uint_as_float(u & 0xffff0000u); }
;     ...
;     for (int nf = 0; nf < 4; nf++)
; #pragma unroll
;       for (int mf = 0; mf < 8; mf++)
;         acc[nf][mf] = __builtin_amdgcn_mfma_f32_16x16x32_bf16(wb[nf], xa[mf], acc[nf][mf], 0, 0, 0);
;     ...
; #pragma unroll
;       for (int nf = 0; nf < 4; nf++) {
;         const int col = n0 + wn * 64 + nf * 16 + quad * 4;
;         f32x4 a = acc[nf][mf];
;         if (EPI == EPI_RESID || EPI == EPI_RESID_ATOMIC) {
;           f32x4 x = a;
;           if (EPI == EPI_RESID || kpart == 0) {
;             const u32x2 xr = *(const u32x2*)((const u16*)(p.ws + WS_XB) + (size_t)row * 1024 + col);
;             x[0] += ALPHA * blo(xr[0]); x[1] += ALPHA * bhi(xr[0]); x[2] += ALPHA * blo(xr[1]); x[3] += ALPHA * bhi(xr[1]);
;           }
;           if (EPI == EPI_RESID) *(f32x4*)((float*)(p.ws + WS_XF) + (size_t)row * 1024 + col) = x;
;           else *(f32x4*)((float*)(p.ws + WS_SLAB) + ((size_t)kpart * 512 + (row - T_P)) * 1024 + col) = x;
	s_nop 0
	v_mfma_f32_16x16x32_bf16 v[126:129], v[232:235], v[200:203], v[126:129]
	v_mfma_f32_16x16x32_bf16 v[122:125], v[232:235], v[204:207], v[122:125]
	v_mfma_f32_16x16x32_bf16 v[118:121], v[232:235], v[208:211], v[118:121]
	v_mfma_f32_16x16x32_bf16 v[114:117], v[232:235], v[212:215], v[114:117]
	v_mfma_f32_16x16x32_bf16 v[110:113], v[232:235], v[216:219], v[110:113]
	global_load_dwordx4 v[146:149], v[138:139], off offset:0
	v_mfma_f32_16x16x32_bf16 v[106:109], v[232:235], v[220:223], v[106:109]
	v_mfma_f32_16x16x32_bf16 v[102:105], v[232:235], v[224:227], v[102:105]
	global_load_dwordx4 v[152:155], v[138:139], off offset:128
	v_mfma_f32_16x16x32_bf16 v[98:101], v[232:235], v[228:231], v[98:101]
	v_lshl_add_u64 v[138:139], v[138:139], 0, s[4:5]
	v_mfma_f32_16x16x32_bf16 v[94:97], v[236:239], v[200:203], v[94:97]
	global_load_dwordx4 v[156:159], v[138:139], off offset:0
	v_mfma_f32_16x16x32_bf16 v[90:93], v[236:239], v[204:207], v[90:93]
	v_mfma_f32_16x16x32_bf16 v[86:89], v[236:239], v[208:211], v[86:89]
	global_load_dwordx4 v[162:165], v[138:139], off offset:128
	v_mfma_f32_16x16x32_bf16 v[82:85], v[236:239], v[212:215], v[82:85]
	v_lshl_add_u64 v[138:139], v[138:139], 0, s[4:5]
	v_mfma_f32_16x16x32_bf16 v[78:81], v[236:239], v[216:219], v[78:81]
	global_load_dwordx4 v[166:169], v[138:139], off offset:0
	v_mfma_f32_16x16x32_bf16 v[74:77], v[236:239], v[220:223], v[74:77]
	v_mfma_f32_16x16x32_bf16 v[70:73], v[236:239], v[224:227], v[70:73]
	global_load_dwordx4 v[170:173], v[138:139], off offset:128
	v_mfma_f32_16x16x32_bf16 v[66:69], v[236:239], v[228:231], v[66:69]
	v_lshl_add_u64 v[138:139], v[138:139], 0, s[4:5]
	v_mfma_f32_16x16x32_bf16 v[62:65], v[240:243], v[200:203], v[62:65]
	global_load_dwordx4 v[176:179], v[138:139], off offset:0
	v_mfma_f32_16x16x32_bf16 v[58:61], v[240:243], v[204:207], v[58:61]
	v_mfma_f32_16x16x32_bf16 v[54:57], v[240:243], v[208:211], v[54:57]
	global_load_dwordx4 v[180:183], v[138:139], off offset:128
	v_mfma_f32_16x16x32_bf16 v[50:53], v[240:243], v[212:215], v[50:53]
	v_lshl_add_u64 v[138:139], v[138:139], 0, s[4:5]
	v_mfma_f32_16x16x32_bf16 v[46:49], v[240:243], v[216:219], v[46:49]
	global_load_dwordx4 v[184:187], v[138:139], off offset:0
	v_mfma_f32_16x16x32_bf16 v[42:45], v[240:243], v[220:223], v[42:45]
	v_mfma_f32_16x16x32_bf16 v[38:41], v[240:243], v[224:227], v[38:41]
	global_load_dwordx4 v[188:191], v[138:139], off offset:128
	v_mfma_f32_16x16x32_bf16 v[34:37], v[240:243], v[228:231], v[34:37]
	v_lshl_add_u64 v[138:139], v[138:139], 0, s[4:5]
	v_mfma_f32_16x16x32_bf16 v[30:33], v[244:247], v[200:203], v[30:33]
	global_load_dwordx4 v[192:195], v[138:139], off offset:0
	v_mfma_f32_16x16x32_bf16 v[26:29], v[244:247], v[204:207], v[26:29]
	v_mfma_f32_16x16x32_bf16 v[22:25], v[244:247], v[208:211], v[22:25]
	global_load_dwordx4 v[196:199], v[138:139], off offset:128
	v_mfma_f32_16x16x32_bf16 v[18:21], v[244:247], v[212:215], v[18:21]
	v_lshl_add_u64 v[138:139], v[138:139], 0, s[4:5]
	v_mfma_f32_16x16x32_bf16 v[14:17], v[244:247], v[216:219], v[14:17]
	v_mfma_f32_16x16x32_bf16 v[10:13], v[244:247], v[220:223], v[10:13]
	v_mfma_f32_16x16x32_bf16 v[6:9], v[244:247], v[224:227], v[6:9]
	v_mfma_f32_16x16x32_bf16 v[2:5], v[244:247], v[228:231], v[2:5]
	s_mov_b32 m0, s43
	global_load_dwordx4 v[200:203], v[138:139], off offset:0
	global_load_dwordx4 v[204:207], v[138:139], off offset:128
	v_lshl_add_u64 v[138:139], v[138:139], 0, s[4:5]
	global_load_dwordx4 v[208:211], v[138:139], off offset:0
	global_load_dwordx4 v[212:215], v[138:139], off offset:128
	v_lshl_add_u64 v[138:139], v[138:139], 0, s[4:5]
	s_nop 7
	v_and_b32_e32 v228, 1, v145
	v_cmp_ne_u32_e32 vcc, 0, v228
	v_mov_b32_e32 v229, 0xfffff040
	v_cndmask_b32_e32 v230, 0, v229, vcc
	v_ashrrev_i32_e32 v231, 31, v230
	v_lshl_add_u64 v[140:141], v[140:141], 0, v[230:231]
	v_add_co_u32_e32 v142, vcc, 0x1000, v140
	s_nop 0
	v_addc_co_u32_e32 v143, vcc, 0, v141, vcc
	v_cmp_ne_u32_e32 vcc, 0, v228
	s_waitcnt vmcnt(15)
	v_permlane16_swap_b32_e32 v146, v148
	v_permlane16_swap_b32_e32 v147, v149
	v_lshlrev_b32_e32 v216, 16, v146
	v_and_b32_e32 v146, 0xffff0000, v146
	v_lshlrev_b32_e32 v217, 16, v147
	v_and_b32_e32 v147, 0xffff0000, v147
	v_fmac_f32_e32 v126, s44, v216
	v_fmac_f32_e32 v127, s44, v146
	v_fmac_f32_e32 v128, s44, v217
	v_fmac_f32_e32 v129, s44, v147
	v_lshlrev_b32_e32 v216, 16, v148
	v_and_b32_e32 v148, 0xffff0000, v148
	v_lshlrev_b32_e32 v217, 16, v149
	v_and_b32_e32 v149, 0xffff0000, v149
	v_fmac_f32_e32 v94, s44, v216
	v_fmac_f32_e32 v95, s44, v148
	v_fmac_f32_e32 v96, s44, v217
	v_fmac_f32_e32 v97, s44, v149
	v_mov_b32_dpp v220, v94 quad_perm:[1,0,3,2] row_mask:0xf bank_mask:0xf
	v_mov_b32_dpp v221, v95 quad_perm:[1,0,3,2] row_mask:0xf bank_mask:0xf
	v_mov_b32_dpp v222, v96 quad_perm:[1,0,3,2] row_mask:0xf bank_mask:0xf
	v_mov_b32_dpp v223, v97 quad_perm:[1,0,3,2] row_mask:0xf bank_mask:0xf
	v_mov_b32_dpp v224, v126 quad_perm:[1,0,3,2] row_mask:0xf bank_mask:0xf
	v_mov_b32_dpp v225, v127 quad_perm:[1,0,3,2] row_mask:0xf bank_mask:0xf
	v_mov_b32_dpp v226, v128 quad_perm:[1,0,3,2] row_mask:0xf bank_mask:0xf
	v_mov_b32_dpp v227, v129 quad_perm:[1,0,3,2] row_mask:0xf bank_mask:0xf
	v_cndmask_b32_e32 v94, v224, v94, vcc
	v_cndmask_b32_e32 v95, v225, v95, vcc
	v_cndmask_b32_e32 v96, v226, v96, vcc
	v_cndmask_b32_e32 v97, v227, v97, vcc
	v_cndmask_b32_e32 v126, v126, v220, vcc
	v_cndmask_b32_e32 v127, v127, v221, vcc
	v_cndmask_b32_e32 v128, v128, v222, vcc
	v_cndmask_b32_e32 v129, v129, v223, vcc
	global_store_dwordx4 v[140:141], v[126:129], off
	global_store_dwordx4 v[142:143], v[94:97], off
	s_waitcnt vmcnt(16)
; DEVI float blo(unsigned u) { return __uint_as_float(u << 16); }
; DEVI float bhi(unsigned u) { return __uint_as_float(u & 0xffff0000u); }
;     ...
; #pragma unroll
;       for (int nf = 0; nf < 4; nf++) {
;         const int col = n0 + wn * 64 + nf * 16 + quad * 4;
;         f32x4 a = acc[nf][mf];
;         if (EPI == EPI_RESID || EPI == EPI_RESID_ATOMIC) {
;           f32x4 x = a;
;           if (EPI == EPI_RESID || kpart == 0) {
;             const u32x2 xr = *(const u32x2*)((const u16*)(p.ws + WS_XB) + (size_t)row * 1024 + col);
;             x[0] += ALPHA * blo(xr[0]); x[1] += ALPHA * bhi(xr[0]); x[2] += ALPHA * blo(xr[1]); x[3] += ALPHA * bhi(xr[1]);
;           }
;           if (EPI == EPI_RESID) *(f32x4*)((float*)(p.ws + WS_XF) + (size_t)row * 1024 + col) = x;
;           else *(f32x4*)((float*)(p.ws + WS_SLAB) + ((size_t)kpart * 512 + (row - T_P)) * 1024 + col) = x;
	v_permlane16_swap_b32_e32 v152, v154
	v_permlane16_swap_b32_e32 v153, v155
	v_lshlrev_b32_e32 v216, 16, v152
	v_and_b32_e32 v152, 0xffff0000, v152
	v_lshlrev_b32_e32 v217, 16, v153
	v_and_b32_e32 v153, 0xffff0000, v153
	v_fmac_f32_e32 v62, s44, v216
	v_fmac_f32_e32 v63, s44, v152
	v_fmac_f32_e32 v64, s44, v217
	v_fmac_f32_e32 v65, s44, v153
	v_lshlrev_b32_e32 v216, 16, v154
	v_and_b32_e32 v154, 0xffff0000, v154
	v_lshlrev_b32_e32 v217, 16, v155
	v_and_b32_e32 v155, 0xffff0000, v155
	v_fmac_f32_e32 v30, s44, v216
	v_fmac_f32_e32 v31, s44, v154
	v_fmac_f32_e32 v32, s44, v217
	v_fmac_f32_e32 v33, s44, v155
	v_mov_b32_dpp v220, v30 quad_perm:[1,0,3,2] row_mask:0xf bank_mask:0xf
	v_mov_b32_dpp v221, v31 quad_perm:[1,0,3,2] row_mask:0xf bank_mask:0xf
	v_mov_b32_dpp v222, v32 quad_perm:[1,0,3,2] row_mask:0xf bank_mask:0xf
	v_mov_b32_dpp v223, v33 quad_perm:[1,0,3,2] row_mask:0xf bank_mask:0xf
	v_mov_b32_dpp v224, v62 quad_perm:[1,0,3,2] row_mask:0xf bank_mask:0xf
	v_mov_b32_dpp v225, v63 quad_perm:[1,0,3,2] row_mask:0xf bank_mask:0xf
	v_mov_b32_dpp v226, v64 quad_perm:[1,0,3,2] row_mask:0xf bank_mask:0xf
	v_mov_b32_dpp v227, v65 quad_perm:[1,0,3,2] row_mask:0xf bank_mask:0xf
	v_cndmask_b32_e32 v30, v224, v30, vcc
	v_cndmask_b32_e32 v31, v225, v31, vcc
	v_cndmask_b32_e32 v32, v226, v32, vcc
	v_cndmask_b32_e32 v33, v227, v33, vcc
	v_cndmask_b32_e32 v62, v62, v220, vcc
	v_cndmask_b32_e32 v63, v63, v221, vcc
	v_cndmask_b32_e32 v64, v64, v222, vcc
	v_cndmask_b32_e32 v65, v65, v223, vcc
	global_store_dwordx4 v[140:141], v[62:65], off offset:128
	global_store_dwordx4 v[142:143], v[30:33], off offset:128
	v_lshl_add_u64 v[140:141], v[140:141], 0, s[10:11]
	v_lshl_add_u64 v[142:143], v[142:143], 0, s[10:11]
	s_waitcnt vmcnt(17)
	v_permlane16_swap_b32_e32 v156, v158
	v_permlane16_swap_b32_e32 v157, v159
	v_lshlrev_b32_e32 v216, 16, v156
	v_and_b32_e32 v156, 0xffff0000, v156
	v_lshlrev_b32_e32 v217, 16, v157
	v_and_b32_e32 v157, 0xffff0000, v157
	v_fmac_f32_e32 v122, s44, v216
	v_fmac_f32_e32 v123, s44, v156
	v_fmac_f32_e32 v124, s44, v217
	v_fmac_f32_e32 v125, s44, v157
	v_lshlrev_b32_e32 v216, 16, v158
	v_and_b32_e32 v158, 0xffff0000, v158
	v_lshlrev_b32_e32 v217, 16, v159
	v_and_b32_e32 v159, 0xffff0000, v159
	v_fmac_f32_e32 v90, s44, v216
	v_fmac_f32_e32 v91, s44, v158
	v_fmac_f32_e32 v92, s44, v217
	v_fmac_f32_e32 v93, s44, v159
	v_mov_b32_dpp v220, v90 quad_perm:[1,0,3,2] row_mask:0xf bank_mask:0xf
	v_mov_b32_dpp v221, v91 quad_perm:[1,0,3,2] row_mask:0xf bank_mask:0xf
	v_mov_b32_dpp v222, v92 quad_perm:[1,0,3,2] row_mask:0xf bank_mask:0xf
	v_mov_b32_dpp v223, v93 quad_perm:[1,0,3,2] row_mask:0xf bank_mask:0xf
	v_mov_b32_dpp v224, v122 quad_perm:[1,0,3,2] row_mask:0xf bank_mask:0xf
	v_mov_b32_dpp v225, v123 quad_perm:[1,0,3,2] row_mask:0xf bank_mask:0xf
	v_mov_b32_dpp v226, v124 quad_perm:[1,0,3,2] row_mask:0xf bank_mask:0xf
	v_mov_b32_dpp v227, v125 quad_perm:[1,0,3,2] row_mask:0xf bank_mask:0xf
	v_cndmask_b32_e32 v90, v224, v90, vcc
	v_cndmask_b32_e32 v91, v225, v91, vcc
	v_cndmask_b32_e32 v92, v226, v92, vcc
	v_cndmask_b32_e32 v93, v227, v93, vcc
	v_cndmask_b32_e32 v122, v122, v220, vcc
	v_cndmask_b32_e32 v123, v123, v221, vcc
	v_cndmask_b32_e32 v124, v124, v222, vcc
	v_cndmask_b32_e32 v125, v125, v223, vcc
	global_store_dwordx4 v[140:141], v[122:125], off
	global_store_dwordx4 v[142:143], v[90:93], off
	s_waitcnt vmcnt(18)
	v_permlane16_swap_b32_e32 v162, v164
	v_permlane16_swap_b32_e32 v163, v165
	v_lshlrev_b32_e32 v216, 16, v162
	v_and_b32_e32 v162, 0xffff0000, v162
	v_lshlrev_b32_e32 v217, 16, v163
	v_and_b32_e32 v163, 0xffff0000, v163
	v_fmac_f32_e32 v58, s44, v216
	v_fmac_f32_e32 v59, s44, v162
	v_fmac_f32_e32 v60, s44, v217
	v_fmac_f32_e32 v61, s44, v163
	v_lshlrev_b32_e32 v216, 16, v164
	v_and_b32_e32 v164, 0xffff0000, v164
	v_lshlrev_b32_e32 v217, 16, v165
	v_and_b32_e32 v165, 0xffff0000, v165
	v_fmac_f32_e32 v26, s44, v216
	v_fmac_f32_e32 v27, s44, v164
	v_fmac_f32_e32 v28, s44, v217
	v_fmac_f32_e32 v29, s44, v165
	v_mov_b32_dpp v220, v26 quad_perm:[1,0,3,2] row_mask:0xf bank_mask:0xf
	v_mov_b32_dpp v221, v27 quad_perm:[1,0,3,2] row_mask:0xf bank_mask:0xf
	v_mov_b32_dpp v222, v28 quad_perm:[1,0,3,2] row_mask:0xf bank_mask:0xf
	v_mov_b32_dpp v223, v29 quad_perm:[1,0,3,2] row_mask:0xf bank_mask:0xf
	v_mov_b32_dpp v224, v58 quad_perm:[1,0,3,2] row_mask:0xf bank_mask:0xf
	v_mov_b32_dpp v225, v59 quad_perm:[1,0,3,2] row_mask:0xf bank_mask:0xf
	v_mov_b32_dpp v226, v60 quad_perm:[1,0,3,2] row_mask:0xf bank_mask:0xf
	v_mov_b32_dpp v227, v61 quad_perm:[1,0,3,2] row_mask:0xf bank_mask:0xf
	v_cndmask_b32_e32 v26, v224, v26, vcc
	v_cndmask_b32_e32 v27, v225, v27, vcc
	v_cndmask_b32_e32 v28, v226, v28, vcc
	v_cndmask_b32_e32 v29, v227, v29, vcc
	v_cndmask_b32_e32 v58, v58, v220, vcc
	v_cndmask_b32_e32 v59, v59, v221, vcc
	v_cndmask_b32_e32 v60, v60, v222, vcc
	v_cndmask_b32_e32 v61, v61, v223, vcc
	global_store_dwordx4 v[140:141], v[58:61], off offset:128
	global_store_dwordx4 v[142:143], v[26:29], off offset:128
	v_lshl_add_u64 v[140:141], v[140:141], 0, s[10:11]
	v_lshl_add_u64 v[142:143], v[142:143], 0, s[10:11]
	s_waitcnt vmcnt(19)
; DEVI float blo(unsigned u) { return __uint_as_float(u << 16); }
; DEVI float bhi(unsigned u) { return __uint_as_float(u & 0xffff0000u); }
;     ...
; #pragma unroll
;       for (int nf = 0; nf < 4; nf++) {
;         const int col = n0 + wn * 64 + nf * 16 + quad * 4;
;         f32x4 a = acc[nf][mf];
;         if (EPI == EPI_RESID || EPI == EPI_RESID_ATOMIC) {
;           f32x4 x = a;
;           if (EPI == EPI_RESID || kpart == 0) {
;             const u32x2 xr = *(const u32x2*)((const u16*)(p.ws + WS_XB) + (size_t)row * 1024 + col);
;             x[0] += ALPHA * blo(xr[0]); x[1] += ALPHA * bhi(xr[0]); x[2] += ALPHA * blo(xr[1]); x[3] += ALPHA * bhi(xr[1]);
;           }
;           if (EPI == EPI_RESID) *(f32x4*)((float*)(p.ws + WS_XF) + (size_t)row * 1024 + col) = x;
;           else *(f32x4*)((float*)(p.ws + WS_SLAB) + ((size_t)kpart * 512 + (row - T_P)) * 1024 + col) = x;
	v_permlane16_swap_b32_e32 v166, v168
	v_permlane16_swap_b32_e32 v167, v169
	v_lshlrev_b32_e32 v216, 16, v166
	v_and_b32_e32 v166, 0xffff0000, v166
	v_lshlrev_b32_e32 v217, 16, v167
	v_and_b32_e32 v167, 0xffff0000, v167
	v_fmac_f32_e32 v118, s44, v216
	v_fmac_f32_e32 v119, s44, v166
	v_fmac_f32_e32 v120, s44, v217
	v_fmac_f32_e32 v121, s44, v167
	v_lshlrev_b32_e32 v216, 16, v168
	v_and_b32_e32 v168, 0xffff0000, v168
	v_lshlrev_b32_e32 v217, 16, v169
	v_and_b32_e32 v169, 0xffff0000, v169
	v_fmac_f32_e32 v86, s44, v216
	v_fmac_f32_e32 v87, s44, v168
	v_fmac_f32_e32 v88, s44, v217
	v_fmac_f32_e32 v89, s44, v169
	v_mov_b32_dpp v220, v86 quad_perm:[1,0,3,2] row_mask:0xf bank_mask:0xf
	v_mov_b32_dpp v221, v87 quad_perm:[1,0,3,2] row_mask:0xf bank_mask:0xf
	v_mov_b32_dpp v222, v88 quad_perm:[1,0,3,2] row_mask:0xf bank_mask:0xf
	v_mov_b32_dpp v223, v89 quad_perm:[1,0,3,2] row_mask:0xf bank_mask:0xf
	v_mov_b32_dpp v224, v118 quad_perm:[1,0,3,2] row_mask:0xf bank_mask:0xf
	v_mov_b32_dpp v225, v119 quad_perm:[1,0,3,2] row_mask:0xf bank_mask:0xf
	v_mov_b32_dpp v226, v120 quad_perm:[1,0,3,2] row_mask:0xf bank_mask:0xf
	v_mov_b32_dpp v227, v121 quad_perm:[1,0,3,2] row_mask:0xf bank_mask:0xf
	v_cndmask_b32_e32 v86, v224, v86, vcc
	v_cndmask_b32_e32 v87, v225, v87, vcc
	v_cndmask_b32_e32 v88, v226, v88, vcc
	v_cndmask_b32_e32 v89, v227, v89, vcc
	v_cndmask_b32_e32 v118, v118, v220, vcc
	v_cndmask_b32_e32 v119, v119, v221, vcc
	v_cndmask_b32_e32 v120, v120, v222, vcc
	v_cndmask_b32_e32 v121, v121, v223, vcc
	global_store_dwordx4 v[140:141], v[118:121], off
	global_store_dwordx4 v[142:143], v[86:89], off
	s_waitcnt vmcnt(20)
	v_permlane16_swap_b32_e32 v170, v172
	v_permlane16_swap_b32_e32 v171, v173
	v_lshlrev_b32_e32 v216, 16, v170
	v_and_b32_e32 v170, 0xffff0000, v170
	v_lshlrev_b32_e32 v217, 16, v171
	v_and_b32_e32 v171, 0xffff0000, v171
	v_fmac_f32_e32 v54, s44, v216
	v_fmac_f32_e32 v55, s44, v170
	v_fmac_f32_e32 v56, s44, v217
	v_fmac_f32_e32 v57, s44, v171
	v_lshlrev_b32_e32 v216, 16, v172
	v_and_b32_e32 v172, 0xffff0000, v172
	v_lshlrev_b32_e32 v217, 16, v173
	v_and_b32_e32 v173, 0xffff0000, v173
	v_fmac_f32_e32 v22, s44, v216
	v_fmac_f32_e32 v23, s44, v172
	v_fmac_f32_e32 v24, s44, v217
	v_fmac_f32_e32 v25, s44, v173
	v_mov_b32_dpp v220, v22 quad_perm:[1,0,3,2] row_mask:0xf bank_mask:0xf
	v_mov_b32_dpp v221, v23 quad_perm:[1,0,3,2] row_mask:0xf bank_mask:0xf
	v_mov_b32_dpp v222, v24 quad_perm:[1,0,3,2] row_mask:0xf bank_mask:0xf
	v_mov_b32_dpp v223, v25 quad_perm:[1,0,3,2] row_mask:0xf bank_mask:0xf
	v_mov_b32_dpp v224, v54 quad_perm:[1,0,3,2] row_mask:0xf bank_mask:0xf
	v_mov_b32_dpp v225, v55 quad_perm:[1,0,3,2] row_mask:0xf bank_mask:0xf
	v_mov_b32_dpp v226, v56 quad_perm:[1,0,3,2] row_mask:0xf bank_mask:0xf
	v_mov_b32_dpp v227, v57 quad_perm:[1,0,3,2] row_mask:0xf bank_mask:0xf
	v_cndmask_b32_e32 v22, v224, v22, vcc
	v_cndmask_b32_e32 v23, v225, v23, vcc
	v_cndmask_b32_e32 v24, v226, v24, vcc
	v_cndmask_b32_e32 v25, v227, v25, vcc
	v_cndmask_b32_e32 v54, v54, v220, vcc
	v_cndmask_b32_e32 v55, v55, v221, vcc
	v_cndmask_b32_e32 v56, v56, v222, vcc
	v_cndmask_b32_e32 v57, v57, v223, vcc
	global_store_dwordx4 v[140:141], v[54:57], off offset:128
	global_store_dwordx4 v[142:143], v[22:25], off offset:128
	v_lshl_add_u64 v[140:141], v[140:141], 0, s[10:11]
	v_lshl_add_u64 v[142:143], v[142:143], 0, s[10:11]
	s_waitcnt vmcnt(21)
	v_permlane16_swap_b32_e32 v176, v178
	v_permlane16_swap_b32_e32 v177, v179
	v_lshlrev_b32_e32 v216, 16, v176
	v_and_b32_e32 v176, 0xffff0000, v176
	v_lshlrev_b32_e32 v217, 16, v177
	v_and_b32_e32 v177, 0xffff0000, v177
	v_fmac_f32_e32 v114, s44, v216
	v_fmac_f32_e32 v115, s44, v176
	v_fmac_f32_e32 v116, s44, v217
	v_fmac_f32_e32 v117, s44, v177
	v_lshlrev_b32_e32 v216, 16, v178
	v_and_b32_e32 v178, 0xffff0000, v178
	v_lshlrev_b32_e32 v217, 16, v179
	v_and_b32_e32 v179, 0xffff0000, v179
	v_fmac_f32_e32 v82, s44, v216
	v_fmac_f32_e32 v83, s44, v178
	v_fmac_f32_e32 v84, s44, v217
	v_fmac_f32_e32 v85, s44, v179
	v_mov_b32_dpp v220, v82 quad_perm:[1,0,3,2] row_mask:0xf bank_mask:0xf
	v_mov_b32_dpp v221, v83 quad_perm:[1,0,3,2] row_mask:0xf bank_mask:0xf
	v_mov_b32_dpp v222, v84 quad_perm:[1,0,3,2] row_mask:0xf bank_mask:0xf
	v_mov_b32_dpp v223, v85 quad_perm:[1,0,3,2] row_mask:0xf bank_mask:0xf
	v_mov_b32_dpp v224, v114 quad_perm:[1,0,3,2] row_mask:0xf bank_mask:0xf
	v_mov_b32_dpp v225, v115 quad_perm:[1,0,3,2] row_mask:0xf bank_mask:0xf
	v_mov_b32_dpp v226, v116 quad_perm:[1,0,3,2] row_mask:0xf bank_mask:0xf
	v_mov_b32_dpp v227, v117 quad_perm:[1,0,3,2] row_mask:0xf bank_mask:0xf
	v_cndmask_b32_e32 v82, v224, v82, vcc
	v_cndmask_b32_e32 v83, v225, v83, vcc
	v_cndmask_b32_e32 v84, v226, v84, vcc
	v_cndmask_b32_e32 v85, v227, v85, vcc
	v_cndmask_b32_e32 v114, v114, v220, vcc
	v_cndmask_b32_e32 v115, v115, v221, vcc
	v_cndmask_b32_e32 v116, v116, v222, vcc
	v_cndmask_b32_e32 v117, v117, v223, vcc
	global_store_dwordx4 v[140:141], v[114:117], off
	global_store_dwordx4 v[142:143], v[82:85], off
	s_waitcnt vmcnt(22)
; DEVI float blo(unsigned u) { return __uint_as_float(u << 16); }
; DEVI float bhi(unsigned u) { return __uint_as_float(u & 0xffff0000u); }
;     ...
; #pragma unroll
;       for (int nf = 0; nf < 4; nf++) {
;         const int col = n0 + wn * 64 + nf * 16 + quad * 4;
;         f32x4 a = acc[nf][mf];
;         if (EPI == EPI_RESID || EPI == EPI_RESID_ATOMIC) {
;           f32x4 x = a;
;           if (EPI == EPI_RESID || kpart == 0) {
;             const u32x2 xr = *(const u32x2*)((const u16*)(p.ws + WS_XB) + (size_t)row * 1024 + col);
;             x[0] += ALPHA * blo(xr[0]); x[1] += ALPHA * bhi(xr[0]); x[2] += ALPHA * blo(xr[1]); x[3] += ALPHA * bhi(xr[1]);
;           }
;           if (EPI == EPI_RESID) *(f32x4*)((float*)(p.ws + WS_XF) + (size_t)row * 1024 + col) = x;
;           else *(f32x4*)((float*)(p.ws + WS_SLAB) + ((size_t)kpart * 512 + (row - T_P)) * 1024 + col) = x;
	v_permlane16_swap_b32_e32 v180, v182
	v_permlane16_swap_b32_e32 v181, v183
	v_lshlrev_b32_e32 v216, 16, v180
	v_and_b32_e32 v180, 0xffff0000, v180
	v_lshlrev_b32_e32 v217, 16, v181
	v_and_b32_e32 v181, 0xffff0000, v181
	v_fmac_f32_e32 v50, s44, v216
	v_fmac_f32_e32 v51, s44, v180
	v_fmac_f32_e32 v52, s44, v217
	v_fmac_f32_e32 v53, s44, v181
	v_lshlrev_b32_e32 v216, 16, v182
	v_and_b32_e32 v182, 0xffff0000, v182
	v_lshlrev_b32_e32 v217, 16, v183
	v_and_b32_e32 v183, 0xffff0000, v183
	v_fmac_f32_e32 v18, s44, v216
	v_fmac_f32_e32 v19, s44, v182
	v_fmac_f32_e32 v20, s44, v217
	v_fmac_f32_e32 v21, s44, v183
	v_mov_b32_dpp v220, v18 quad_perm:[1,0,3,2] row_mask:0xf bank_mask:0xf
	v_mov_b32_dpp v221, v19 quad_perm:[1,0,3,2] row_mask:0xf bank_mask:0xf
	v_mov_b32_dpp v222, v20 quad_perm:[1,0,3,2] row_mask:0xf bank_mask:0xf
	v_mov_b32_dpp v223, v21 quad_perm:[1,0,3,2] row_mask:0xf bank_mask:0xf
	v_mov_b32_dpp v224, v50 quad_perm:[1,0,3,2] row_mask:0xf bank_mask:0xf
	v_mov_b32_dpp v225, v51 quad_perm:[1,0,3,2] row_mask:0xf bank_mask:0xf
	v_mov_b32_dpp v226, v52 quad_perm:[1,0,3,2] row_mask:0xf bank_mask:0xf
	v_mov_b32_dpp v227, v53 quad_perm:[1,0,3,2] row_mask:0xf bank_mask:0xf
	v_cndmask_b32_e32 v18, v224, v18, vcc
	v_cndmask_b32_e32 v19, v225, v19, vcc
	v_cndmask_b32_e32 v20, v226, v20, vcc
	v_cndmask_b32_e32 v21, v227, v21, vcc
	v_cndmask_b32_e32 v50, v50, v220, vcc
	v_cndmask_b32_e32 v51, v51, v221, vcc
	v_cndmask_b32_e32 v52, v52, v222, vcc
	v_cndmask_b32_e32 v53, v53, v223, vcc
	global_store_dwordx4 v[140:141], v[50:53], off offset:128
	global_store_dwordx4 v[142:143], v[18:21], off offset:128
	v_lshl_add_u64 v[140:141], v[140:141], 0, s[10:11]
	v_lshl_add_u64 v[142:143], v[142:143], 0, s[10:11]
	s_waitcnt vmcnt(23)
	v_permlane16_swap_b32_e32 v184, v186
	v_permlane16_swap_b32_e32 v185, v187
	v_lshlrev_b32_e32 v216, 16, v184
	v_and_b32_e32 v184, 0xffff0000, v184
	v_lshlrev_b32_e32 v217, 16, v185
	v_and_b32_e32 v185, 0xffff0000, v185
	v_fmac_f32_e32 v110, s44, v216
	v_fmac_f32_e32 v111, s44, v184
	v_fmac_f32_e32 v112, s44, v217
	v_fmac_f32_e32 v113, s44, v185
	v_lshlrev_b32_e32 v216, 16, v186
	v_and_b32_e32 v186, 0xffff0000, v186
	v_lshlrev_b32_e32 v217, 16, v187
	v_and_b32_e32 v187, 0xffff0000, v187
	v_fmac_f32_e32 v78, s44, v216
	v_fmac_f32_e32 v79, s44, v186
	v_fmac_f32_e32 v80, s44, v217
	v_fmac_f32_e32 v81, s44, v187
	v_mov_b32_dpp v220, v78 quad_perm:[1,0,3,2] row_mask:0xf bank_mask:0xf
	v_mov_b32_dpp v221, v79 quad_perm:[1,0,3,2] row_mask:0xf bank_mask:0xf
	v_mov_b32_dpp v222, v80 quad_perm:[1,0,3,2] row_mask:0xf bank_mask:0xf
	v_mov_b32_dpp v223, v81 quad_perm:[1,0,3,2] row_mask:0xf bank_mask:0xf
	v_mov_b32_dpp v224, v110 quad_perm:[1,0,3,2] row_mask:0xf bank_mask:0xf
	v_mov_b32_dpp v225, v111 quad_perm:[1,0,3,2] row_mask:0xf bank_mask:0xf
	v_mov_b32_dpp v226, v112 quad_perm:[1,0,3,2] row_mask:0xf bank_mask:0xf
	v_mov_b32_dpp v227, v113 quad_perm:[1,0,3,2] row_mask:0xf bank_mask:0xf
	v_cndmask_b32_e32 v78, v224, v78, vcc
	v_cndmask_b32_e32 v79, v225, v79, vcc
	v_cndmask_b32_e32 v80, v226, v80, vcc
	v_cndmask_b32_e32 v81, v227, v81, vcc
	v_cndmask_b32_e32 v110, v110, v220, vcc
	v_cndmask_b32_e32 v111, v111, v221, vcc
	v_cndmask_b32_e32 v112, v112, v222, vcc
	v_cndmask_b32_e32 v113, v113, v223, vcc
	global_store_dwordx4 v[140:141], v[110:113], off
	global_store_dwordx4 v[142:143], v[78:81], off
	s_waitcnt vmcnt(24)
	v_permlane16_swap_b32_e32 v188, v190
	v_permlane16_swap_b32_e32 v189, v191
	v_lshlrev_b32_e32 v216, 16, v188
	v_and_b32_e32 v188, 0xffff0000, v188
	v_lshlrev_b32_e32 v217, 16, v189
	v_and_b32_e32 v189, 0xffff0000, v189
	v_fmac_f32_e32 v46, s44, v216
	v_fmac_f32_e32 v47, s44, v188
	v_fmac_f32_e32 v48, s44, v217
	v_fmac_f32_e32 v49, s44, v189
	v_lshlrev_b32_e32 v216, 16, v190
	v_and_b32_e32 v190, 0xffff0000, v190
	v_lshlrev_b32_e32 v217, 16, v191
	v_and_b32_e32 v191, 0xffff0000, v191
	v_fmac_f32_e32 v14, s44, v216
	v_fmac_f32_e32 v15, s44, v190
	v_fmac_f32_e32 v16, s44, v217
	v_fmac_f32_e32 v17, s44, v191
	v_mov_b32_dpp v220, v14 quad_perm:[1,0,3,2] row_mask:0xf bank_mask:0xf
	v_mov_b32_dpp v221, v15 quad_perm:[1,0,3,2] row_mask:0xf bank_mask:0xf
	v_mov_b32_dpp v222, v16 quad_perm:[1,0,3,2] row_mask:0xf bank_mask:0xf
	v_mov_b32_dpp v223, v17 quad_perm:[1,0,3,2] row_mask:0xf bank_mask:0xf
	v_mov_b32_dpp v224, v46 quad_perm:[1,0,3,2] row_mask:0xf bank_mask:0xf
	v_mov_b32_dpp v225, v47 quad_perm:[1,0,3,2] row_mask:0xf bank_mask:0xf
	v_mov_b32_dpp v226, v48 quad_perm:[1,0,3,2] row_mask:0xf bank_mask:0xf
	v_mov_b32_dpp v227, v49 quad_perm:[1,0,3,2] row_mask:0xf bank_mask:0xf
	v_cndmask_b32_e32 v14, v224, v14, vcc
	v_cndmask_b32_e32 v15, v225, v15, vcc
	v_cndmask_b32_e32 v16, v226, v16, vcc
	v_cndmask_b32_e32 v17, v227, v17, vcc
	v_cndmask_b32_e32 v46, v46, v220, vcc
	v_cndmask_b32_e32 v47, v47, v221, vcc
	v_cndmask_b32_e32 v48, v48, v222, vcc
	v_cndmask_b32_e32 v49, v49, v223, vcc
	global_store_dwordx4 v[140:141], v[46:49], off offset:128
	global_store_dwordx4 v[142:143], v[14:17], off offset:128
	v_lshl_add_u64 v[140:141], v[140:141], 0, s[10:11]
	v_lshl_add_u64 v[142:143], v[142:143], 0, s[10:11]
	s_waitcnt vmcnt(25)
; DEVI float blo(unsigned u) { return __uint_as_float(u << 16); }
; DEVI float bhi(unsigned u) { return __uint_as_float(u & 0xffff0000u); }
;     ...
; #pragma unroll
;       for (int nf = 0; nf < 4; nf++) {
;         const int col = n0 + wn * 64 + nf * 16 + quad * 4;
;         f32x4 a = acc[nf][mf];
;         if (EPI == EPI_RESID || EPI == EPI_RESID_ATOMIC) {
;           f32x4 x = a;
;           if (EPI == EPI_RESID || kpart == 0) {
;             const u32x2 xr = *(const u32x2*)((const u16*)(p.ws + WS_XB) + (size_t)row * 1024 + col);
;             x[0] += ALPHA * blo(xr[0]); x[1] += ALPHA * bhi(xr[0]); x[2] += ALPHA * blo(xr[1]); x[3] += ALPHA * bhi(xr[1]);
;           }
;           if (EPI == EPI_RESID) *(f32x4*)((float*)(p.ws + WS_XF) + (size_t)row * 1024 + col) = x;
;           else *(f32x4*)((float*)(p.ws + WS_SLAB) + ((size_t)kpart * 512 + (row - T_P)) * 1024 + col) = x;
	v_permlane16_swap_b32_e32 v192, v194
	v_permlane16_swap_b32_e32 v193, v195
	v_lshlrev_b32_e32 v216, 16, v192
	v_and_b32_e32 v192, 0xffff0000, v192
	v_lshlrev_b32_e32 v217, 16, v193
	v_and_b32_e32 v193, 0xffff0000, v193
	v_fmac_f32_e32 v106, s44, v216
	v_fmac_f32_e32 v107, s44, v192
	v_fmac_f32_e32 v108, s44, v217
	v_fmac_f32_e32 v109, s44, v193
	v_lshlrev_b32_e32 v216, 16, v194
	v_and_b32_e32 v194, 0xffff0000, v194
	v_lshlrev_b32_e32 v217, 16, v195
	v_and_b32_e32 v195, 0xffff0000, v195
	v_fmac_f32_e32 v74, s44, v216
	v_fmac_f32_e32 v75, s44, v194
	v_fmac_f32_e32 v76, s44, v217
	v_fmac_f32_e32 v77, s44, v195
	v_mov_b32_dpp v220, v74 quad_perm:[1,0,3,2] row_mask:0xf bank_mask:0xf
	v_mov_b32_dpp v221, v75 quad_perm:[1,0,3,2] row_mask:0xf bank_mask:0xf
	v_mov_b32_dpp v222, v76 quad_perm:[1,0,3,2] row_mask:0xf bank_mask:0xf
	v_mov_b32_dpp v223, v77 quad_perm:[1,0,3,2] row_mask:0xf bank_mask:0xf
	v_mov_b32_dpp v224, v106 quad_perm:[1,0,3,2] row_mask:0xf bank_mask:0xf
	v_mov_b32_dpp v225, v107 quad_perm:[1,0,3,2] row_mask:0xf bank_mask:0xf
	v_mov_b32_dpp v226, v108 quad_perm:[1,0,3,2] row_mask:0xf bank_mask:0xf
	v_mov_b32_dpp v227, v109 quad_perm:[1,0,3,2] row_mask:0xf bank_mask:0xf
	v_cndmask_b32_e32 v74, v224, v74, vcc
	v_cndmask_b32_e32 v75, v225, v75, vcc
	v_cndmask_b32_e32 v76, v226, v76, vcc
	v_cndmask_b32_e32 v77, v227, v77, vcc
	v_cndmask_b32_e32 v106, v106, v220, vcc
	v_cndmask_b32_e32 v107, v107, v221, vcc
	v_cndmask_b32_e32 v108, v108, v222, vcc
	v_cndmask_b32_e32 v109, v109, v223, vcc
	global_store_dwordx4 v[140:141], v[106:109], off
	global_store_dwordx4 v[142:143], v[74:77], off
	s_waitcnt vmcnt(26)
	v_permlane16_swap_b32_e32 v196, v198
	v_permlane16_swap_b32_e32 v197, v199
	v_lshlrev_b32_e32 v216, 16, v196
	v_and_b32_e32 v196, 0xffff0000, v196
	v_lshlrev_b32_e32 v217, 16, v197
	v_and_b32_e32 v197, 0xffff0000, v197
	v_fmac_f32_e32 v42, s44, v216
	v_fmac_f32_e32 v43, s44, v196
	v_fmac_f32_e32 v44, s44, v217
	v_fmac_f32_e32 v45, s44, v197
	v_lshlrev_b32_e32 v216, 16, v198
	v_and_b32_e32 v198, 0xffff0000, v198
	v_lshlrev_b32_e32 v217, 16, v199
	v_and_b32_e32 v199, 0xffff0000, v199
	v_fmac_f32_e32 v10, s44, v216
	v_fmac_f32_e32 v11, s44, v198
	v_fmac_f32_e32 v12, s44, v217
	v_fmac_f32_e32 v13, s44, v199
	v_mov_b32_dpp v220, v10 quad_perm:[1,0,3,2] row_mask:0xf bank_mask:0xf
	v_mov_b32_dpp v221, v11 quad_perm:[1,0,3,2] row_mask:0xf bank_mask:0xf
	v_mov_b32_dpp v222, v12 quad_perm:[1,0,3,2] row_mask:0xf bank_mask:0xf
	v_mov_b32_dpp v223, v13 quad_perm:[1,0,3,2] row_mask:0xf bank_mask:0xf
	v_mov_b32_dpp v224, v42 quad_perm:[1,0,3,2] row_mask:0xf bank_mask:0xf
	v_mov_b32_dpp v225, v43 quad_perm:[1,0,3,2] row_mask:0xf bank_mask:0xf
	v_mov_b32_dpp v226, v44 quad_perm:[1,0,3,2] row_mask:0xf bank_mask:0xf
	v_mov_b32_dpp v227, v45 quad_perm:[1,0,3,2] row_mask:0xf bank_mask:0xf
	v_cndmask_b32_e32 v10, v224, v10, vcc
	v_cndmask_b32_e32 v11, v225, v11, vcc
	v_cndmask_b32_e32 v12, v226, v12, vcc
	v_cndmask_b32_e32 v13, v227, v13, vcc
	v_cndmask_b32_e32 v42, v42, v220, vcc
	v_cndmask_b32_e32 v43, v43, v221, vcc
	v_cndmask_b32_e32 v44, v44, v222, vcc
	v_cndmask_b32_e32 v45, v45, v223, vcc
	global_store_dwordx4 v[140:141], v[42:45], off offset:128
	global_store_dwordx4 v[142:143], v[10:13], off offset:128
	v_lshl_add_u64 v[140:141], v[140:141], 0, s[10:11]
	v_lshl_add_u64 v[142:143], v[142:143], 0, s[10:11]
	s_waitcnt vmcnt(27)
	v_permlane16_swap_b32_e32 v200, v202
	v_permlane16_swap_b32_e32 v201, v203
	v_lshlrev_b32_e32 v216, 16, v200
	v_and_b32_e32 v200, 0xffff0000, v200
	v_lshlrev_b32_e32 v217, 16, v201
	v_and_b32_e32 v201, 0xffff0000, v201
	v_fmac_f32_e32 v102, s44, v216
	v_fmac_f32_e32 v103, s44, v200
	v_fmac_f32_e32 v104, s44, v217
	v_fmac_f32_e32 v105, s44, v201
	v_lshlrev_b32_e32 v216, 16, v202
	v_and_b32_e32 v202, 0xffff0000, v202
	v_lshlrev_b32_e32 v217, 16, v203
	v_and_b32_e32 v203, 0xffff0000, v203
	v_fmac_f32_e32 v70, s44, v216
	v_fmac_f32_e32 v71, s44, v202
	v_fmac_f32_e32 v72, s44, v217
	v_fmac_f32_e32 v73, s44, v203
	v_mov_b32_dpp v220, v70 quad_perm:[1,0,3,2] row_mask:0xf bank_mask:0xf
	v_mov_b32_dpp v221, v71 quad_perm:[1,0,3,2] row_mask:0xf bank_mask:0xf
	v_mov_b32_dpp v222, v72 quad_perm:[1,0,3,2] row_mask:0xf bank_mask:0xf
	v_mov_b32_dpp v223, v73 quad_perm:[1,0,3,2] row_mask:0xf bank_mask:0xf
	v_mov_b32_dpp v224, v102 quad_perm:[1,0,3,2] row_mask:0xf bank_mask:0xf
	v_mov_b32_dpp v225, v103 quad_perm:[1,0,3,2] row_mask:0xf bank_mask:0xf
	v_mov_b32_dpp v226, v104 quad_perm:[1,0,3,2] row_mask:0xf bank_mask:0xf
	v_mov_b32_dpp v227, v105 quad_perm:[1,0,3,2] row_mask:0xf bank_mask:0xf
	v_cndmask_b32_e32 v70, v224, v70, vcc
	v_cndmask_b32_e32 v71, v225, v71, vcc
	v_cndmask_b32_e32 v72, v226, v72, vcc
	v_cndmask_b32_e32 v73, v227, v73, vcc
	v_cndmask_b32_e32 v102, v102, v220, vcc
	v_cndmask_b32_e32 v103, v103, v221, vcc
	v_cndmask_b32_e32 v104, v104, v222, vcc
	v_cndmask_b32_e32 v105, v105, v223, vcc
	global_store_dwordx4 v[140:141], v[102:105], off
	global_store_dwordx4 v[142:143], v[70:73], off
	s_waitcnt vmcnt(28)
; DEVI float blo(unsigned u) { return __uint_as_float(u << 16); }
; DEVI float bhi(unsigned u) { return __uint_as_float(u & 0xffff0000u); }
; DEVI int xcd_first_tile() { return (blockIdx.x & 7) * (gridDim.x >> 3) + (blockIdx.x >> 3); }
;     ...
; #pragma unroll
;       for (int nf = 0; nf < 4; nf++) {
;         const int col = n0 + wn * 64 + nf * 16 + quad * 4;
;         f32x4 a = acc[nf][mf];
;         if (EPI == EPI_RESID || EPI == EPI_RESID_ATOMIC) {
;           f32x4 x = a;
;           if (EPI == EPI_RESID || kpart == 0) {
;             const u32x2 xr = *(const u32x2*)((const u16*)(p.ws + WS_XB) + (size_t)row * 1024 + col);
;             x[0] += ALPHA * blo(xr[0]); x[1] += ALPHA * bhi(xr[0]); x[2] += ALPHA * blo(xr[1]); x[3] += ALPHA * bhi(xr[1]);
;           }
;           if (EPI == EPI_RESID) *(f32x4*)((float*)(p.ws + WS_XF) + (size_t)row * 1024 + col) = x;
;           else *(f32x4*)((float*)(p.ws + WS_SLAB) + ((size_t)kpart * 512 + (row - T_P)) * 1024 + col) = x;
; DEVI void run_phase(const Params& p, int ph, char* smem) {
;     ...
;       for (int t = xcd_first_tile(); t < 512 + 16 * 11; t += xcd_tile_step()) {
;         if (t < 512) {
;           int mt_, nt_; tile_coords(t, 64, 8, mt_, nt_);
;           gemm_tile256<EPI_RESID>(p, hb, DFF, Bt, DFF, mt_ * 256, nt_ * 128, nullptr, 0, smem);
;         } else {
;           const int u_ = t - 512, tl_ = u_ / 11, q_ = u_ - tl_ * 11;
;           gemm_tile256<EPI_RESID_ATOMIC>(p, hb, DFF, Bt, DFF, (64 + (tl_ & 1)) * 256, (tl_ >> 1) * 128, nullptr, 0, smem, q_ * 256, 8, q_);
	v_permlane16_swap_b32_e32 v204, v206
	v_permlane16_swap_b32_e32 v205, v207
	v_lshlrev_b32_e32 v216, 16, v204
	v_and_b32_e32 v204, 0xffff0000, v204
	v_lshlrev_b32_e32 v217, 16, v205
	v_and_b32_e32 v205, 0xffff0000, v205
	v_fmac_f32_e32 v38, s44, v216
	v_fmac_f32_e32 v39, s44, v204
	v_fmac_f32_e32 v40, s44, v217
	v_fmac_f32_e32 v41, s44, v205
	v_lshlrev_b32_e32 v216, 16, v206
	v_and_b32_e32 v206, 0xffff0000, v206
	v_lshlrev_b32_e32 v217, 16, v207
	v_and_b32_e32 v207, 0xffff0000, v207
	v_fmac_f32_e32 v6, s44, v216
	v_fmac_f32_e32 v7, s44, v206
	v_fmac_f32_e32 v8, s44, v217
	v_fmac_f32_e32 v9, s44, v207
	v_mov_b32_dpp v220, v6 quad_perm:[1,0,3,2] row_mask:0xf bank_mask:0xf
	v_mov_b32_dpp v221, v7 quad_perm:[1,0,3,2] row_mask:0xf bank_mask:0xf
	v_mov_b32_dpp v222, v8 quad_perm:[1,0,3,2] row_mask:0xf bank_mask:0xf
	v_mov_b32_dpp v223, v9 quad_perm:[1,0,3,2] row_mask:0xf bank_mask:0xf
	v_mov_b32_dpp v224, v38 quad_perm:[1,0,3,2] row_mask:0xf bank_mask:0xf
	v_mov_b32_dpp v225, v39 quad_perm:[1,0,3,2] row_mask:0xf bank_mask:0xf
	v_mov_b32_dpp v226, v40 quad_perm:[1,0,3,2] row_mask:0xf bank_mask:0xf
	v_mov_b32_dpp v227, v41 quad_perm:[1,0,3,2] row_mask:0xf bank_mask:0xf
	v_cndmask_b32_e32 v6, v224, v6, vcc
	v_cndmask_b32_e32 v7, v225, v7, vcc
	v_cndmask_b32_e32 v8, v226, v8, vcc
	v_cndmask_b32_e32 v9, v227, v9, vcc
	v_cndmask_b32_e32 v38, v38, v220, vcc
	v_cndmask_b32_e32 v39, v39, v221, vcc
	v_cndmask_b32_e32 v40, v40, v222, vcc
	v_cndmask_b32_e32 v41, v41, v223, vcc
	global_store_dwordx4 v[140:141], v[38:41], off offset:128
	global_store_dwordx4 v[142:143], v[6:9], off offset:128
	v_lshl_add_u64 v[140:141], v[140:141], 0, s[10:11]
	v_lshl_add_u64 v[142:143], v[142:143], 0, s[10:11]
	s_waitcnt vmcnt(29)
	v_permlane16_swap_b32_e32 v208, v210
	v_permlane16_swap_b32_e32 v209, v211
	v_lshlrev_b32_e32 v216, 16, v208
	v_and_b32_e32 v208, 0xffff0000, v208
	v_lshlrev_b32_e32 v217, 16, v209
	v_and_b32_e32 v209, 0xffff0000, v209
	v_fmac_f32_e32 v98, s44, v216
	v_fmac_f32_e32 v99, s44, v208
	v_fmac_f32_e32 v100, s44, v217
	v_fmac_f32_e32 v101, s44, v209
	v_lshlrev_b32_e32 v216, 16, v210
	v_and_b32_e32 v210, 0xffff0000, v210
	v_lshlrev_b32_e32 v217, 16, v211
	v_and_b32_e32 v211, 0xffff0000, v211
	v_fmac_f32_e32 v66, s44, v216
	v_fmac_f32_e32 v67, s44, v210
	v_fmac_f32_e32 v68, s44, v217
	v_fmac_f32_e32 v69, s44, v211
	v_mov_b32_dpp v220, v66 quad_perm:[1,0,3,2] row_mask:0xf bank_mask:0xf
	v_mov_b32_dpp v221, v67 quad_perm:[1,0,3,2] row_mask:0xf bank_mask:0xf
	v_mov_b32_dpp v222, v68 quad_perm:[1,0,3,2] row_mask:0xf bank_mask:0xf
	v_mov_b32_dpp v223, v69 quad_perm:[1,0,3,2] row_mask:0xf bank_mask:0xf
	v_mov_b32_dpp v224, v98 quad_perm:[1,0,3,2] row_mask:0xf bank_mask:0xf
	v_mov_b32_dpp v225, v99 quad_perm:[1,0,3,2] row_mask:0xf bank_mask:0xf
	v_mov_b32_dpp v226, v100 quad_perm:[1,0,3,2] row_mask:0xf bank_mask:0xf
	v_mov_b32_dpp v227, v101 quad_perm:[1,0,3,2] row_mask:0xf bank_mask:0xf
	v_cndmask_b32_e32 v66, v224, v66, vcc
	v_cndmask_b32_e32 v67, v225, v67, vcc
	v_cndmask_b32_e32 v68, v226, v68, vcc
	v_cndmask_b32_e32 v69, v227, v69, vcc
	v_cndmask_b32_e32 v98, v98, v220, vcc
	v_cndmask_b32_e32 v99, v99, v221, vcc
	v_cndmask_b32_e32 v100, v100, v222, vcc
	v_cndmask_b32_e32 v101, v101, v223, vcc
	global_store_dwordx4 v[140:141], v[98:101], off
	global_store_dwordx4 v[142:143], v[66:69], off
	s_waitcnt vmcnt(30)
	v_permlane16_swap_b32_e32 v212, v214
	v_permlane16_swap_b32_e32 v213, v215
	v_lshlrev_b32_e32 v216, 16, v212
	v_and_b32_e32 v212, 0xffff0000, v212
	v_lshlrev_b32_e32 v217, 16, v213
	v_and_b32_e32 v213, 0xffff0000, v213
	v_fmac_f32_e32 v34, s44, v216
	v_fmac_f32_e32 v35, s44, v212
	v_fmac_f32_e32 v36, s44, v217
	v_fmac_f32_e32 v37, s44, v213
	v_lshlrev_b32_e32 v216, 16, v214
	v_and_b32_e32 v214, 0xffff0000, v214
	v_lshlrev_b32_e32 v217, 16, v215
	v_and_b32_e32 v215, 0xffff0000, v215
	v_fmac_f32_e32 v2, s44, v216
	v_fmac_f32_e32 v3, s44, v214
	v_fmac_f32_e32 v4, s44, v217
	v_fmac_f32_e32 v5, s44, v215
	v_mov_b32_dpp v220, v2 quad_perm:[1,0,3,2] row_mask:0xf bank_mask:0xf
	v_mov_b32_dpp v221, v3 quad_perm:[1,0,3,2] row_mask:0xf bank_mask:0xf
	v_mov_b32_dpp v222, v4 quad_perm:[1,0,3,2] row_mask:0xf bank_mask:0xf
	v_mov_b32_dpp v223, v5 quad_perm:[1,0,3,2] row_mask:0xf bank_mask:0xf
	v_mov_b32_dpp v224, v34 quad_perm:[1,0,3,2] row_mask:0xf bank_mask:0xf
	v_mov_b32_dpp v225, v35 quad_perm:[1,0,3,2] row_mask:0xf bank_mask:0xf
	v_mov_b32_dpp v226, v36 quad_perm:[1,0,3,2] row_mask:0xf bank_mask:0xf
	v_mov_b32_dpp v227, v37 quad_perm:[1,0,3,2] row_mask:0xf bank_mask:0xf
	v_cndmask_b32_e32 v2, v224, v2, vcc
	v_cndmask_b32_e32 v3, v225, v3, vcc
	v_cndmask_b32_e32 v4, v226, v4, vcc
	v_cndmask_b32_e32 v5, v227, v5, vcc
	v_cndmask_b32_e32 v34, v34, v220, vcc
	v_cndmask_b32_e32 v35, v35, v221, vcc
	v_cndmask_b32_e32 v36, v36, v222, vcc
	v_cndmask_b32_e32 v37, v37, v223, vcc
	global_store_dwordx4 v[140:141], v[34:37], off offset:128
	global_store_dwordx4 v[142:143], v[2:5], off offset:128
	v_readlane_b32 s39, v250, 7
	s_cmpk_lg_u32 s39, 0x200
	s_cbranch_scc1 .LBB0_41
	v_readlane_b32 s40, v250, 0
	s_lshr_b32 s41, s40, 3
	s_and_b32 s40, s40, 7
	s_mul_i32 s40, s40, 22
	s_add_i32 s40, s40, s41
	s_cmp_lt_u32 s41, 22
	s_movk_i32 s38, 0x4000
	s_branch .LBB0_41

;     ...
;   for (int kt = 0; kt < nk; kt++) {
;     if (kt + 1 < nk) asm volatile("s_waitcnt vmcnt(6)" ::: "memory");
;     else asm volatile("s_waitcnt vmcnt(0)" ::: "memory");
;     __builtin_amdgcn_s_barrier();
;     asm volatile("" ::: "memory");
;     if (kt + 2 < nk) G2_STAGE(kt + 2);
;     const char* cS = smem + (kt % 3) * 24576;
;     bf16x8 xa[8], wb[4];
; #pragma unroll
;     for (int f = 0; f < 8; f++) xa[f] = *(const bf16x8*)(cS + aoff + f * 1024);
; #pragma unroll
;     for (int f = 0; f < 4; f++) wb[f] = *(const bf16x8*)(cS + boff + f * 1024);
; #pragma unroll
;     for (int nf = 0; nf < 4; nf++)
; #pragma unroll
;       for (int mf = 0; mf < 8; mf++)
;         acc[nf][mf] = __builtin_amdgcn_mfma_f32_16x16x32_bf16(wb[nf], xa[mf], acc[nf][mf], 0, 0, 0);
;   }
.Lt8_loop:
	.p2align 3
	s_waitcnt vmcnt(6) lgkmcnt(0)
	s_barrier
	s_setprio 1
	v_add_u32_e32 v144, s40, v136
	v_mfma_f32_16x16x32_bf16 v[126:129], v[184:187], v[146:149], v[126:129]
	ds_read_b128 v[200:203], v144 offset:0
	v_mfma_f32_16x16x32_bf16 v[122:125], v[184:187], v[152:155], v[122:125]
	ds_read_b128 v[204:207], v144 offset:1024
	v_mfma_f32_16x16x32_bf16 v[118:121], v[184:187], v[156:159], v[118:121]
	ds_read_b128 v[208:211], v144 offset:2048
	v_mfma_f32_16x16x32_bf16 v[114:117], v[184:187], v[162:165], v[114:117]
	ds_read_b128 v[212:215], v144 offset:3072
	v_mfma_f32_16x16x32_bf16 v[110:113], v[184:187], v[166:169], v[110:113]
	ds_read_b128 v[216:219], v144 offset:4096
	v_mfma_f32_16x16x32_bf16 v[106:109], v[184:187], v[170:173], v[106:109]
	ds_read_b128 v[220:223], v144 offset:5120
	v_mfma_f32_16x16x32_bf16 v[102:105], v[184:187], v[176:179], v[102:105]
	ds_read_b128 v[224:227], v144 offset:6144
	v_mfma_f32_16x16x32_bf16 v[98:101], v[184:187], v[180:183], v[98:101]
	ds_read_b128 v[228:231], v144 offset:7168
	v_mfma_f32_16x16x32_bf16 v[94:97], v[188:191], v[146:149], v[94:97]
	v_add_u32_e64 v144, s40, v137
	v_mfma_f32_16x16x32_bf16 v[90:93], v[188:191], v[152:155], v[90:93]
	v_mfma_f32_16x16x32_bf16 v[86:89], v[188:191], v[156:159], v[86:89]
	ds_read_b128 v[232:235], v144 offset:16384
	v_mfma_f32_16x16x32_bf16 v[82:85], v[188:191], v[162:165], v[82:85]
	ds_read_b128 v[236:239], v144 offset:17408
	v_mfma_f32_16x16x32_bf16 v[78:81], v[188:191], v[166:169], v[78:81]
	ds_read_b128 v[240:243], v144 offset:18432
	v_mfma_f32_16x16x32_bf16 v[74:77], v[188:191], v[170:173], v[74:77]
	ds_read_b128 v[244:247], v144 offset:19456
	v_mfma_f32_16x16x32_bf16 v[70:73], v[188:191], v[176:179], v[70:73]
	s_add_i32 s42, s46, s41
	s_mov_b32 m0, s42
	v_lshl_add_u64 v[142:143], v[132:133], 0, s[2:3]
	v_mfma_f32_16x16x32_bf16 v[66:69], v[188:191], v[180:183], v[66:69]
	global_load_lds_dwordx4 v[132:133], off
	s_add_i32 m0, m0, 0x1000
	v_mfma_f32_16x16x32_bf16 v[62:65], v[192:195], v[146:149], v[62:65]
	v_mfma_f32_16x16x32_bf16 v[58:61], v[192:195], v[152:155], v[58:61]
	v_mfma_f32_16x16x32_bf16 v[54:57], v[192:195], v[156:159], v[54:57]
	global_load_lds_dwordx4 v[142:143], off
	v_lshl_add_u64 v[142:143], v[142:143], 0, s[2:3]
	s_add_i32 m0, m0, 0x1000
	v_mfma_f32_16x16x32_bf16 v[50:53], v[192:195], v[162:165], v[50:53]
	v_mfma_f32_16x16x32_bf16 v[46:49], v[192:195], v[166:169], v[46:49]
	v_mfma_f32_16x16x32_bf16 v[42:45], v[192:195], v[170:173], v[42:45]
	global_load_lds_dwordx4 v[142:143], off
	v_lshl_add_u64 v[142:143], v[142:143], 0, s[2:3]
	s_add_i32 m0, m0, 0x1000
	v_mfma_f32_16x16x32_bf16 v[38:41], v[192:195], v[176:179], v[38:41]
	v_mfma_f32_16x16x32_bf16 v[34:37], v[192:195], v[180:183], v[34:37]
	v_mfma_f32_16x16x32_bf16 v[30:33], v[196:199], v[146:149], v[30:33]
	global_load_lds_dwordx4 v[142:143], off
	s_add_i32 m0, m0, 0x1000
	v_lshl_add_u64 v[142:143], v[134:135], 0, s[2:3]
	v_mfma_f32_16x16x32_bf16 v[26:29], v[196:199], v[152:155], v[26:29]
	v_mfma_f32_16x16x32_bf16 v[22:25], v[196:199], v[156:159], v[22:25]
	v_mfma_f32_16x16x32_bf16 v[18:21], v[196:199], v[162:165], v[18:21]
	global_load_lds_dwordx4 v[134:135], off
	s_add_i32 m0, m0, 0x1000
	v_lshl_add_u64 v[132:133], v[132:133], 0, s[12:13]
	v_mfma_f32_16x16x32_bf16 v[14:17], v[196:199], v[166:169], v[14:17]
	v_mfma_f32_16x16x32_bf16 v[10:13], v[196:199], v[170:173], v[10:13]
	v_mfma_f32_16x16x32_bf16 v[6:9], v[196:199], v[176:179], v[6:9]
	global_load_lds_dwordx4 v[142:143], off
	v_lshl_add_u64 v[134:135], v[134:135], 0, s[4:5]
	v_mfma_f32_16x16x32_bf16 v[2:5], v[196:199], v[180:183], v[2:5]
	s_setprio 0
	s_mov_b32 s41, s40
	s_add_i32 s40, s40, 0x6000
	s_cmp_eq_u32 s40, 0x12000
	s_cselect_b32 s40, 0, s40
	s_nop 0
	.p2align 3
	s_waitcnt vmcnt(6) lgkmcnt(0)
	s_barrier
	s_setprio 1
	v_add_u32_e32 v144, s40, v136
	v_mfma_f32_16x16x32_bf16 v[126:129], v[232:235], v[200:203], v[126:129]
	ds_read_b128 v[146:149], v144 offset:0
	v_mfma_f32_16x16x32_bf16 v[122:125], v[232:235], v[204:207], v[122:125]
	ds_read_b128 v[152:155], v144 offset:1024
	v_mfma_f32_16x16x32_bf16 v[118:121], v[232:235], v[208:211], v[118:121]
	ds_read_b128 v[156:159], v144 offset:2048
	v_mfma_f32_16x16x32_bf16 v[114:117], v[232:235], v[212:215], v[114:117]
	ds_read_b128 v[162:165], v144 offset:3072
	v_mfma_f32_16x16x32_bf16 v[110:113], v[232:235], v[216:219], v[110:113]
	ds_read_b128 v[166:169], v144 offset:4096
	v_mfma_f32_16x16x32_bf16 v[106:109], v[232:235], v[220:223], v[106:109]
	ds_read_b128 v[170:173], v144 offset:5120
	v_mfma_f32_16x16x32_bf16 v[102:105], v[232:235], v[224:227], v[102:105]
	ds_read_b128 v[176:179], v144 offset:6144
	v_mfma_f32_16x16x32_bf16 v[98:101], v[232:235], v[228:231], v[98:101]
	ds_read_b128 v[180:183], v144 offset:7168
	v_mfma_f32_16x16x32_bf16 v[94:97], v[236:239], v[200:203], v[94:97]
	v_add_u32_e64 v144, s40, v137
	v_mfma_f32_16x16x32_bf16 v[90:93], v[236:239], v[204:207], v[90:93]
	v_mfma_f32_16x16x32_bf16 v[86:89], v[236:239], v[208:211], v[86:89]
	ds_read_b128 v[184:187], v144 offset:16384
	v_mfma_f32_16x16x32_bf16 v[82:85], v[236:239], v[212:215], v[82:85]
	ds_read_b128 v[188:191], v144 offset:17408
	v_mfma_f32_16x16x32_bf16 v[78:81], v[236:239], v[216:219], v[78:81]
	ds_read_b128 v[192:195], v144 offset:18432
	v_mfma_f32_16x16x32_bf16 v[74:77], v[236:239], v[220:223], v[74:77]
	ds_read_b128 v[196:199], v144 offset:19456
	v_mfma_f32_16x16x32_bf16 v[70:73], v[236:239], v[224:227], v[70:73]
	s_add_i32 s42, s46, s41
	s_mov_b32 m0, s42
	v_lshl_add_u64 v[142:143], v[132:133], 0, s[2:3]
	v_mfma_f32_16x16x32_bf16 v[66:69], v[236:239], v[228:231], v[66:69]
	global_load_lds_dwordx4 v[132:133], off
;     ...
;   for (int kt = 0; kt < nk; kt++) {
;     if (kt + 1 < nk) asm volatile("s_waitcnt vmcnt(6)" ::: "memory");
;     else asm volatile("s_waitcnt vmcnt(0)" ::: "memory");
;     __builtin_amdgcn_s_barrier();
;     asm volatile("" ::: "memory");
;     if (kt + 2 < nk) G2_STAGE(kt + 2);
;     const char* cS = smem + (kt % 3) * 24576;
;     bf16x8 xa[8], wb[4];
; #pragma unroll
;     for (int f = 0; f < 8; f++) xa[f] = *(const bf16x8*)(cS + aoff + f * 1024);
; #pragma unroll
;     for (int f = 0; f < 4; f++) wb[f] = *(const bf16x8*)(cS + boff + f * 1024);
; #pragma unroll
;     for (int nf = 0; nf < 4; nf++)
; #pragma unroll
;       for (int mf = 0; mf < 8; mf++)
;         acc[nf][mf] = __builtin_amdgcn_mfma_f32_16x16x32_bf16(wb[nf], xa[mf], acc[nf][mf], 0, 0, 0);
;   }
	s_add_i32 m0, m0, 0x1000
	v_mfma_f32_16x16x32_bf16 v[62:65], v[240:243], v[200:203], v[62:65]
	v_mfma_f32_16x16x32_bf16 v[58:61], v[240:243], v[204:207], v[58:61]
	v_mfma_f32_16x16x32_bf16 v[54:57], v[240:243], v[208:211], v[54:57]
	global_load_lds_dwordx4 v[142:143], off
	v_lshl_add_u64 v[142:143], v[142:143], 0, s[2:3]
	s_add_i32 m0, m0, 0x1000
	v_mfma_f32_16x16x32_bf16 v[50:53], v[240:243], v[212:215], v[50:53]
	v_mfma_f32_16x16x32_bf16 v[46:49], v[240:243], v[216:219], v[46:49]
	v_mfma_f32_16x16x32_bf16 v[42:45], v[240:243], v[220:223], v[42:45]
	global_load_lds_dwordx4 v[142:143], off
	v_lshl_add_u64 v[142:143], v[142:143], 0, s[2:3]
	s_add_i32 m0, m0, 0x1000
	v_mfma_f32_16x16x32_bf16 v[38:41], v[240:243], v[224:227], v[38:41]
	v_mfma_f32_16x16x32_bf16 v[34:37], v[240:243], v[228:231], v[34:37]
	v_mfma_f32_16x16x32_bf16 v[30:33], v[244:247], v[200:203], v[30:33]
	global_load_lds_dwordx4 v[142:143], off
	s_add_i32 m0, m0, 0x1000
	v_lshl_add_u64 v[142:143], v[134:135], 0, s[2:3]
	v_mfma_f32_16x16x32_bf16 v[26:29], v[244:247], v[204:207], v[26:29]
	v_mfma_f32_16x16x32_bf16 v[22:25], v[244:247], v[208:211], v[22:25]
	v_mfma_f32_16x16x32_bf16 v[18:21], v[244:247], v[212:215], v[18:21]
	global_load_lds_dwordx4 v[134:135], off
	s_add_i32 m0, m0, 0x1000
	v_lshl_add_u64 v[132:133], v[132:133], 0, s[12:13]
	v_mfma_f32_16x16x32_bf16 v[14:17], v[244:247], v[216:219], v[14:17]
	v_mfma_f32_16x16x32_bf16 v[10:13], v[244:247], v[220:223], v[10:13]
	v_mfma_f32_16x16x32_bf16 v[6:9], v[244:247], v[224:227], v[6:9]
	global_load_lds_dwordx4 v[142:143], off
	v_lshl_add_u64 v[134:135], v[134:135], 0, s[4:5]
	v_mfma_f32_16x16x32_bf16 v[2:5], v[244:247], v[228:231], v[2:5]
	s_setprio 0
	s_mov_b32 s41, s40
	s_add_i32 s40, s40, 0x6000
	s_cmp_eq_u32 s40, 0x12000
	s_cselect_b32 s40, 0, s40
	s_nop 0
	s_sub_i32 s39, s39, 1
	s_cmp_lg_u32 s39, 0
	s_cbranch_scc1 .Lt8_loop
	.p2align 3
	s_waitcnt vmcnt(6) lgkmcnt(0)
	s_barrier
	s_setprio 1
	v_add_u32_e32 v144, s40, v136
	v_mfma_f32_16x16x32_bf16 v[126:129], v[184:187], v[146:149], v[126:129]
	ds_read_b128 v[200:203], v144 offset:0
	v_mfma_f32_16x16x32_bf16 v[122:125], v[184:187], v[152:155], v[122:125]
	ds_read_b128 v[204:207], v144 offset:1024
	v_mfma_f32_16x16x32_bf16 v[118:121], v[184:187], v[156:159], v[118:121]
	ds_read_b128 v[208:211], v144 offset:2048
	v_mfma_f32_16x16x32_bf16 v[114:117], v[184:187], v[162:165], v[114:117]
	ds_read_b128 v[212:215], v144 offset:3072
	v_mfma_f32_16x16x32_bf16 v[110:113], v[184:187], v[166:169], v[110:113]
	ds_read_b128 v[216:219], v144 offset:4096
	v_mfma_f32_16x16x32_bf16 v[106:109], v[184:187], v[170:173], v[106:109]
	ds_read_b128 v[220:223], v144 offset:5120
	v_mfma_f32_16x16x32_bf16 v[102:105], v[184:187], v[176:179], v[102:105]
	ds_read_b128 v[224:227], v144 offset:6144
	v_mfma_f32_16x16x32_bf16 v[98:101], v[184:187], v[180:183], v[98:101]
	ds_read_b128 v[228:231], v144 offset:7168
	v_mfma_f32_16x16x32_bf16 v[94:97], v[188:191], v[146:149], v[94:97]
	v_add_u32_e64 v144, s40, v137
	v_mfma_f32_16x16x32_bf16 v[90:93], v[188:191], v[152:155], v[90:93]
	v_mfma_f32_16x16x32_bf16 v[86:89], v[188:191], v[156:159], v[86:89]
	ds_read_b128 v[232:235], v144 offset:16384
	v_mfma_f32_16x16x32_bf16 v[82:85], v[188:191], v[162:165], v[82:85]
	ds_read_b128 v[236:239], v144 offset:17408
	v_mfma_f32_16x16x32_bf16 v[78:81], v[188:191], v[166:169], v[78:81]
	ds_read_b128 v[240:243], v144 offset:18432
	v_mfma_f32_16x16x32_bf16 v[74:77], v[188:191], v[170:173], v[74:77]
	ds_read_b128 v[244:247], v144 offset:19456
	v_mfma_f32_16x16x32_bf16 v[70:73], v[188:191], v[176:179], v[70:73]
	s_add_i32 s42, s46, s41
	s_mov_b32 m0, s42
	v_lshl_add_u64 v[142:143], v[132:133], 0, s[2:3]
	v_mfma_f32_16x16x32_bf16 v[66:69], v[188:191], v[180:183], v[66:69]
	global_load_lds_dwordx4 v[132:133], off
	s_add_i32 m0, m0, 0x1000
	v_mfma_f32_16x16x32_bf16 v[62:65], v[192:195], v[146:149], v[62:65]
	v_mfma_f32_16x16x32_bf16 v[58:61], v[192:195], v[152:155], v[58:61]
	v_mfma_f32_16x16x32_bf16 v[54:57], v[192:195], v[156:159], v[54:57]
	global_load_lds_dwordx4 v[142:143], off
	v_lshl_add_u64 v[142:143], v[142:143], 0, s[2:3]
	s_add_i32 m0, m0, 0x1000
	v_mfma_f32_16x16x32_bf16 v[50:53], v[192:195], v[162:165], v[50:53]
	v_mfma_f32_16x16x32_bf16 v[46:49], v[192:195], v[166:169], v[46:49]
	v_mfma_f32_16x16x32_bf16 v[42:45], v[192:195], v[170:173], v[42:45]
	global_load_lds_dwordx4 v[142:143], off
	v_lshl_add_u64 v[142:143], v[142:143], 0, s[2:3]
	s_add_i32 m0, m0, 0x1000
	v_mfma_f32_16x16x32_bf16 v[38:41], v[192:195], v[176:179], v[38:41]
	v_mfma_f32_16x16x32_bf16 v[34:37], v[192:195], v[180:183], v[34:37]
	v_mfma_f32_16x16x32_bf16 v[30:33], v[196:199], v[146:149], v[30:33]
	global_load_lds_dwordx4 v[142:143], off
	s_add_i32 m0, m0, 0x1000
	v_lshl_add_u64 v[142:143], v[134:135], 0, s[2:3]
	v_mfma_f32_16x16x32_bf16 v[26:29], v[196:199], v[152:155], v[26:29]
	v_mfma_f32_16x16x32_bf16 v[22:25], v[196:199], v[156:159], v[22:25]
	v_mfma_f32_16x16x32_bf16 v[18:21], v[196:199], v[162:165], v[18:21]
	global_load_lds_dwordx4 v[134:135], off
	s_add_i32 m0, m0, 0x1000
	v_lshl_add_u64 v[132:133], v[132:133], 0, s[12:13]
	v_mfma_f32_16x16x32_bf16 v[14:17], v[196:199], v[166:169], v[14:17]
	v_mfma_f32_16x16x32_bf16 v[10:13], v[196:199], v[170:173], v[10:13]
	v_mfma_f32_16x16x32_bf16 v[6:9], v[196:199], v[176:179], v[6:9]
	global_load_lds_dwordx4 v[142:143], off
	v_lshl_add_u64 v[134:135], v[134:135], 0, s[4:5]
	v_mfma_f32_16x16x32_bf16 v[2:5], v[196:199], v[180:183], v[2:5]
	s_setprio 0
	s_mov_b32 s41, s40
	s_add_i32 s40, s40, 0x6000
	s_cmp_eq_u32 s40, 0x12000
	s_cselect_b32 s40, 0, s40
	s_nop 0
	.p2align 3
	s_waitcnt vmcnt(6) lgkmcnt(0)
	s_barrier
;     ...
;   for (int kt = 0; kt < nk; kt++) {
;     if (kt + 1 < nk) asm volatile("s_waitcnt vmcnt(6)" ::: "memory");
;     else asm volatile("s_waitcnt vmcnt(0)" ::: "memory");
;     __builtin_amdgcn_s_barrier();
;     asm volatile("" ::: "memory");
;     if (kt + 2 < nk) G2_STAGE(kt + 2);
;     const char* cS = smem + (kt % 3) * 24576;
;     bf16x8 xa[8], wb[4];
; #pragma unroll
;     for (int f = 0; f < 8; f++) xa[f] = *(const bf16x8*)(cS + aoff + f * 1024);
; #pragma unroll
;     for (int f = 0; f < 4; f++) wb[f] = *(const bf16x8*)(cS + boff + f * 1024);
; #pragma unroll
;     for (int nf = 0; nf < 4; nf++)
; #pragma unroll
;       for (int mf = 0; mf < 8; mf++)
;         acc[nf][mf] = __builtin_amdgcn_mfma_f32_16x16x32_bf16(wb[nf], xa[mf], acc[nf][mf], 0, 0, 0);
;   }
	s_setprio 1
	v_add_u32_e32 v144, s40, v136
	v_mfma_f32_16x16x32_bf16 v[126:129], v[232:235], v[200:203], v[126:129]
	ds_read_b128 v[146:149], v144 offset:0
	v_mfma_f32_16x16x32_bf16 v[122:125], v[232:235], v[204:207], v[122:125]
	ds_read_b128 v[152:155], v144 offset:1024
	v_mfma_f32_16x16x32_bf16 v[118:121], v[232:235], v[208:211], v[118:121]
	ds_read_b128 v[156:159], v144 offset:2048
	v_mfma_f32_16x16x32_bf16 v[114:117], v[232:235], v[212:215], v[114:117]
	ds_read_b128 v[162:165], v144 offset:3072
	v_mfma_f32_16x16x32_bf16 v[110:113], v[232:235], v[216:219], v[110:113]
	ds_read_b128 v[166:169], v144 offset:4096
	v_mfma_f32_16x16x32_bf16 v[106:109], v[232:235], v[220:223], v[106:109]
	ds_read_b128 v[170:173], v144 offset:5120
	v_mfma_f32_16x16x32_bf16 v[102:105], v[232:235], v[224:227], v[102:105]
	ds_read_b128 v[176:179], v144 offset:6144
	v_mfma_f32_16x16x32_bf16 v[98:101], v[232:235], v[228:231], v[98:101]
	ds_read_b128 v[180:183], v144 offset:7168
	v_mfma_f32_16x16x32_bf16 v[94:97], v[236:239], v[200:203], v[94:97]
	v_add_u32_e64 v144, s40, v137
	v_mfma_f32_16x16x32_bf16 v[90:93], v[236:239], v[204:207], v[90:93]
	v_mfma_f32_16x16x32_bf16 v[86:89], v[236:239], v[208:211], v[86:89]
	ds_read_b128 v[184:187], v144 offset:16384
	v_mfma_f32_16x16x32_bf16 v[82:85], v[236:239], v[212:215], v[82:85]
	ds_read_b128 v[188:191], v144 offset:17408
	v_mfma_f32_16x16x32_bf16 v[78:81], v[236:239], v[216:219], v[78:81]
	ds_read_b128 v[192:195], v144 offset:18432
	v_mfma_f32_16x16x32_bf16 v[74:77], v[236:239], v[220:223], v[74:77]
	ds_read_b128 v[196:199], v144 offset:19456
	v_mfma_f32_16x16x32_bf16 v[70:73], v[236:239], v[224:227], v[70:73]
	v_mfma_f32_16x16x32_bf16 v[66:69], v[236:239], v[228:231], v[66:69]
	v_mfma_f32_16x16x32_bf16 v[62:65], v[240:243], v[200:203], v[62:65]
	v_mfma_f32_16x16x32_bf16 v[58:61], v[240:243], v[204:207], v[58:61]
	v_mfma_f32_16x16x32_bf16 v[54:57], v[240:243], v[208:211], v[54:57]
	v_mfma_f32_16x16x32_bf16 v[50:53], v[240:243], v[212:215], v[50:53]
	v_mfma_f32_16x16x32_bf16 v[46:49], v[240:243], v[216:219], v[46:49]
	v_mfma_f32_16x16x32_bf16 v[42:45], v[240:243], v[220:223], v[42:45]
	v_mfma_f32_16x16x32_bf16 v[38:41], v[240:243], v[224:227], v[38:41]
	v_mfma_f32_16x16x32_bf16 v[34:37], v[240:243], v[228:231], v[34:37]
	v_mfma_f32_16x16x32_bf16 v[30:33], v[244:247], v[200:203], v[30:33]
	v_mfma_f32_16x16x32_bf16 v[26:29], v[244:247], v[204:207], v[26:29]
	v_mfma_f32_16x16x32_bf16 v[22:25], v[244:247], v[208:211], v[22:25]
	v_mfma_f32_16x16x32_bf16 v[18:21], v[244:247], v[212:215], v[18:21]
	v_mfma_f32_16x16x32_bf16 v[14:17], v[244:247], v[216:219], v[14:17]
	v_mfma_f32_16x16x32_bf16 v[10:13], v[244:247], v[220:223], v[10:13]
	v_mfma_f32_16x16x32_bf16 v[6:9], v[244:247], v[224:227], v[6:9]
	v_mfma_f32_16x16x32_bf16 v[2:5], v[244:247], v[228:231], v[2:5]
	s_setprio 0
	s_mov_b32 s41, s40
	s_add_i32 s40, s40, 0x6000
	s_cmp_eq_u32 s40, 0x12000
	s_cselect_b32 s40, 0, s40
	s_nop 0
	.p2align 3
	s_waitcnt vmcnt(0) lgkmcnt(0)
	s_barrier
	s_setprio 1
	v_add_u32_e32 v144, s40, v136
	v_mfma_f32_16x16x32_bf16 v[126:129], v[184:187], v[146:149], v[126:129]
	ds_read_b128 v[200:203], v144 offset:0
	v_mfma_f32_16x16x32_bf16 v[122:125], v[184:187], v[152:155], v[122:125]
	ds_read_b128 v[204:207], v144 offset:1024
	v_mfma_f32_16x16x32_bf16 v[118:121], v[184:187], v[156:159], v[118:121]
	ds_read_b128 v[208:211], v144 offset:2048
	v_mfma_f32_16x16x32_bf16 v[114:117], v[184:187], v[162:165], v[114:117]
	ds_read_b128 v[212:215], v144 offset:3072
	v_mfma_f32_16x16x32_bf16 v[110:113], v[184:187], v[166:169], v[110:113]
	ds_read_b128 v[216:219], v144 offset:4096
	v_mfma_f32_16x16x32_bf16 v[106:109], v[184:187], v[170:173], v[106:109]
	ds_read_b128 v[220:223], v144 offset:5120
	v_mfma_f32_16x16x32_bf16 v[102:105], v[184:187], v[176:179], v[102:105]
	ds_read_b128 v[224:227], v144 offset:6144
	v_mfma_f32_16x16x32_bf16 v[98:101], v[184:187], v[180:183], v[98:101]
	ds_read_b128 v[228:231], v144 offset:7168
	v_mfma_f32_16x16x32_bf16 v[94:97], v[188:191], v[146:149], v[94:97]
	v_add_u32_e64 v144, s40, v137
	v_mfma_f32_16x16x32_bf16 v[90:93], v[188:191], v[152:155], v[90:93]
	v_mfma_f32_16x16x32_bf16 v[86:89], v[188:191], v[156:159], v[86:89]
	ds_read_b128 v[232:235], v144 offset:16384
	v_mfma_f32_16x16x32_bf16 v[82:85], v[188:191], v[162:165], v[82:85]
	ds_read_b128 v[236:239], v144 offset:17408
	v_mfma_f32_16x16x32_bf16 v[78:81], v[188:191], v[166:169], v[78:81]
	ds_read_b128 v[240:243], v144 offset:18432
	v_mfma_f32_16x16x32_bf16 v[74:77], v[188:191], v[170:173], v[74:77]
	ds_read_b128 v[244:247], v144 offset:19456
	v_mfma_f32_16x16x32_bf16 v[70:73], v[188:191], v[176:179], v[70:73]
	v_mfma_f32_16x16x32_bf16 v[66:69], v[188:191], v[180:183], v[66:69]
	v_mfma_f32_16x16x32_bf16 v[62:65], v[192:195], v[146:149], v[62:65]
	v_mfma_f32_16x16x32_bf16 v[58:61], v[192:195], v[152:155], v[58:61]
	v_mfma_f32_16x16x32_bf16 v[54:57], v[192:195], v[156:159], v[54:57]
	v_mfma_f32_16x16x32_bf16 v[50:53], v[192:195], v[162:165], v[50:53]
	v_mfma_f32_16x16x32_bf16 v[46:49], v[192:195], v[166:169], v[46:49]
	v_mfma_f32_16x16x32_bf16 v[42:45], v[192:195], v[170:173], v[42:45]
	v_mfma_f32_16x16x32_bf16 v[38:41], v[192:195], v[176:179], v[38:41]
	v_mfma_f32_16x16x32_bf16 v[34:37], v[192:195], v[180:183], v[34:37]
	v_mfma_f32_16x16x32_bf16 v[30:33], v[196:199], v[146:149], v[30:33]
	v_mfma_f32_16x16x32_bf16 v[26:29], v[196:199], v[152:155], v[26:29]
	v_mfma_f32_16x16x32_bf16 v[22:25], v[196:199], v[156:159], v[22:25]
	v_mfma_f32_16x16x32_bf16 v[18:21], v[196:199], v[162:165], v[18:21]
	v_mfma_f32_16x16x32_bf16 v[14:17], v[196:199], v[166:169], v[14:17]
	v_mfma_f32_16x16x32_bf16 v[10:13], v[196:199], v[170:173], v[10:13]
	v_mfma_f32_16x16x32_bf16 v[6:9], v[196:199], v[176:179], v[6:9]
	v_mfma_f32_16x16x32_bf16 v[2:5], v[196:199], v[180:183], v[2:5]
	s_setprio 0
	s_mov_b32 s41, s40
	s_add_i32 s40, s40, 0x6000
	s_cmp_eq_u32 s40, 0x12000
	s_cselect_b32 s40, 0, s40
	s_nop 0
	s_mov_b32 s4, 0x8000
	s_mov_b32 s5, 0
	s_mov_b32 s10, 0x10000
	s_mov_b32 s11, 0
	s_mov_b32 s44, 0x3fd744fd
	.p2align 3
	s_waitcnt lgkmcnt(0)
; DEVI float blo(unsigned u) { return __uint_as_float(u << 16); }
; DEVI float bhi(unsigned u) { return __uint_as_float(u & 0xffff0000u); }
;     ...
;     for (int nf = 0; nf < 4; nf++)
; #pragma unroll
;       for (int mf = 0; mf < 8; mf++)
;         acc[nf][mf] = __builtin_amdgcn_mfma_f32_16x16x32_bf16(wb[nf], xa[mf], acc[nf][mf], 0, 0, 0);
;     ...
; #pragma unroll
;       for (int nf = 0; nf < 4; nf++) {
;         const int col = n0 + wn * 64 + nf * 16 + quad * 4;
;         f32x4 a = acc[nf][mf];
;         if (EPI == EPI_RESID || EPI == EPI_RESID_ATOMIC) {
;           f32x4 x = a;
;           if (EPI == EPI_RESID || kpart == 0) {
;             const u32x2 xr = *(const u32x2*)((const u16*)(p.ws + WS_XB) + (size_t)row * 1024 + col);
;             x[0] += ALPHA * blo(xr[0]); x[1] += ALPHA * bhi(xr[0]); x[2] += ALPHA * blo(xr[1]); x[3] += ALPHA * bhi(xr[1]);
;           }
;           if (EPI == EPI_RESID) *(f32x4*)((float*)(p.ws + WS_XF) + (size_t)row * 1024 + col) = x;
;           else *(f32x4*)((float*)(p.ws + WS_SLAB) + ((size_t)kpart * 512 + (row - T_P)) * 1024 + col) = x;
	s_nop 0
	v_mfma_f32_16x16x32_bf16 v[126:129], v[232:235], v[200:203], v[126:129]
	v_mfma_f32_16x16x32_bf16 v[122:125], v[232:235], v[204:207], v[122:125]
	v_mfma_f32_16x16x32_bf16 v[118:121], v[232:235], v[208:211], v[118:121]
	v_mfma_f32_16x16x32_bf16 v[114:117], v[232:235], v[212:215], v[114:117]
	v_mfma_f32_16x16x32_bf16 v[110:113], v[232:235], v[216:219], v[110:113]
	global_load_dwordx4 v[146:149], v[138:139], off offset:0
	v_mfma_f32_16x16x32_bf16 v[106:109], v[232:235], v[220:223], v[106:109]
	v_mfma_f32_16x16x32_bf16 v[102:105], v[232:235], v[224:227], v[102:105]
	global_load_dwordx4 v[152:155], v[138:139], off offset:64
	v_mfma_f32_16x16x32_bf16 v[98:101], v[232:235], v[228:231], v[98:101]
	v_lshl_add_u64 v[138:139], v[138:139], 0, s[4:5]
	v_mfma_f32_16x16x32_bf16 v[94:97], v[236:239], v[200:203], v[94:97]
	global_load_dwordx4 v[156:159], v[138:139], off offset:0
	v_mfma_f32_16x16x32_bf16 v[90:93], v[236:239], v[204:207], v[90:93]
	v_mfma_f32_16x16x32_bf16 v[86:89], v[236:239], v[208:211], v[86:89]
	global_load_dwordx4 v[162:165], v[138:139], off offset:64
	v_mfma_f32_16x16x32_bf16 v[82:85], v[236:239], v[212:215], v[82:85]
	v_lshl_add_u64 v[138:139], v[138:139], 0, s[4:5]
	v_mfma_f32_16x16x32_bf16 v[78:81], v[236:239], v[216:219], v[78:81]
	global_load_dwordx4 v[166:169], v[138:139], off offset:0
	v_mfma_f32_16x16x32_bf16 v[74:77], v[236:239], v[220:223], v[74:77]
	v_mfma_f32_16x16x32_bf16 v[70:73], v[236:239], v[224:227], v[70:73]
	global_load_dwordx4 v[170:173], v[138:139], off offset:64
	v_mfma_f32_16x16x32_bf16 v[66:69], v[236:239], v[228:231], v[66:69]
	v_lshl_add_u64 v[138:139], v[138:139], 0, s[4:5]
	v_mfma_f32_16x16x32_bf16 v[62:65], v[240:243], v[200:203], v[62:65]
	global_load_dwordx4 v[176:179], v[138:139], off offset:0
	v_mfma_f32_16x16x32_bf16 v[58:61], v[240:243], v[204:207], v[58:61]
	v_mfma_f32_16x16x32_bf16 v[54:57], v[240:243], v[208:211], v[54:57]
	global_load_dwordx4 v[180:183], v[138:139], off offset:64
	v_mfma_f32_16x16x32_bf16 v[50:53], v[240:243], v[212:215], v[50:53]
	v_lshl_add_u64 v[138:139], v[138:139], 0, s[4:5]
	v_mfma_f32_16x16x32_bf16 v[46:49], v[240:243], v[216:219], v[46:49]
	global_load_dwordx4 v[184:187], v[138:139], off offset:0
	v_mfma_f32_16x16x32_bf16 v[42:45], v[240:243], v[220:223], v[42:45]
	v_mfma_f32_16x16x32_bf16 v[38:41], v[240:243], v[224:227], v[38:41]
	global_load_dwordx4 v[188:191], v[138:139], off offset:64
	v_mfma_f32_16x16x32_bf16 v[34:37], v[240:243], v[228:231], v[34:37]
	v_lshl_add_u64 v[138:139], v[138:139], 0, s[4:5]
	v_mfma_f32_16x16x32_bf16 v[30:33], v[244:247], v[200:203], v[30:33]
	global_load_dwordx4 v[192:195], v[138:139], off offset:0
	v_mfma_f32_16x16x32_bf16 v[26:29], v[244:247], v[204:207], v[26:29]
	v_mfma_f32_16x16x32_bf16 v[22:25], v[244:247], v[208:211], v[22:25]
	global_load_dwordx4 v[196:199], v[138:139], off offset:64
	v_mfma_f32_16x16x32_bf16 v[18:21], v[244:247], v[212:215], v[18:21]
	v_lshl_add_u64 v[138:139], v[138:139], 0, s[4:5]
	v_mfma_f32_16x16x32_bf16 v[14:17], v[244:247], v[216:219], v[14:17]
	v_mfma_f32_16x16x32_bf16 v[10:13], v[244:247], v[220:223], v[10:13]
	v_mfma_f32_16x16x32_bf16 v[6:9], v[244:247], v[224:227], v[6:9]
	v_mfma_f32_16x16x32_bf16 v[2:5], v[244:247], v[228:231], v[2:5]
	s_mov_b32 m0, s43
	global_load_dwordx4 v[200:203], v[138:139], off offset:0
	global_load_dwordx4 v[204:207], v[138:139], off offset:64
	v_lshl_add_u64 v[138:139], v[138:139], 0, s[4:5]
	global_load_dwordx4 v[208:211], v[138:139], off offset:0
	global_load_dwordx4 v[212:215], v[138:139], off offset:64
	v_lshl_add_u64 v[138:139], v[138:139], 0, s[4:5]
	s_nop 7
	v_and_b32_e32 v228, 1, v145
	v_cmp_ne_u32_e32 vcc, 0, v228
	v_mov_b32_e32 v229, 0xfffff040
	v_cndmask_b32_e32 v230, 0, v229, vcc
	v_ashrrev_i32_e32 v231, 31, v230
	v_lshl_add_u64 v[140:141], v[140:141], 0, v[230:231]
	v_add_co_u32_e32 v142, vcc, 0x1000, v140
	s_nop 0
	v_addc_co_u32_e32 v143, vcc, 0, v141, vcc
	v_cmp_ne_u32_e32 vcc, 0, v228
	s_waitcnt vmcnt(15)
	v_permlane16_swap_b32_e32 v146, v148
	v_permlane16_swap_b32_e32 v147, v149
	v_lshlrev_b32_e32 v216, 16, v146
	v_and_b32_e32 v146, 0xffff0000, v146
	v_lshlrev_b32_e32 v217, 16, v147
	v_and_b32_e32 v147, 0xffff0000, v147
	v_fmac_f32_e32 v126, s44, v216
	v_fmac_f32_e32 v127, s44, v146
	v_fmac_f32_e32 v128, s44, v217
	v_fmac_f32_e32 v129, s44, v147
	v_lshlrev_b32_e32 v216, 16, v148
	v_and_b32_e32 v148, 0xffff0000, v148
	v_lshlrev_b32_e32 v217, 16, v149
	v_and_b32_e32 v149, 0xffff0000, v149
	v_fmac_f32_e32 v94, s44, v216
	v_fmac_f32_e32 v95, s44, v148
	v_fmac_f32_e32 v96, s44, v217
	v_fmac_f32_e32 v97, s44, v149
	v_mov_b32_dpp v220, v94 quad_perm:[1,0,3,2] row_mask:0xf bank_mask:0xf
	v_mov_b32_dpp v221, v95 quad_perm:[1,0,3,2] row_mask:0xf bank_mask:0xf
	v_mov_b32_dpp v222, v96 quad_perm:[1,0,3,2] row_mask:0xf bank_mask:0xf
	v_mov_b32_dpp v223, v97 quad_perm:[1,0,3,2] row_mask:0xf bank_mask:0xf
	v_mov_b32_dpp v224, v126 quad_perm:[1,0,3,2] row_mask:0xf bank_mask:0xf
	v_mov_b32_dpp v225, v127 quad_perm:[1,0,3,2] row_mask:0xf bank_mask:0xf
	v_mov_b32_dpp v226, v128 quad_perm:[1,0,3,2] row_mask:0xf bank_mask:0xf
	v_mov_b32_dpp v227, v129 quad_perm:[1,0,3,2] row_mask:0xf bank_mask:0xf
	v_cndmask_b32_e32 v94, v224, v94, vcc
	v_cndmask_b32_e32 v95, v225, v95, vcc
	v_cndmask_b32_e32 v96, v226, v96, vcc
	v_cndmask_b32_e32 v97, v227, v97, vcc
	v_cndmask_b32_e32 v126, v126, v220, vcc
	v_cndmask_b32_e32 v127, v127, v221, vcc
	v_cndmask_b32_e32 v128, v128, v222, vcc
	v_cndmask_b32_e32 v129, v129, v223, vcc
	global_store_dwordx4 v[140:141], v[126:129], off
	global_store_dwordx4 v[142:143], v[94:97], off
	s_waitcnt vmcnt(16)
; DEVI float blo(unsigned u) { return __uint_as_float(u << 16); }
; DEVI float bhi(unsigned u) { return __uint_as_float(u & 0xffff0000u); }
;     ...
; #pragma unroll
;       for (int nf = 0; nf < 4; nf++) {
;         const int col = n0 + wn * 64 + nf * 16 + quad * 4;
;         f32x4 a = acc[nf][mf];
;         if (EPI == EPI_RESID || EPI == EPI_RESID_ATOMIC) {
;           f32x4 x = a;
;           if (EPI == EPI_RESID || kpart == 0) {
;             const u32x2 xr = *(const u32x2*)((const u16*)(p.ws + WS_XB) + (size_t)row * 1024 + col);
;             x[0] += ALPHA * blo(xr[0]); x[1] += ALPHA * bhi(xr[0]); x[2] += ALPHA * blo(xr[1]); x[3] += ALPHA * bhi(xr[1]);
;           }
;           if (EPI == EPI_RESID) *(f32x4*)((float*)(p.ws + WS_XF) + (size_t)row * 1024 + col) = x;
;           else *(f32x4*)((float*)(p.ws + WS_SLAB) + ((size_t)kpart * 512 + (row - T_P)) * 1024 + col) = x;
	v_permlane16_swap_b32_e32 v152, v154
	v_permlane16_swap_b32_e32 v153, v155
	v_lshlrev_b32_e32 v216, 16, v152
	v_and_b32_e32 v152, 0xffff0000, v152
	v_lshlrev_b32_e32 v217, 16, v153
	v_and_b32_e32 v153, 0xffff0000, v153
	v_fmac_f32_e32 v62, s44, v216
	v_fmac_f32_e32 v63, s44, v152
	v_fmac_f32_e32 v64, s44, v217
	v_fmac_f32_e32 v65, s44, v153
	v_lshlrev_b32_e32 v216, 16, v154
	v_and_b32_e32 v154, 0xffff0000, v154
	v_lshlrev_b32_e32 v217, 16, v155
	v_and_b32_e32 v155, 0xffff0000, v155
	v_fmac_f32_e32 v30, s44, v216
	v_fmac_f32_e32 v31, s44, v154
	v_fmac_f32_e32 v32, s44, v217
	v_fmac_f32_e32 v33, s44, v155
	v_mov_b32_dpp v220, v30 quad_perm:[1,0,3,2] row_mask:0xf bank_mask:0xf
	v_mov_b32_dpp v221, v31 quad_perm:[1,0,3,2] row_mask:0xf bank_mask:0xf
	v_mov_b32_dpp v222, v32 quad_perm:[1,0,3,2] row_mask:0xf bank_mask:0xf
	v_mov_b32_dpp v223, v33 quad_perm:[1,0,3,2] row_mask:0xf bank_mask:0xf
	v_mov_b32_dpp v224, v62 quad_perm:[1,0,3,2] row_mask:0xf bank_mask:0xf
	v_mov_b32_dpp v225, v63 quad_perm:[1,0,3,2] row_mask:0xf bank_mask:0xf
	v_mov_b32_dpp v226, v64 quad_perm:[1,0,3,2] row_mask:0xf bank_mask:0xf
	v_mov_b32_dpp v227, v65 quad_perm:[1,0,3,2] row_mask:0xf bank_mask:0xf
	v_cndmask_b32_e32 v30, v224, v30, vcc
	v_cndmask_b32_e32 v31, v225, v31, vcc
	v_cndmask_b32_e32 v32, v226, v32, vcc
	v_cndmask_b32_e32 v33, v227, v33, vcc
	v_cndmask_b32_e32 v62, v62, v220, vcc
	v_cndmask_b32_e32 v63, v63, v221, vcc
	v_cndmask_b32_e32 v64, v64, v222, vcc
	v_cndmask_b32_e32 v65, v65, v223, vcc
	global_store_dwordx4 v[140:141], v[62:65], off offset:128
	global_store_dwordx4 v[142:143], v[30:33], off offset:128
	v_lshl_add_u64 v[140:141], v[140:141], 0, s[10:11]
	v_lshl_add_u64 v[142:143], v[142:143], 0, s[10:11]
	s_waitcnt vmcnt(17)
	v_permlane16_swap_b32_e32 v156, v158
	v_permlane16_swap_b32_e32 v157, v159
	v_lshlrev_b32_e32 v216, 16, v156
	v_and_b32_e32 v156, 0xffff0000, v156
	v_lshlrev_b32_e32 v217, 16, v157
	v_and_b32_e32 v157, 0xffff0000, v157
	v_fmac_f32_e32 v122, s44, v216
	v_fmac_f32_e32 v123, s44, v156
	v_fmac_f32_e32 v124, s44, v217
	v_fmac_f32_e32 v125, s44, v157
	v_lshlrev_b32_e32 v216, 16, v158
	v_and_b32_e32 v158, 0xffff0000, v158
	v_lshlrev_b32_e32 v217, 16, v159
	v_and_b32_e32 v159, 0xffff0000, v159
	v_fmac_f32_e32 v90, s44, v216
	v_fmac_f32_e32 v91, s44, v158
	v_fmac_f32_e32 v92, s44, v217
	v_fmac_f32_e32 v93, s44, v159
	v_mov_b32_dpp v220, v90 quad_perm:[1,0,3,2] row_mask:0xf bank_mask:0xf
	v_mov_b32_dpp v221, v91 quad_perm:[1,0,3,2] row_mask:0xf bank_mask:0xf
	v_mov_b32_dpp v222, v92 quad_perm:[1,0,3,2] row_mask:0xf bank_mask:0xf
	v_mov_b32_dpp v223, v93 quad_perm:[1,0,3,2] row_mask:0xf bank_mask:0xf
	v_mov_b32_dpp v224, v122 quad_perm:[1,0,3,2] row_mask:0xf bank_mask:0xf
	v_mov_b32_dpp v225, v123 quad_perm:[1,0,3,2] row_mask:0xf bank_mask:0xf
	v_mov_b32_dpp v226, v124 quad_perm:[1,0,3,2] row_mask:0xf bank_mask:0xf
	v_mov_b32_dpp v227, v125 quad_perm:[1,0,3,2] row_mask:0xf bank_mask:0xf
	v_cndmask_b32_e32 v90, v224, v90, vcc
	v_cndmask_b32_e32 v91, v225, v91, vcc
	v_cndmask_b32_e32 v92, v226, v92, vcc
	v_cndmask_b32_e32 v93, v227, v93, vcc
	v_cndmask_b32_e32 v122, v122, v220, vcc
	v_cndmask_b32_e32 v123, v123, v221, vcc
	v_cndmask_b32_e32 v124, v124, v222, vcc
	v_cndmask_b32_e32 v125, v125, v223, vcc
	global_store_dwordx4 v[140:141], v[122:125], off
	global_store_dwordx4 v[142:143], v[90:93], off
	s_waitcnt vmcnt(18)
	v_permlane16_swap_b32_e32 v162, v164
	v_permlane16_swap_b32_e32 v163, v165
	v_lshlrev_b32_e32 v216, 16, v162
	v_and_b32_e32 v162, 0xffff0000, v162
	v_lshlrev_b32_e32 v217, 16, v163
	v_and_b32_e32 v163, 0xffff0000, v163
	v_fmac_f32_e32 v58, s44, v216
	v_fmac_f32_e32 v59, s44, v162
	v_fmac_f32_e32 v60, s44, v217
	v_fmac_f32_e32 v61, s44, v163
	v_lshlrev_b32_e32 v216, 16, v164
	v_and_b32_e32 v164, 0xffff0000, v164
	v_lshlrev_b32_e32 v217, 16, v165
	v_and_b32_e32 v165, 0xffff0000, v165
	v_fmac_f32_e32 v26, s44, v216
	v_fmac_f32_e32 v27, s44, v164
	v_fmac_f32_e32 v28, s44, v217
	v_fmac_f32_e32 v29, s44, v165
	v_mov_b32_dpp v220, v26 quad_perm:[1,0,3,2] row_mask:0xf bank_mask:0xf
	v_mov_b32_dpp v221, v27 quad_perm:[1,0,3,2] row_mask:0xf bank_mask:0xf
	v_mov_b32_dpp v222, v28 quad_perm:[1,0,3,2] row_mask:0xf bank_mask:0xf
	v_mov_b32_dpp v223, v29 quad_perm:[1,0,3,2] row_mask:0xf bank_mask:0xf
	v_mov_b32_dpp v224, v58 quad_perm:[1,0,3,2] row_mask:0xf bank_mask:0xf
	v_mov_b32_dpp v225, v59 quad_perm:[1,0,3,2] row_mask:0xf bank_mask:0xf
	v_mov_b32_dpp v226, v60 quad_perm:[1,0,3,2] row_mask:0xf bank_mask:0xf
	v_mov_b32_dpp v227, v61 quad_perm:[1,0,3,2] row_mask:0xf bank_mask:0xf
	v_cndmask_b32_e32 v26, v224, v26, vcc
	v_cndmask_b32_e32 v27, v225, v27, vcc
	v_cndmask_b32_e32 v28, v226, v28, vcc
	v_cndmask_b32_e32 v29, v227, v29, vcc
	v_cndmask_b32_e32 v58, v58, v220, vcc
	v_cndmask_b32_e32 v59, v59, v221, vcc
	v_cndmask_b32_e32 v60, v60, v222, vcc
	v_cndmask_b32_e32 v61, v61, v223, vcc
	global_store_dwordx4 v[140:141], v[58:61], off offset:128
	global_store_dwordx4 v[142:143], v[26:29], off offset:128
	v_lshl_add_u64 v[140:141], v[140:141], 0, s[10:11]
	v_lshl_add_u64 v[142:143], v[142:143], 0, s[10:11]
	s_waitcnt vmcnt(19)
; DEVI float blo(unsigned u) { return __uint_as_float(u << 16); }
; DEVI float bhi(unsigned u) { return __uint_as_float(u & 0xffff0000u); }
;     ...
; #pragma unroll
;       for (int nf = 0; nf < 4; nf++) {
;         const int col = n0 + wn * 64 + nf * 16 + quad * 4;
;         f32x4 a = acc[nf][mf];
;         if (EPI == EPI_RESID || EPI == EPI_RESID_ATOMIC) {
;           f32x4 x = a;
;           if (EPI == EPI_RESID || kpart == 0) {
;             const u32x2 xr = *(const u32x2*)((const u16*)(p.ws + WS_XB) + (size_t)row * 1024 + col);
;             x[0] += ALPHA * blo(xr[0]); x[1] += ALPHA * bhi(xr[0]); x[2] += ALPHA * blo(xr[1]); x[3] += ALPHA * bhi(xr[1]);
;           }
;           if (EPI == EPI_RESID) *(f32x4*)((float*)(p.ws + WS_XF) + (size_t)row * 1024 + col) = x;
;           else *(f32x4*)((float*)(p.ws + WS_SLAB) + ((size_t)kpart * 512 + (row - T_P)) * 1024 + col) = x;
	v_permlane16_swap_b32_e32 v166, v168
	v_permlane16_swap_b32_e32 v167, v169
	v_lshlrev_b32_e32 v216, 16, v166
	v_and_b32_e32 v166, 0xffff0000, v166
	v_lshlrev_b32_e32 v217, 16, v167
	v_and_b32_e32 v167, 0xffff0000, v167
	v_fmac_f32_e32 v118, s44, v216
	v_fmac_f32_e32 v119, s44, v166
	v_fmac_f32_e32 v120, s44, v217
	v_fmac_f32_e32 v121, s44, v167
	v_lshlrev_b32_e32 v216, 16, v168
	v_and_b32_e32 v168, 0xffff0000, v168
	v_lshlrev_b32_e32 v217, 16, v169
	v_and_b32_e32 v169, 0xffff0000, v169
	v_fmac_f32_e32 v86, s44, v216
	v_fmac_f32_e32 v87, s44, v168
	v_fmac_f32_e32 v88, s44, v217
	v_fmac_f32_e32 v89, s44, v169
	v_mov_b32_dpp v220, v86 quad_perm:[1,0,3,2] row_mask:0xf bank_mask:0xf
	v_mov_b32_dpp v221, v87 quad_perm:[1,0,3,2] row_mask:0xf bank_mask:0xf
	v_mov_b32_dpp v222, v88 quad_perm:[1,0,3,2] row_mask:0xf bank_mask:0xf
	v_mov_b32_dpp v223, v89 quad_perm:[1,0,3,2] row_mask:0xf bank_mask:0xf
	v_mov_b32_dpp v224, v118 quad_perm:[1,0,3,2] row_mask:0xf bank_mask:0xf
	v_mov_b32_dpp v225, v119 quad_perm:[1,0,3,2] row_mask:0xf bank_mask:0xf
	v_mov_b32_dpp v226, v120 quad_perm:[1,0,3,2] row_mask:0xf bank_mask:0xf
	v_mov_b32_dpp v227, v121 quad_perm:[1,0,3,2] row_mask:0xf bank_mask:0xf
	v_cndmask_b32_e32 v86, v224, v86, vcc
	v_cndmask_b32_e32 v87, v225, v87, vcc
	v_cndmask_b32_e32 v88, v226, v88, vcc
	v_cndmask_b32_e32 v89, v227, v89, vcc
	v_cndmask_b32_e32 v118, v118, v220, vcc
	v_cndmask_b32_e32 v119, v119, v221, vcc
	v_cndmask_b32_e32 v120, v120, v222, vcc
	v_cndmask_b32_e32 v121, v121, v223, vcc
	global_store_dwordx4 v[140:141], v[118:121], off
	global_store_dwordx4 v[142:143], v[86:89], off
	s_waitcnt vmcnt(20)
	v_permlane16_swap_b32_e32 v170, v172
	v_permlane16_swap_b32_e32 v171, v173
	v_lshlrev_b32_e32 v216, 16, v170
	v_and_b32_e32 v170, 0xffff0000, v170
	v_lshlrev_b32_e32 v217, 16, v171
	v_and_b32_e32 v171, 0xffff0000, v171
	v_fmac_f32_e32 v54, s44, v216
	v_fmac_f32_e32 v55, s44, v170
	v_fmac_f32_e32 v56, s44, v217
	v_fmac_f32_e32 v57, s44, v171
	v_lshlrev_b32_e32 v216, 16, v172
	v_and_b32_e32 v172, 0xffff0000, v172
	v_lshlrev_b32_e32 v217, 16, v173
	v_and_b32_e32 v173, 0xffff0000, v173
	v_fmac_f32_e32 v22, s44, v216
	v_fmac_f32_e32 v23, s44, v172
	v_fmac_f32_e32 v24, s44, v217
	v_fmac_f32_e32 v25, s44, v173
	v_mov_b32_dpp v220, v22 quad_perm:[1,0,3,2] row_mask:0xf bank_mask:0xf
	v_mov_b32_dpp v221, v23 quad_perm:[1,0,3,2] row_mask:0xf bank_mask:0xf
	v_mov_b32_dpp v222, v24 quad_perm:[1,0,3,2] row_mask:0xf bank_mask:0xf
	v_mov_b32_dpp v223, v25 quad_perm:[1,0,3,2] row_mask:0xf bank_mask:0xf
	v_mov_b32_dpp v224, v54 quad_perm:[1,0,3,2] row_mask:0xf bank_mask:0xf
	v_mov_b32_dpp v225, v55 quad_perm:[1,0,3,2] row_mask:0xf bank_mask:0xf
	v_mov_b32_dpp v226, v56 quad_perm:[1,0,3,2] row_mask:0xf bank_mask:0xf
	v_mov_b32_dpp v227, v57 quad_perm:[1,0,3,2] row_mask:0xf bank_mask:0xf
	v_cndmask_b32_e32 v22, v224, v22, vcc
	v_cndmask_b32_e32 v23, v225, v23, vcc
	v_cndmask_b32_e32 v24, v226, v24, vcc
	v_cndmask_b32_e32 v25, v227, v25, vcc
	v_cndmask_b32_e32 v54, v54, v220, vcc
	v_cndmask_b32_e32 v55, v55, v221, vcc
	v_cndmask_b32_e32 v56, v56, v222, vcc
	v_cndmask_b32_e32 v57, v57, v223, vcc
	global_store_dwordx4 v[140:141], v[54:57], off offset:128
	global_store_dwordx4 v[142:143], v[22:25], off offset:128
	v_lshl_add_u64 v[140:141], v[140:141], 0, s[10:11]
	v_lshl_add_u64 v[142:143], v[142:143], 0, s[10:11]
	s_waitcnt vmcnt(21)
	v_permlane16_swap_b32_e32 v176, v178
	v_permlane16_swap_b32_e32 v177, v179
	v_lshlrev_b32_e32 v216, 16, v176
	v_and_b32_e32 v176, 0xffff0000, v176
	v_lshlrev_b32_e32 v217, 16, v177
	v_and_b32_e32 v177, 0xffff0000, v177
	v_fmac_f32_e32 v114, s44, v216
	v_fmac_f32_e32 v115, s44, v176
	v_fmac_f32_e32 v116, s44, v217
	v_fmac_f32_e32 v117, s44, v177
	v_lshlrev_b32_e32 v216, 16, v178
	v_and_b32_e32 v178, 0xffff0000, v178
	v_lshlrev_b32_e32 v217, 16, v179
	v_and_b32_e32 v179, 0xffff0000, v179
	v_fmac_f32_e32 v82, s44, v216
	v_fmac_f32_e32 v83, s44, v178
	v_fmac_f32_e32 v84, s44, v217
	v_fmac_f32_e32 v85, s44, v179
	v_mov_b32_dpp v220, v82 quad_perm:[1,0,3,2] row_mask:0xf bank_mask:0xf
	v_mov_b32_dpp v221, v83 quad_perm:[1,0,3,2] row_mask:0xf bank_mask:0xf
	v_mov_b32_dpp v222, v84 quad_perm:[1,0,3,2] row_mask:0xf bank_mask:0xf
	v_mov_b32_dpp v223, v85 quad_perm:[1,0,3,2] row_mask:0xf bank_mask:0xf
	v_mov_b32_dpp v224, v114 quad_perm:[1,0,3,2] row_mask:0xf bank_mask:0xf
	v_mov_b32_dpp v225, v115 quad_perm:[1,0,3,2] row_mask:0xf bank_mask:0xf
	v_mov_b32_dpp v226, v116 quad_perm:[1,0,3,2] row_mask:0xf bank_mask:0xf
	v_mov_b32_dpp v227, v117 quad_perm:[1,0,3,2] row_mask:0xf bank_mask:0xf
	v_cndmask_b32_e32 v82, v224, v82, vcc
	v_cndmask_b32_e32 v83, v225, v83, vcc
	v_cndmask_b32_e32 v84, v226, v84, vcc
	v_cndmask_b32_e32 v85, v227, v85, vcc
	v_cndmask_b32_e32 v114, v114, v220, vcc
	v_cndmask_b32_e32 v115, v115, v221, vcc
	v_cndmask_b32_e32 v116, v116, v222, vcc
	v_cndmask_b32_e32 v117, v117, v223, vcc
	global_store_dwordx4 v[140:141], v[114:117], off
	global_store_dwordx4 v[142:143], v[82:85], off
	s_waitcnt vmcnt(22)
; DEVI float blo(unsigned u) { return __uint_as_float(u << 16); }
; DEVI float bhi(unsigned u) { return __uint_as_float(u & 0xffff0000u); }
;     ...
; #pragma unroll
;       for (int nf = 0; nf < 4; nf++) {
;         const int col = n0 + wn * 64 + nf * 16 + quad * 4;
;         f32x4 a = acc[nf][mf];
;         if (EPI == EPI_RESID || EPI == EPI_RESID_ATOMIC) {
;           f32x4 x = a;
;           if (EPI == EPI_RESID || kpart == 0) {
;             const u32x2 xr = *(const u32x2*)((const u16*)(p.ws + WS_XB) + (size_t)row * 1024 + col);
;             x[0] += ALPHA * blo(xr[0]); x[1] += ALPHA * bhi(xr[0]); x[2] += ALPHA * blo(xr[1]); x[3] += ALPHA * bhi(xr[1]);
;           }
;           if (EPI == EPI_RESID) *(f32x4*)((float*)(p.ws + WS_XF) + (size_t)row * 1024 + col) = x;
;           else *(f32x4*)((float*)(p.ws + WS_SLAB) + ((size_t)kpart * 512 + (row - T_P)) * 1024 + col) = x;
	v_permlane16_swap_b32_e32 v180, v182
	v_permlane16_swap_b32_e32 v181, v183
	v_lshlrev_b32_e32 v216, 16, v180
	v_and_b32_e32 v180, 0xffff0000, v180
	v_lshlrev_b32_e32 v217, 16, v181
	v_and_b32_e32 v181, 0xffff0000, v181
	v_fmac_f32_e32 v50, s44, v216
	v_fmac_f32_e32 v51, s44, v180
	v_fmac_f32_e32 v52, s44, v217
	v_fmac_f32_e32 v53, s44, v181
	v_lshlrev_b32_e32 v216, 16, v182
	v_and_b32_e32 v182, 0xffff0000, v182
	v_lshlrev_b32_e32 v217, 16, v183
	v_and_b32_e32 v183, 0xffff0000, v183
	v_fmac_f32_e32 v18, s44, v216
	v_fmac_f32_e32 v19, s44, v182
	v_fmac_f32_e32 v20, s44, v217
	v_fmac_f32_e32 v21, s44, v183
	v_mov_b32_dpp v220, v18 quad_perm:[1,0,3,2] row_mask:0xf bank_mask:0xf
	v_mov_b32_dpp v221, v19 quad_perm:[1,0,3,2] row_mask:0xf bank_mask:0xf
	v_mov_b32_dpp v222, v20 quad_perm:[1,0,3,2] row_mask:0xf bank_mask:0xf
	v_mov_b32_dpp v223, v21 quad_perm:[1,0,3,2] row_mask:0xf bank_mask:0xf
	v_mov_b32_dpp v224, v50 quad_perm:[1,0,3,2] row_mask:0xf bank_mask:0xf
	v_mov_b32_dpp v225, v51 quad_perm:[1,0,3,2] row_mask:0xf bank_mask:0xf
	v_mov_b32_dpp v226, v52 quad_perm:[1,0,3,2] row_mask:0xf bank_mask:0xf
	v_mov_b32_dpp v227, v53 quad_perm:[1,0,3,2] row_mask:0xf bank_mask:0xf
	v_cndmask_b32_e32 v18, v224, v18, vcc
	v_cndmask_b32_e32 v19, v225, v19, vcc
	v_cndmask_b32_e32 v20, v226, v20, vcc
	v_cndmask_b32_e32 v21, v227, v21, vcc
	v_cndmask_b32_e32 v50, v50, v220, vcc
	v_cndmask_b32_e32 v51, v51, v221, vcc
	v_cndmask_b32_e32 v52, v52, v222, vcc
	v_cndmask_b32_e32 v53, v53, v223, vcc
	global_store_dwordx4 v[140:141], v[50:53], off offset:128
	global_store_dwordx4 v[142:143], v[18:21], off offset:128
	v_lshl_add_u64 v[140:141], v[140:141], 0, s[10:11]
	v_lshl_add_u64 v[142:143], v[142:143], 0, s[10:11]
	s_waitcnt vmcnt(23)
	v_permlane16_swap_b32_e32 v184, v186
	v_permlane16_swap_b32_e32 v185, v187
	v_lshlrev_b32_e32 v216, 16, v184
	v_and_b32_e32 v184, 0xffff0000, v184
	v_lshlrev_b32_e32 v217, 16, v185
	v_and_b32_e32 v185, 0xffff0000, v185
	v_fmac_f32_e32 v110, s44, v216
	v_fmac_f32_e32 v111, s44, v184
	v_fmac_f32_e32 v112, s44, v217
	v_fmac_f32_e32 v113, s44, v185
	v_lshlrev_b32_e32 v216, 16, v186
	v_and_b32_e32 v186, 0xffff0000, v186
	v_lshlrev_b32_e32 v217, 16, v187
	v_and_b32_e32 v187, 0xffff0000, v187
	v_fmac_f32_e32 v78, s44, v216
	v_fmac_f32_e32 v79, s44, v186
	v_fmac_f32_e32 v80, s44, v217
	v_fmac_f32_e32 v81, s44, v187
	v_mov_b32_dpp v220, v78 quad_perm:[1,0,3,2] row_mask:0xf bank_mask:0xf
	v_mov_b32_dpp v221, v79 quad_perm:[1,0,3,2] row_mask:0xf bank_mask:0xf
	v_mov_b32_dpp v222, v80 quad_perm:[1,0,3,2] row_mask:0xf bank_mask:0xf
	v_mov_b32_dpp v223, v81 quad_perm:[1,0,3,2] row_mask:0xf bank_mask:0xf
	v_mov_b32_dpp v224, v110 quad_perm:[1,0,3,2] row_mask:0xf bank_mask:0xf
	v_mov_b32_dpp v225, v111 quad_perm:[1,0,3,2] row_mask:0xf bank_mask:0xf
	v_mov_b32_dpp v226, v112 quad_perm:[1,0,3,2] row_mask:0xf bank_mask:0xf
	v_mov_b32_dpp v227, v113 quad_perm:[1,0,3,2] row_mask:0xf bank_mask:0xf
	v_cndmask_b32_e32 v78, v224, v78, vcc
	v_cndmask_b32_e32 v79, v225, v79, vcc
	v_cndmask_b32_e32 v80, v226, v80, vcc
	v_cndmask_b32_e32 v81, v227, v81, vcc
	v_cndmask_b32_e32 v110, v110, v220, vcc
	v_cndmask_b32_e32 v111, v111, v221, vcc
	v_cndmask_b32_e32 v112, v112, v222, vcc
	v_cndmask_b32_e32 v113, v113, v223, vcc
	global_store_dwordx4 v[140:141], v[110:113], off
	global_store_dwordx4 v[142:143], v[78:81], off
	s_waitcnt vmcnt(24)
	v_permlane16_swap_b32_e32 v188, v190
	v_permlane16_swap_b32_e32 v189, v191
	v_lshlrev_b32_e32 v216, 16, v188
	v_and_b32_e32 v188, 0xffff0000, v188
	v_lshlrev_b32_e32 v217, 16, v189
	v_and_b32_e32 v189, 0xffff0000, v189
	v_fmac_f32_e32 v46, s44, v216
	v_fmac_f32_e32 v47, s44, v188
	v_fmac_f32_e32 v48, s44, v217
	v_fmac_f32_e32 v49, s44, v189
	v_lshlrev_b32_e32 v216, 16, v190
	v_and_b32_e32 v190, 0xffff0000, v190
	v_lshlrev_b32_e32 v217, 16, v191
	v_and_b32_e32 v191, 0xffff0000, v191
	v_fmac_f32_e32 v14, s44, v216
	v_fmac_f32_e32 v15, s44, v190
	v_fmac_f32_e32 v16, s44, v217
	v_fmac_f32_e32 v17, s44, v191
	v_mov_b32_dpp v220, v14 quad_perm:[1,0,3,2] row_mask:0xf bank_mask:0xf
	v_mov_b32_dpp v221, v15 quad_perm:[1,0,3,2] row_mask:0xf bank_mask:0xf
	v_mov_b32_dpp v222, v16 quad_perm:[1,0,3,2] row_mask:0xf bank_mask:0xf
	v_mov_b32_dpp v223, v17 quad_perm:[1,0,3,2] row_mask:0xf bank_mask:0xf
	v_mov_b32_dpp v224, v46 quad_perm:[1,0,3,2] row_mask:0xf bank_mask:0xf
	v_mov_b32_dpp v225, v47 quad_perm:[1,0,3,2] row_mask:0xf bank_mask:0xf
	v_mov_b32_dpp v226, v48 quad_perm:[1,0,3,2] row_mask:0xf bank_mask:0xf
	v_mov_b32_dpp v227, v49 quad_perm:[1,0,3,2] row_mask:0xf bank_mask:0xf
	v_cndmask_b32_e32 v14, v224, v14, vcc
	v_cndmask_b32_e32 v15, v225, v15, vcc
	v_cndmask_b32_e32 v16, v226, v16, vcc
	v_cndmask_b32_e32 v17, v227, v17, vcc
	v_cndmask_b32_e32 v46, v46, v220, vcc
	v_cndmask_b32_e32 v47, v47, v221, vcc
	v_cndmask_b32_e32 v48, v48, v222, vcc
	v_cndmask_b32_e32 v49, v49, v223, vcc
	global_store_dwordx4 v[140:141], v[46:49], off offset:128
	global_store_dwordx4 v[142:143], v[14:17], off offset:128
	v_lshl_add_u64 v[140:141], v[140:141], 0, s[10:11]
	v_lshl_add_u64 v[142:143], v[142:143], 0, s[10:11]
	s_waitcnt vmcnt(25)
; DEVI float blo(unsigned u) { return __uint_as_float(u << 16); }
; DEVI float bhi(unsigned u) { return __uint_as_float(u & 0xffff0000u); }
;     ...
; #pragma unroll
;       for (int nf = 0; nf < 4; nf++) {
;         const int col = n0 + wn * 64 + nf * 16 + quad * 4;
;         f32x4 a = acc[nf][mf];
;         if (EPI == EPI_RESID || EPI == EPI_RESID_ATOMIC) {
;           f32x4 x = a;
;           if (EPI == EPI_RESID || kpart == 0) {
;             const u32x2 xr = *(const u32x2*)((const u16*)(p.ws + WS_XB) + (size_t)row * 1024 + col);
;             x[0] += ALPHA * blo(xr[0]); x[1] += ALPHA * bhi(xr[0]); x[2] += ALPHA * blo(xr[1]); x[3] += ALPHA * bhi(xr[1]);
;           }
;           if (EPI == EPI_RESID) *(f32x4*)((float*)(p.ws + WS_XF) + (size_t)row * 1024 + col) = x;
;           else *(f32x4*)((float*)(p.ws + WS_SLAB) + ((size_t)kpart * 512 + (row - T_P)) * 1024 + col) = x;
	v_permlane16_swap_b32_e32 v192, v194
	v_permlane16_swap_b32_e32 v193, v195
	v_lshlrev_b32_e32 v216, 16, v192
	v_and_b32_e32 v192, 0xffff0000, v192
	v_lshlrev_b32_e32 v217, 16, v193
	v_and_b32_e32 v193, 0xffff0000, v193
	v_fmac_f32_e32 v106, s44, v216
	v_fmac_f32_e32 v107, s44, v192
	v_fmac_f32_e32 v108, s44, v217
	v_fmac_f32_e32 v109, s44, v193
	v_lshlrev_b32_e32 v216, 16, v194
	v_and_b32_e32 v194, 0xffff0000, v194
	v_lshlrev_b32_e32 v217, 16, v195
	v_and_b32_e32 v195, 0xffff0000, v195
	v_fmac_f32_e32 v74, s44, v216
	v_fmac_f32_e32 v75, s44, v194
	v_fmac_f32_e32 v76, s44, v217
	v_fmac_f32_e32 v77, s44, v195
	v_mov_b32_dpp v220, v74 quad_perm:[1,0,3,2] row_mask:0xf bank_mask:0xf
	v_mov_b32_dpp v221, v75 quad_perm:[1,0,3,2] row_mask:0xf bank_mask:0xf
	v_mov_b32_dpp v222, v76 quad_perm:[1,0,3,2] row_mask:0xf bank_mask:0xf
	v_mov_b32_dpp v223, v77 quad_perm:[1,0,3,2] row_mask:0xf bank_mask:0xf
	v_mov_b32_dpp v224, v106 quad_perm:[1,0,3,2] row_mask:0xf bank_mask:0xf
	v_mov_b32_dpp v225, v107 quad_perm:[1,0,3,2] row_mask:0xf bank_mask:0xf
	v_mov_b32_dpp v226, v108 quad_perm:[1,0,3,2] row_mask:0xf bank_mask:0xf
	v_mov_b32_dpp v227, v109 quad_perm:[1,0,3,2] row_mask:0xf bank_mask:0xf
	v_cndmask_b32_e32 v74, v224, v74, vcc
	v_cndmask_b32_e32 v75, v225, v75, vcc
	v_cndmask_b32_e32 v76, v226, v76, vcc
	v_cndmask_b32_e32 v77, v227, v77, vcc
	v_cndmask_b32_e32 v106, v106, v220, vcc
	v_cndmask_b32_e32 v107, v107, v221, vcc
	v_cndmask_b32_e32 v108, v108, v222, vcc
	v_cndmask_b32_e32 v109, v109, v223, vcc
	global_store_dwordx4 v[140:141], v[106:109], off
	global_store_dwordx4 v[142:143], v[74:77], off
	s_waitcnt vmcnt(26)
	v_permlane16_swap_b32_e32 v196, v198
	v_permlane16_swap_b32_e32 v197, v199
	v_lshlrev_b32_e32 v216, 16, v196
	v_and_b32_e32 v196, 0xffff0000, v196
	v_lshlrev_b32_e32 v217, 16, v197
	v_and_b32_e32 v197, 0xffff0000, v197
	v_fmac_f32_e32 v42, s44, v216
	v_fmac_f32_e32 v43, s44, v196
	v_fmac_f32_e32 v44, s44, v217
	v_fmac_f32_e32 v45, s44, v197
	v_lshlrev_b32_e32 v216, 16, v198
	v_and_b32_e32 v198, 0xffff0000, v198
	v_lshlrev_b32_e32 v217, 16, v199
	v_and_b32_e32 v199, 0xffff0000, v199
	v_fmac_f32_e32 v10, s44, v216
	v_fmac_f32_e32 v11, s44, v198
	v_fmac_f32_e32 v12, s44, v217
	v_fmac_f32_e32 v13, s44, v199
	v_mov_b32_dpp v220, v10 quad_perm:[1,0,3,2] row_mask:0xf bank_mask:0xf
	v_mov_b32_dpp v221, v11 quad_perm:[1,0,3,2] row_mask:0xf bank_mask:0xf
	v_mov_b32_dpp v222, v12 quad_perm:[1,0,3,2] row_mask:0xf bank_mask:0xf
	v_mov_b32_dpp v223, v13 quad_perm:[1,0,3,2] row_mask:0xf bank_mask:0xf
	v_mov_b32_dpp v224, v42 quad_perm:[1,0,3,2] row_mask:0xf bank_mask:0xf
	v_mov_b32_dpp v225, v43 quad_perm:[1,0,3,2] row_mask:0xf bank_mask:0xf
	v_mov_b32_dpp v226, v44 quad_perm:[1,0,3,2] row_mask:0xf bank_mask:0xf
	v_mov_b32_dpp v227, v45 quad_perm:[1,0,3,2] row_mask:0xf bank_mask:0xf
	v_cndmask_b32_e32 v10, v224, v10, vcc
	v_cndmask_b32_e32 v11, v225, v11, vcc
	v_cndmask_b32_e32 v12, v226, v12, vcc
	v_cndmask_b32_e32 v13, v227, v13, vcc
	v_cndmask_b32_e32 v42, v42, v220, vcc
	v_cndmask_b32_e32 v43, v43, v221, vcc
	v_cndmask_b32_e32 v44, v44, v222, vcc
	v_cndmask_b32_e32 v45, v45, v223, vcc
	global_store_dwordx4 v[140:141], v[42:45], off offset:128
	global_store_dwordx4 v[142:143], v[10:13], off offset:128
	v_lshl_add_u64 v[140:141], v[140:141], 0, s[10:11]
	v_lshl_add_u64 v[142:143], v[142:143], 0, s[10:11]
	s_waitcnt vmcnt(27)
	v_permlane16_swap_b32_e32 v200, v202
	v_permlane16_swap_b32_e32 v201, v203
	v_lshlrev_b32_e32 v216, 16, v200
	v_and_b32_e32 v200, 0xffff0000, v200
	v_lshlrev_b32_e32 v217, 16, v201
	v_and_b32_e32 v201, 0xffff0000, v201
	v_fmac_f32_e32 v102, s44, v216
	v_fmac_f32_e32 v103, s44, v200
	v_fmac_f32_e32 v104, s44, v217
	v_fmac_f32_e32 v105, s44, v201
	v_lshlrev_b32_e32 v216, 16, v202
	v_and_b32_e32 v202, 0xffff0000, v202
	v_lshlrev_b32_e32 v217, 16, v203
	v_and_b32_e32 v203, 0xffff0000, v203
	v_fmac_f32_e32 v70, s44, v216
	v_fmac_f32_e32 v71, s44, v202
	v_fmac_f32_e32 v72, s44, v217
	v_fmac_f32_e32 v73, s44, v203
	v_mov_b32_dpp v220, v70 quad_perm:[1,0,3,2] row_mask:0xf bank_mask:0xf
	v_mov_b32_dpp v221, v71 quad_perm:[1,0,3,2] row_mask:0xf bank_mask:0xf
	v_mov_b32_dpp v222, v72 quad_perm:[1,0,3,2] row_mask:0xf bank_mask:0xf
	v_mov_b32_dpp v223, v73 quad_perm:[1,0,3,2] row_mask:0xf bank_mask:0xf
	v_mov_b32_dpp v224, v102 quad_perm:[1,0,3,2] row_mask:0xf bank_mask:0xf
	v_mov_b32_dpp v225, v103 quad_perm:[1,0,3,2] row_mask:0xf bank_mask:0xf
	v_mov_b32_dpp v226, v104 quad_perm:[1,0,3,2] row_mask:0xf bank_mask:0xf
	v_mov_b32_dpp v227, v105 quad_perm:[1,0,3,2] row_mask:0xf bank_mask:0xf
	v_cndmask_b32_e32 v70, v224, v70, vcc
	v_cndmask_b32_e32 v71, v225, v71, vcc
	v_cndmask_b32_e32 v72, v226, v72, vcc
	v_cndmask_b32_e32 v73, v227, v73, vcc
	v_cndmask_b32_e32 v102, v102, v220, vcc
	v_cndmask_b32_e32 v103, v103, v221, vcc
	v_cndmask_b32_e32 v104, v104, v222, vcc
	v_cndmask_b32_e32 v105, v105, v223, vcc
	global_store_dwordx4 v[140:141], v[102:105], off
	global_store_dwordx4 v[142:143], v[70:73], off
	s_waitcnt vmcnt(28)
; DEVI float blo(unsigned u) { return __uint_as_float(u << 16); }
; DEVI float bhi(unsigned u) { return __uint_as_float(u & 0xffff0000u); }
; DEVI int xcd_first_tile() { return (blockIdx.x & 7) * (gridDim.x >> 3) + (blockIdx.x >> 3); }
;     ...
; #pragma unroll
;       for (int nf = 0; nf < 4; nf++) {
;         const int col = n0 + wn * 64 + nf * 16 + quad * 4;
;         f32x4 a = acc[nf][mf];
;         if (EPI == EPI_RESID || EPI == EPI_RESID_ATOMIC) {
;           f32x4 x = a;
;           if (EPI == EPI_RESID || kpart == 0) {
;             const u32x2 xr = *(const u32x2*)((const u16*)(p.ws + WS_XB) + (size_t)row * 1024 + col);
;             x[0] += ALPHA * blo(xr[0]); x[1] += ALPHA * bhi(xr[0]); x[2] += ALPHA * blo(xr[1]); x[3] += ALPHA * bhi(xr[1]);
;           }
;           if (EPI == EPI_RESID) *(f32x4*)((float*)(p.ws + WS_XF) + (size_t)row * 1024 + col) = x;
;           else *(f32x4*)((float*)(p.ws + WS_SLAB) + ((size_t)kpart * 512 + (row - T_P)) * 1024 + col) = x;
; DEVI void run_phase(const Params& p, int ph, char* smem) {
;     ...
;       for (int t = xcd_first_tile(); t < 512 + 16 * 2; t += xcd_tile_step()) {
;         if (t < 512) {
;           int mt_, nt_; tile_coords(t, 64, 8, mt_, nt_);
;           gemm_tile256<EPI_RESID>(p, ox, 256, Bt, 256, mt_ * 256, nt_ * 128, nullptr, 0, smem);
;         } else {
;           const int u_ = t - 512, tl_ = u_ / 2, q_ = u_ - tl_ * 2;
;           gemm_tile256<EPI_RESID_ATOMIC>(p, ox, 256, Bt, 256, (64 + (tl_ & 1)) * 256, (tl_ >> 1) * 128, nullptr, 0, smem, q_ * 128, 4, q_);
;         }
	v_permlane16_swap_b32_e32 v204, v206
	v_permlane16_swap_b32_e32 v205, v207
	v_lshlrev_b32_e32 v216, 16, v204
	v_and_b32_e32 v204, 0xffff0000, v204
	v_lshlrev_b32_e32 v217, 16, v205
	v_and_b32_e32 v205, 0xffff0000, v205
	v_fmac_f32_e32 v38, s44, v216
	v_fmac_f32_e32 v39, s44, v204
	v_fmac_f32_e32 v40, s44, v217
	v_fmac_f32_e32 v41, s44, v205
	v_lshlrev_b32_e32 v216, 16, v206
	v_and_b32_e32 v206, 0xffff0000, v206
	v_lshlrev_b32_e32 v217, 16, v207
	v_and_b32_e32 v207, 0xffff0000, v207
	v_fmac_f32_e32 v6, s44, v216
	v_fmac_f32_e32 v7, s44, v206
	v_fmac_f32_e32 v8, s44, v217
	v_fmac_f32_e32 v9, s44, v207
	v_mov_b32_dpp v220, v6 quad_perm:[1,0,3,2] row_mask:0xf bank_mask:0xf
	v_mov_b32_dpp v221, v7 quad_perm:[1,0,3,2] row_mask:0xf bank_mask:0xf
	v_mov_b32_dpp v222, v8 quad_perm:[1,0,3,2] row_mask:0xf bank_mask:0xf
	v_mov_b32_dpp v223, v9 quad_perm:[1,0,3,2] row_mask:0xf bank_mask:0xf
	v_mov_b32_dpp v224, v38 quad_perm:[1,0,3,2] row_mask:0xf bank_mask:0xf
	v_mov_b32_dpp v225, v39 quad_perm:[1,0,3,2] row_mask:0xf bank_mask:0xf
	v_mov_b32_dpp v226, v40 quad_perm:[1,0,3,2] row_mask:0xf bank_mask:0xf
	v_mov_b32_dpp v227, v41 quad_perm:[1,0,3,2] row_mask:0xf bank_mask:0xf
	v_cndmask_b32_e32 v6, v224, v6, vcc
	v_cndmask_b32_e32 v7, v225, v7, vcc
	v_cndmask_b32_e32 v8, v226, v8, vcc
	v_cndmask_b32_e32 v9, v227, v9, vcc
	v_cndmask_b32_e32 v38, v38, v220, vcc
	v_cndmask_b32_e32 v39, v39, v221, vcc
	v_cndmask_b32_e32 v40, v40, v222, vcc
	v_cndmask_b32_e32 v41, v41, v223, vcc
	global_store_dwordx4 v[140:141], v[38:41], off offset:128
	global_store_dwordx4 v[142:143], v[6:9], off offset:128
	v_lshl_add_u64 v[140:141], v[140:141], 0, s[10:11]
	v_lshl_add_u64 v[142:143], v[142:143], 0, s[10:11]
	s_waitcnt vmcnt(29)
	v_permlane16_swap_b32_e32 v208, v210
	v_permlane16_swap_b32_e32 v209, v211
	v_lshlrev_b32_e32 v216, 16, v208
	v_and_b32_e32 v208, 0xffff0000, v208
	v_lshlrev_b32_e32 v217, 16, v209
	v_and_b32_e32 v209, 0xffff0000, v209
	v_fmac_f32_e32 v98, s44, v216
	v_fmac_f32_e32 v99, s44, v208
	v_fmac_f32_e32 v100, s44, v217
	v_fmac_f32_e32 v101, s44, v209
	v_lshlrev_b32_e32 v216, 16, v210
	v_and_b32_e32 v210, 0xffff0000, v210
	v_lshlrev_b32_e32 v217, 16, v211
	v_and_b32_e32 v211, 0xffff0000, v211
	v_fmac_f32_e32 v66, s44, v216
	v_fmac_f32_e32 v67, s44, v210
	v_fmac_f32_e32 v68, s44, v217
	v_fmac_f32_e32 v69, s44, v211
	v_mov_b32_dpp v220, v66 quad_perm:[1,0,3,2] row_mask:0xf bank_mask:0xf
	v_mov_b32_dpp v221, v67 quad_perm:[1,0,3,2] row_mask:0xf bank_mask:0xf
	v_mov_b32_dpp v222, v68 quad_perm:[1,0,3,2] row_mask:0xf bank_mask:0xf
	v_mov_b32_dpp v223, v69 quad_perm:[1,0,3,2] row_mask:0xf bank_mask:0xf
	v_mov_b32_dpp v224, v98 quad_perm:[1,0,3,2] row_mask:0xf bank_mask:0xf
	v_mov_b32_dpp v225, v99 quad_perm:[1,0,3,2] row_mask:0xf bank_mask:0xf
	v_mov_b32_dpp v226, v100 quad_perm:[1,0,3,2] row_mask:0xf bank_mask:0xf
	v_mov_b32_dpp v227, v101 quad_perm:[1,0,3,2] row_mask:0xf bank_mask:0xf
	v_cndmask_b32_e32 v66, v224, v66, vcc
	v_cndmask_b32_e32 v67, v225, v67, vcc
	v_cndmask_b32_e32 v68, v226, v68, vcc
	v_cndmask_b32_e32 v69, v227, v69, vcc
	v_cndmask_b32_e32 v98, v98, v220, vcc
	v_cndmask_b32_e32 v99, v99, v221, vcc
	v_cndmask_b32_e32 v100, v100, v222, vcc
	v_cndmask_b32_e32 v101, v101, v223, vcc
	global_store_dwordx4 v[140:141], v[98:101], off
	global_store_dwordx4 v[142:143], v[66:69], off
	s_waitcnt vmcnt(30)
	v_permlane16_swap_b32_e32 v212, v214
	v_permlane16_swap_b32_e32 v213, v215
	v_lshlrev_b32_e32 v216, 16, v212
	v_and_b32_e32 v212, 0xffff0000, v212
	v_lshlrev_b32_e32 v217, 16, v213
	v_and_b32_e32 v213, 0xffff0000, v213
	v_fmac_f32_e32 v34, s44, v216
	v_fmac_f32_e32 v35, s44, v212
	v_fmac_f32_e32 v36, s44, v217
	v_fmac_f32_e32 v37, s44, v213
	v_lshlrev_b32_e32 v216, 16, v214
	v_and_b32_e32 v214, 0xffff0000, v214
	v_lshlrev_b32_e32 v217, 16, v215
	v_and_b32_e32 v215, 0xffff0000, v215
	v_fmac_f32_e32 v2, s44, v216
	v_fmac_f32_e32 v3, s44, v214
	v_fmac_f32_e32 v4, s44, v217
	v_fmac_f32_e32 v5, s44, v215
	v_mov_b32_dpp v220, v2 quad_perm:[1,0,3,2] row_mask:0xf bank_mask:0xf
	v_mov_b32_dpp v221, v3 quad_perm:[1,0,3,2] row_mask:0xf bank_mask:0xf
	v_mov_b32_dpp v222, v4 quad_perm:[1,0,3,2] row_mask:0xf bank_mask:0xf
	v_mov_b32_dpp v223, v5 quad_perm:[1,0,3,2] row_mask:0xf bank_mask:0xf
	v_mov_b32_dpp v224, v34 quad_perm:[1,0,3,2] row_mask:0xf bank_mask:0xf
	v_mov_b32_dpp v225, v35 quad_perm:[1,0,3,2] row_mask:0xf bank_mask:0xf
	v_mov_b32_dpp v226, v36 quad_perm:[1,0,3,2] row_mask:0xf bank_mask:0xf
	v_mov_b32_dpp v227, v37 quad_perm:[1,0,3,2] row_mask:0xf bank_mask:0xf
	v_cndmask_b32_e32 v2, v224, v2, vcc
	v_cndmask_b32_e32 v3, v225, v3, vcc
	v_cndmask_b32_e32 v4, v226, v4, vcc
	v_cndmask_b32_e32 v5, v227, v5, vcc
	v_cndmask_b32_e32 v34, v34, v220, vcc
	v_cndmask_b32_e32 v35, v35, v221, vcc
	v_cndmask_b32_e32 v36, v36, v222, vcc
	v_cndmask_b32_e32 v37, v37, v223, vcc
	global_store_dwordx4 v[140:141], v[34:37], off offset:128
	global_store_dwordx4 v[142:143], v[2:5], off offset:128
	v_readlane_b32 s39, v250, 7
	s_cmpk_lg_u32 s39, 0x200
	s_cbranch_scc1 .LBB0_146
	v_readlane_b32 s40, v250, 0
	s_lshr_b32 s41, s40, 3
	s_and_b32 s40, s40, 7
	s_mul_i32 s40, s40, 4
	s_add_i32 s40, s40, s41
	s_cmp_lt_u32 s41, 4
	s_movk_i32 s38, 0x4000
	s_branch .LBB0_146

;     ...
;   for (int kt = 0; kt < nk; kt++) {
;     if (kt + 1 < nk) asm volatile("s_waitcnt vmcnt(6)" ::: "memory");
;     else asm volatile("s_waitcnt vmcnt(0)" ::: "memory");
;     __builtin_amdgcn_s_barrier();
;     asm volatile("" ::: "memory");
;     if (kt + 2 < nk) G2_STAGE(kt + 2);
;     const char* cS = smem + (kt % 3) * 24576;
;     bf16x8 xa[8], wb[4];
; #pragma unroll
;     for (int f = 0; f < 8; f++) xa[f] = *(const bf16x8*)(cS + aoff + f * 1024);
; #pragma unroll
;     for (int f = 0; f < 4; f++) wb[f] = *(const bf16x8*)(cS + boff + f * 1024);
; #pragma unroll
;     for (int nf = 0; nf < 4; nf++)
; #pragma unroll
;       for (int mf = 0; mf < 8; mf++)
;         acc[nf][mf] = __builtin_amdgcn_mfma_f32_16x16x32_bf16(wb[nf], xa[mf], acc[nf][mf], 0, 0, 0);
;   }
.Lt4_loop:
	.p2align 3
	s_waitcnt vmcnt(6) lgkmcnt(0)
	s_barrier
	s_setprio 1
	v_add_u32_e32 v144, s41, v136
	v_mfma_f32_16x16x32_bf16 v[126:129], v[184:187], v[146:149], v[126:129]
	ds_read_b128 v[200:203], v144 offset:0
	v_mfma_f32_16x16x32_bf16 v[122:125], v[184:187], v[152:155], v[122:125]
	ds_read_b128 v[204:207], v144 offset:1024
	v_mfma_f32_16x16x32_bf16 v[118:121], v[184:187], v[156:159], v[118:121]
	ds_read_b128 v[208:211], v144 offset:2048
	v_mfma_f32_16x16x32_bf16 v[114:117], v[184:187], v[162:165], v[114:117]
	ds_read_b128 v[212:215], v144 offset:3072
	v_mfma_f32_16x16x32_bf16 v[110:113], v[184:187], v[166:169], v[110:113]
	ds_read_b128 v[216:219], v144 offset:4096
	v_mfma_f32_16x16x32_bf16 v[106:109], v[184:187], v[170:173], v[106:109]
	ds_read_b128 v[220:223], v144 offset:5120
	v_mfma_f32_16x16x32_bf16 v[102:105], v[184:187], v[176:179], v[102:105]
	ds_read_b128 v[224:227], v144 offset:6144
	v_mfma_f32_16x16x32_bf16 v[98:101], v[184:187], v[180:183], v[98:101]
	ds_read_b128 v[228:231], v144 offset:7168
	v_mfma_f32_16x16x32_bf16 v[94:97], v[188:191], v[146:149], v[94:97]
	v_add_u32_e64 v144, s41, v137
	v_mfma_f32_16x16x32_bf16 v[90:93], v[188:191], v[152:155], v[90:93]
	v_mfma_f32_16x16x32_bf16 v[86:89], v[188:191], v[156:159], v[86:89]
	ds_read_b128 v[232:235], v144 offset:16384
	v_mfma_f32_16x16x32_bf16 v[82:85], v[188:191], v[162:165], v[82:85]
	ds_read_b128 v[236:239], v144 offset:17408
	v_mfma_f32_16x16x32_bf16 v[78:81], v[188:191], v[166:169], v[78:81]
	ds_read_b128 v[240:243], v144 offset:18432
	v_mfma_f32_16x16x32_bf16 v[74:77], v[188:191], v[170:173], v[74:77]
	ds_read_b128 v[244:247], v144 offset:19456
	v_mfma_f32_16x16x32_bf16 v[70:73], v[188:191], v[176:179], v[70:73]
	s_add_i32 s43, s47, s42
	s_mov_b32 m0, s43
	v_lshl_add_u64 v[142:143], v[132:133], 0, s[2:3]
	v_mfma_f32_16x16x32_bf16 v[66:69], v[188:191], v[180:183], v[66:69]
	global_load_lds_dwordx4 v[132:133], off
	s_add_i32 m0, m0, 0x1000
	v_mfma_f32_16x16x32_bf16 v[62:65], v[192:195], v[146:149], v[62:65]
	v_mfma_f32_16x16x32_bf16 v[58:61], v[192:195], v[152:155], v[58:61]
	v_mfma_f32_16x16x32_bf16 v[54:57], v[192:195], v[156:159], v[54:57]
	global_load_lds_dwordx4 v[142:143], off
	v_lshl_add_u64 v[142:143], v[142:143], 0, s[2:3]
	s_add_i32 m0, m0, 0x1000
	v_mfma_f32_16x16x32_bf16 v[50:53], v[192:195], v[162:165], v[50:53]
	v_mfma_f32_16x16x32_bf16 v[46:49], v[192:195], v[166:169], v[46:49]
	v_mfma_f32_16x16x32_bf16 v[42:45], v[192:195], v[170:173], v[42:45]
	global_load_lds_dwordx4 v[142:143], off
	v_lshl_add_u64 v[142:143], v[142:143], 0, s[2:3]
	s_add_i32 m0, m0, 0x1000
	v_mfma_f32_16x16x32_bf16 v[38:41], v[192:195], v[176:179], v[38:41]
	v_mfma_f32_16x16x32_bf16 v[34:37], v[192:195], v[180:183], v[34:37]
	v_mfma_f32_16x16x32_bf16 v[30:33], v[196:199], v[146:149], v[30:33]
	global_load_lds_dwordx4 v[142:143], off
	s_add_i32 m0, m0, 0x1000
	v_lshl_add_u64 v[142:143], v[134:135], 0, s[2:3]
	v_mfma_f32_16x16x32_bf16 v[26:29], v[196:199], v[152:155], v[26:29]
	v_mfma_f32_16x16x32_bf16 v[22:25], v[196:199], v[156:159], v[22:25]
	v_mfma_f32_16x16x32_bf16 v[18:21], v[196:199], v[162:165], v[18:21]
	global_load_lds_dwordx4 v[134:135], off
	s_add_i32 m0, m0, 0x1000
	v_lshl_add_u64 v[132:133], v[132:133], 0, s[12:13]
	v_mfma_f32_16x16x32_bf16 v[14:17], v[196:199], v[166:169], v[14:17]
	v_mfma_f32_16x16x32_bf16 v[10:13], v[196:199], v[170:173], v[10:13]
	v_mfma_f32_16x16x32_bf16 v[6:9], v[196:199], v[176:179], v[6:9]
	global_load_lds_dwordx4 v[142:143], off
	v_lshl_add_u64 v[134:135], v[134:135], 0, s[4:5]
	v_mfma_f32_16x16x32_bf16 v[2:5], v[196:199], v[180:183], v[2:5]
	s_setprio 0
	s_mov_b32 s42, s41
	s_add_i32 s41, s41, 0x6000
	s_cmp_eq_u32 s41, 0x12000
	s_cselect_b32 s41, 0, s41
	s_nop 0
	.p2align 3
	s_waitcnt vmcnt(6) lgkmcnt(0)
	s_barrier
	s_setprio 1
	v_add_u32_e32 v144, s41, v136
	v_mfma_f32_16x16x32_bf16 v[126:129], v[232:235], v[200:203], v[126:129]
	ds_read_b128 v[146:149], v144 offset:0
	v_mfma_f32_16x16x32_bf16 v[122:125], v[232:235], v[204:207], v[122:125]
	ds_read_b128 v[152:155], v144 offset:1024
	v_mfma_f32_16x16x32_bf16 v[118:121], v[232:235], v[208:211], v[118:121]
	ds_read_b128 v[156:159], v144 offset:2048
	v_mfma_f32_16x16x32_bf16 v[114:117], v[232:235], v[212:215], v[114:117]
	ds_read_b128 v[162:165], v144 offset:3072
	v_mfma_f32_16x16x32_bf16 v[110:113], v[232:235], v[216:219], v[110:113]
	ds_read_b128 v[166:169], v144 offset:4096
	v_mfma_f32_16x16x32_bf16 v[106:109], v[232:235], v[220:223], v[106:109]
	ds_read_b128 v[170:173], v144 offset:5120
	v_mfma_f32_16x16x32_bf16 v[102:105], v[232:235], v[224:227], v[102:105]
	ds_read_b128 v[176:179], v144 offset:6144
	v_mfma_f32_16x16x32_bf16 v[98:101], v[232:235], v[228:231], v[98:101]
	ds_read_b128 v[180:183], v144 offset:7168
	v_mfma_f32_16x16x32_bf16 v[94:97], v[236:239], v[200:203], v[94:97]
	v_add_u32_e64 v144, s41, v137
	v_mfma_f32_16x16x32_bf16 v[90:93], v[236:239], v[204:207], v[90:93]
	v_mfma_f32_16x16x32_bf16 v[86:89], v[236:239], v[208:211], v[86:89]
	ds_read_b128 v[184:187], v144 offset:16384
	v_mfma_f32_16x16x32_bf16 v[82:85], v[236:239], v[212:215], v[82:85]
	ds_read_b128 v[188:191], v144 offset:17408
	v_mfma_f32_16x16x32_bf16 v[78:81], v[236:239], v[216:219], v[78:81]
	ds_read_b128 v[192:195], v144 offset:18432
	v_mfma_f32_16x16x32_bf16 v[74:77], v[236:239], v[220:223], v[74:77]
	ds_read_b128 v[196:199], v144 offset:19456
	v_mfma_f32_16x16x32_bf16 v[70:73], v[236:239], v[224:227], v[70:73]
	s_add_i32 s43, s47, s42
	s_mov_b32 m0, s43
	v_lshl_add_u64 v[142:143], v[132:133], 0, s[2:3]
	v_mfma_f32_16x16x32_bf16 v[66:69], v[236:239], v[228:231], v[66:69]
	global_load_lds_dwordx4 v[132:133], off
;     ...
;   for (int kt = 0; kt < nk; kt++) {
;     if (kt + 1 < nk) asm volatile("s_waitcnt vmcnt(6)" ::: "memory");
;     else asm volatile("s_waitcnt vmcnt(0)" ::: "memory");
;     __builtin_amdgcn_s_barrier();
;     asm volatile("" ::: "memory");
;     if (kt + 2 < nk) G2_STAGE(kt + 2);
;     const char* cS = smem + (kt % 3) * 24576;
;     bf16x8 xa[8], wb[4];
; #pragma unroll
;     for (int f = 0; f < 8; f++) xa[f] = *(const bf16x8*)(cS + aoff + f * 1024);
; #pragma unroll
;     for (int f = 0; f < 4; f++) wb[f] = *(const bf16x8*)(cS + boff + f * 1024);
; #pragma unroll
;     for (int nf = 0; nf < 4; nf++)
; #pragma unroll
;       for (int mf = 0; mf < 8; mf++)
;         acc[nf][mf] = __builtin_amdgcn_mfma_f32_16x16x32_bf16(wb[nf], xa[mf], acc[nf][mf], 0, 0, 0);
;   }
	s_add_i32 m0, m0, 0x1000
	v_mfma_f32_16x16x32_bf16 v[62:65], v[240:243], v[200:203], v[62:65]
	v_mfma_f32_16x16x32_bf16 v[58:61], v[240:243], v[204:207], v[58:61]
	v_mfma_f32_16x16x32_bf16 v[54:57], v[240:243], v[208:211], v[54:57]
	global_load_lds_dwordx4 v[142:143], off
	v_lshl_add_u64 v[142:143], v[142:143], 0, s[2:3]
	s_add_i32 m0, m0, 0x1000
	v_mfma_f32_16x16x32_bf16 v[50:53], v[240:243], v[212:215], v[50:53]
	v_mfma_f32_16x16x32_bf16 v[46:49], v[240:243], v[216:219], v[46:49]
	v_mfma_f32_16x16x32_bf16 v[42:45], v[240:243], v[220:223], v[42:45]
	global_load_lds_dwordx4 v[142:143], off
	v_lshl_add_u64 v[142:143], v[142:143], 0, s[2:3]
	s_add_i32 m0, m0, 0x1000
	v_mfma_f32_16x16x32_bf16 v[38:41], v[240:243], v[224:227], v[38:41]
	v_mfma_f32_16x16x32_bf16 v[34:37], v[240:243], v[228:231], v[34:37]
	v_mfma_f32_16x16x32_bf16 v[30:33], v[244:247], v[200:203], v[30:33]
	global_load_lds_dwordx4 v[142:143], off
	s_add_i32 m0, m0, 0x1000
	v_lshl_add_u64 v[142:143], v[134:135], 0, s[2:3]
	v_mfma_f32_16x16x32_bf16 v[26:29], v[244:247], v[204:207], v[26:29]
	v_mfma_f32_16x16x32_bf16 v[22:25], v[244:247], v[208:211], v[22:25]
	v_mfma_f32_16x16x32_bf16 v[18:21], v[244:247], v[212:215], v[18:21]
	global_load_lds_dwordx4 v[134:135], off
	s_add_i32 m0, m0, 0x1000
	v_lshl_add_u64 v[132:133], v[132:133], 0, s[12:13]
	v_mfma_f32_16x16x32_bf16 v[14:17], v[244:247], v[216:219], v[14:17]
	v_mfma_f32_16x16x32_bf16 v[10:13], v[244:247], v[220:223], v[10:13]
	v_mfma_f32_16x16x32_bf16 v[6:9], v[244:247], v[224:227], v[6:9]
	global_load_lds_dwordx4 v[142:143], off
	v_lshl_add_u64 v[134:135], v[134:135], 0, s[4:5]
	v_mfma_f32_16x16x32_bf16 v[2:5], v[244:247], v[228:231], v[2:5]
	s_setprio 0
	s_mov_b32 s42, s41
	s_add_i32 s41, s41, 0x6000
	s_cmp_eq_u32 s41, 0x12000
	s_cselect_b32 s41, 0, s41
	s_nop 0
	s_sub_i32 s40, s40, 1
	s_cmp_lg_u32 s40, 0
	s_cbranch_scc1 .Lt4_loop
	.p2align 3
	s_waitcnt vmcnt(6) lgkmcnt(0)
	s_barrier
	s_setprio 1
	v_add_u32_e32 v144, s41, v136
	v_mfma_f32_16x16x32_bf16 v[126:129], v[184:187], v[146:149], v[126:129]
	ds_read_b128 v[200:203], v144 offset:0
	v_mfma_f32_16x16x32_bf16 v[122:125], v[184:187], v[152:155], v[122:125]
	ds_read_b128 v[204:207], v144 offset:1024
	v_mfma_f32_16x16x32_bf16 v[118:121], v[184:187], v[156:159], v[118:121]
	ds_read_b128 v[208:211], v144 offset:2048
	v_mfma_f32_16x16x32_bf16 v[114:117], v[184:187], v[162:165], v[114:117]
	ds_read_b128 v[212:215], v144 offset:3072
	v_mfma_f32_16x16x32_bf16 v[110:113], v[184:187], v[166:169], v[110:113]
	ds_read_b128 v[216:219], v144 offset:4096
	v_mfma_f32_16x16x32_bf16 v[106:109], v[184:187], v[170:173], v[106:109]
	ds_read_b128 v[220:223], v144 offset:5120
	v_mfma_f32_16x16x32_bf16 v[102:105], v[184:187], v[176:179], v[102:105]
	ds_read_b128 v[224:227], v144 offset:6144
	v_mfma_f32_16x16x32_bf16 v[98:101], v[184:187], v[180:183], v[98:101]
	ds_read_b128 v[228:231], v144 offset:7168
	v_mfma_f32_16x16x32_bf16 v[94:97], v[188:191], v[146:149], v[94:97]
	v_add_u32_e64 v144, s41, v137
	v_mfma_f32_16x16x32_bf16 v[90:93], v[188:191], v[152:155], v[90:93]
	v_mfma_f32_16x16x32_bf16 v[86:89], v[188:191], v[156:159], v[86:89]
	ds_read_b128 v[232:235], v144 offset:16384
	v_mfma_f32_16x16x32_bf16 v[82:85], v[188:191], v[162:165], v[82:85]
	ds_read_b128 v[236:239], v144 offset:17408
	v_mfma_f32_16x16x32_bf16 v[78:81], v[188:191], v[166:169], v[78:81]
	ds_read_b128 v[240:243], v144 offset:18432
	v_mfma_f32_16x16x32_bf16 v[74:77], v[188:191], v[170:173], v[74:77]
	ds_read_b128 v[244:247], v144 offset:19456
	v_mfma_f32_16x16x32_bf16 v[70:73], v[188:191], v[176:179], v[70:73]
	s_add_i32 s43, s47, s42
	s_mov_b32 m0, s43
	v_lshl_add_u64 v[142:143], v[132:133], 0, s[2:3]
	v_mfma_f32_16x16x32_bf16 v[66:69], v[188:191], v[180:183], v[66:69]
	global_load_lds_dwordx4 v[132:133], off
	s_add_i32 m0, m0, 0x1000
	v_mfma_f32_16x16x32_bf16 v[62:65], v[192:195], v[146:149], v[62:65]
	v_mfma_f32_16x16x32_bf16 v[58:61], v[192:195], v[152:155], v[58:61]
	v_mfma_f32_16x16x32_bf16 v[54:57], v[192:195], v[156:159], v[54:57]
	global_load_lds_dwordx4 v[142:143], off
	v_lshl_add_u64 v[142:143], v[142:143], 0, s[2:3]
	s_add_i32 m0, m0, 0x1000
	v_mfma_f32_16x16x32_bf16 v[50:53], v[192:195], v[162:165], v[50:53]
	v_mfma_f32_16x16x32_bf16 v[46:49], v[192:195], v[166:169], v[46:49]
	v_mfma_f32_16x16x32_bf16 v[42:45], v[192:195], v[170:173], v[42:45]
	global_load_lds_dwordx4 v[142:143], off
	v_lshl_add_u64 v[142:143], v[142:143], 0, s[2:3]
	s_add_i32 m0, m0, 0x1000
	v_mfma_f32_16x16x32_bf16 v[38:41], v[192:195], v[176:179], v[38:41]
	v_mfma_f32_16x16x32_bf16 v[34:37], v[192:195], v[180:183], v[34:37]
	v_mfma_f32_16x16x32_bf16 v[30:33], v[196:199], v[146:149], v[30:33]
	global_load_lds_dwordx4 v[142:143], off
	s_add_i32 m0, m0, 0x1000
	v_lshl_add_u64 v[142:143], v[134:135], 0, s[2:3]
	v_mfma_f32_16x16x32_bf16 v[26:29], v[196:199], v[152:155], v[26:29]
	v_mfma_f32_16x16x32_bf16 v[22:25], v[196:199], v[156:159], v[22:25]
	v_mfma_f32_16x16x32_bf16 v[18:21], v[196:199], v[162:165], v[18:21]
	global_load_lds_dwordx4 v[134:135], off
	s_add_i32 m0, m0, 0x1000
	v_lshl_add_u64 v[132:133], v[132:133], 0, s[12:13]
	v_mfma_f32_16x16x32_bf16 v[14:17], v[196:199], v[166:169], v[14:17]
	v_mfma_f32_16x16x32_bf16 v[10:13], v[196:199], v[170:173], v[10:13]
	v_mfma_f32_16x16x32_bf16 v[6:9], v[196:199], v[176:179], v[6:9]
	global_load_lds_dwordx4 v[142:143], off
	v_lshl_add_u64 v[134:135], v[134:135], 0, s[4:5]
	v_mfma_f32_16x16x32_bf16 v[2:5], v[196:199], v[180:183], v[2:5]
	s_setprio 0
	s_mov_b32 s42, s41
	s_add_i32 s41, s41, 0x6000
	s_cmp_eq_u32 s41, 0x12000
	s_cselect_b32 s41, 0, s41
	s_nop 0
	.p2align 3
	s_waitcnt vmcnt(6) lgkmcnt(0)
	s_barrier
;     ...
;   for (int kt = 0; kt < nk; kt++) {
;     if (kt + 1 < nk) asm volatile("s_waitcnt vmcnt(6)" ::: "memory");
;     else asm volatile("s_waitcnt vmcnt(0)" ::: "memory");
;     __builtin_amdgcn_s_barrier();
;     asm volatile("" ::: "memory");
;     if (kt + 2 < nk) G2_STAGE(kt + 2);
;     const char* cS = smem + (kt % 3) * 24576;
;     bf16x8 xa[8], wb[4];
; #pragma unroll
;     for (int f = 0; f < 8; f++) xa[f] = *(const bf16x8*)(cS + aoff + f * 1024);
; #pragma unroll
;     for (int f = 0; f < 4; f++) wb[f] = *(const bf16x8*)(cS + boff + f * 1024);
; #pragma unroll
;     for (int nf = 0; nf < 4; nf++)
; #pragma unroll
;       for (int mf = 0; mf < 8; mf++)
;         acc[nf][mf] = __builtin_amdgcn_mfma_f32_16x16x32_bf16(wb[nf], xa[mf], acc[nf][mf], 0, 0, 0);
;   }
	s_setprio 1
	v_add_u32_e32 v144, s41, v136
	v_mfma_f32_16x16x32_bf16 v[126:129], v[232:235], v[200:203], v[126:129]
	ds_read_b128 v[146:149], v144 offset:0
	v_mfma_f32_16x16x32_bf16 v[122:125], v[232:235], v[204:207], v[122:125]
	ds_read_b128 v[152:155], v144 offset:1024
	v_mfma_f32_16x16x32_bf16 v[118:121], v[232:235], v[208:211], v[118:121]
	ds_read_b128 v[156:159], v144 offset:2048
	v_mfma_f32_16x16x32_bf16 v[114:117], v[232:235], v[212:215], v[114:117]
	ds_read_b128 v[162:165], v144 offset:3072
	v_mfma_f32_16x16x32_bf16 v[110:113], v[232:235], v[216:219], v[110:113]
	ds_read_b128 v[166:169], v144 offset:4096
	v_mfma_f32_16x16x32_bf16 v[106:109], v[232:235], v[220:223], v[106:109]
	ds_read_b128 v[170:173], v144 offset:5120
	v_mfma_f32_16x16x32_bf16 v[102:105], v[232:235], v[224:227], v[102:105]
	ds_read_b128 v[176:179], v144 offset:6144
	v_mfma_f32_16x16x32_bf16 v[98:101], v[232:235], v[228:231], v[98:101]
	ds_read_b128 v[180:183], v144 offset:7168
	v_mfma_f32_16x16x32_bf16 v[94:97], v[236:239], v[200:203], v[94:97]
	v_add_u32_e64 v144, s41, v137
	v_mfma_f32_16x16x32_bf16 v[90:93], v[236:239], v[204:207], v[90:93]
	v_mfma_f32_16x16x32_bf16 v[86:89], v[236:239], v[208:211], v[86:89]
	ds_read_b128 v[184:187], v144 offset:16384
	v_mfma_f32_16x16x32_bf16 v[82:85], v[236:239], v[212:215], v[82:85]
	ds_read_b128 v[188:191], v144 offset:17408
	v_mfma_f32_16x16x32_bf16 v[78:81], v[236:239], v[216:219], v[78:81]
	ds_read_b128 v[192:195], v144 offset:18432
	v_mfma_f32_16x16x32_bf16 v[74:77], v[236:239], v[220:223], v[74:77]
	ds_read_b128 v[196:199], v144 offset:19456
	v_mfma_f32_16x16x32_bf16 v[70:73], v[236:239], v[224:227], v[70:73]
	v_mfma_f32_16x16x32_bf16 v[66:69], v[236:239], v[228:231], v[66:69]
	v_mfma_f32_16x16x32_bf16 v[62:65], v[240:243], v[200:203], v[62:65]
	v_mfma_f32_16x16x32_bf16 v[58:61], v[240:243], v[204:207], v[58:61]
	v_mfma_f32_16x16x32_bf16 v[54:57], v[240:243], v[208:211], v[54:57]
	v_mfma_f32_16x16x32_bf16 v[50:53], v[240:243], v[212:215], v[50:53]
	v_mfma_f32_16x16x32_bf16 v[46:49], v[240:243], v[216:219], v[46:49]
	v_mfma_f32_16x16x32_bf16 v[42:45], v[240:243], v[220:223], v[42:45]
	v_mfma_f32_16x16x32_bf16 v[38:41], v[240:243], v[224:227], v[38:41]
	v_mfma_f32_16x16x32_bf16 v[34:37], v[240:243], v[228:231], v[34:37]
	v_mfma_f32_16x16x32_bf16 v[30:33], v[244:247], v[200:203], v[30:33]
	v_mfma_f32_16x16x32_bf16 v[26:29], v[244:247], v[204:207], v[26:29]
	v_mfma_f32_16x16x32_bf16 v[22:25], v[244:247], v[208:211], v[22:25]
	v_mfma_f32_16x16x32_bf16 v[18:21], v[244:247], v[212:215], v[18:21]
	v_mfma_f32_16x16x32_bf16 v[14:17], v[244:247], v[216:219], v[14:17]
	v_mfma_f32_16x16x32_bf16 v[10:13], v[244:247], v[220:223], v[10:13]
	v_mfma_f32_16x16x32_bf16 v[6:9], v[244:247], v[224:227], v[6:9]
	v_mfma_f32_16x16x32_bf16 v[2:5], v[244:247], v[228:231], v[2:5]
	s_setprio 0
	s_mov_b32 s42, s41
	s_add_i32 s41, s41, 0x6000
	s_cmp_eq_u32 s41, 0x12000
	s_cselect_b32 s41, 0, s41
	s_nop 0
	.p2align 3
	s_waitcnt vmcnt(0) lgkmcnt(0)
	s_barrier
	s_setprio 1
	v_add_u32_e32 v144, s41, v136
	v_mfma_f32_16x16x32_bf16 v[126:129], v[184:187], v[146:149], v[126:129]
	ds_read_b128 v[200:203], v144 offset:0
	v_mfma_f32_16x16x32_bf16 v[122:125], v[184:187], v[152:155], v[122:125]
	ds_read_b128 v[204:207], v144 offset:1024
	v_mfma_f32_16x16x32_bf16 v[118:121], v[184:187], v[156:159], v[118:121]
	ds_read_b128 v[208:211], v144 offset:2048
	v_mfma_f32_16x16x32_bf16 v[114:117], v[184:187], v[162:165], v[114:117]
	ds_read_b128 v[212:215], v144 offset:3072
	v_mfma_f32_16x16x32_bf16 v[110:113], v[184:187], v[166:169], v[110:113]
	ds_read_b128 v[216:219], v144 offset:4096
	v_mfma_f32_16x16x32_bf16 v[106:109], v[184:187], v[170:173], v[106:109]
	ds_read_b128 v[220:223], v144 offset:5120
	v_mfma_f32_16x16x32_bf16 v[102:105], v[184:187], v[176:179], v[102:105]
	ds_read_b128 v[224:227], v144 offset:6144
	v_mfma_f32_16x16x32_bf16 v[98:101], v[184:187], v[180:183], v[98:101]
	ds_read_b128 v[228:231], v144 offset:7168
	v_mfma_f32_16x16x32_bf16 v[94:97], v[188:191], v[146:149], v[94:97]
	v_add_u32_e64 v144, s41, v137
	v_mfma_f32_16x16x32_bf16 v[90:93], v[188:191], v[152:155], v[90:93]
	v_mfma_f32_16x16x32_bf16 v[86:89], v[188:191], v[156:159], v[86:89]
	ds_read_b128 v[232:235], v144 offset:16384
	v_mfma_f32_16x16x32_bf16 v[82:85], v[188:191], v[162:165], v[82:85]
	ds_read_b128 v[236:239], v144 offset:17408
	v_mfma_f32_16x16x32_bf16 v[78:81], v[188:191], v[166:169], v[78:81]
	ds_read_b128 v[240:243], v144 offset:18432
	v_mfma_f32_16x16x32_bf16 v[74:77], v[188:191], v[170:173], v[74:77]
	ds_read_b128 v[244:247], v144 offset:19456
	v_mfma_f32_16x16x32_bf16 v[70:73], v[188:191], v[176:179], v[70:73]
	v_mfma_f32_16x16x32_bf16 v[66:69], v[188:191], v[180:183], v[66:69]
	v_mfma_f32_16x16x32_bf16 v[62:65], v[192:195], v[146:149], v[62:65]
	v_mfma_f32_16x16x32_bf16 v[58:61], v[192:195], v[152:155], v[58:61]
	v_mfma_f32_16x16x32_bf16 v[54:57], v[192:195], v[156:159], v[54:57]
	v_mfma_f32_16x16x32_bf16 v[50:53], v[192:195], v[162:165], v[50:53]
	v_mfma_f32_16x16x32_bf16 v[46:49], v[192:195], v[166:169], v[46:49]
	v_mfma_f32_16x16x32_bf16 v[42:45], v[192:195], v[170:173], v[42:45]
	v_mfma_f32_16x16x32_bf16 v[38:41], v[192:195], v[176:179], v[38:41]
	v_mfma_f32_16x16x32_bf16 v[34:37], v[192:195], v[180:183], v[34:37]
	v_mfma_f32_16x16x32_bf16 v[30:33], v[196:199], v[146:149], v[30:33]
	v_mfma_f32_16x16x32_bf16 v[26:29], v[196:199], v[152:155], v[26:29]
	v_mfma_f32_16x16x32_bf16 v[22:25], v[196:199], v[156:159], v[22:25]
	v_mfma_f32_16x16x32_bf16 v[18:21], v[196:199], v[162:165], v[18:21]
	v_mfma_f32_16x16x32_bf16 v[14:17], v[196:199], v[166:169], v[14:17]
	v_mfma_f32_16x16x32_bf16 v[10:13], v[196:199], v[170:173], v[10:13]
	v_mfma_f32_16x16x32_bf16 v[6:9], v[196:199], v[176:179], v[6:9]
	v_mfma_f32_16x16x32_bf16 v[2:5], v[196:199], v[180:183], v[2:5]
	s_setprio 0
	s_mov_b32 s42, s41
	s_add_i32 s41, s41, 0x6000
	s_cmp_eq_u32 s41, 0x12000
	s_cselect_b32 s41, 0, s41
	s_nop 0
	s_mov_b32 s4, 0x8000
	s_mov_b32 s5, 0
	s_mov_b32 s10, 0x10000
	s_mov_b32 s11, 0
	s_mov_b32 s45, 0x3fd744fd
	.p2align 3
	s_waitcnt lgkmcnt(0)
; DEVI unsigned pack2(float a, float b) { return __builtin_bit_cast(unsigned, __builtin_convertvector((f32x2_t){a, b}, bf16x2_t)); }
; DEVI float blo(unsigned u) { return __uint_as_float(u << 16); }
; DEVI float bhi(unsigned u) { return __uint_as_float(u & 0xffff0000u); }
; DEVI float siluf_(float x) { return x * __builtin_amdgcn_rcpf(1.f + __expf(-x)); }
;     ...
;     for (int nf = 0; nf < 4; nf++)
; #pragma unroll
;       for (int mf = 0; mf < 8; mf++)
;         acc[nf][mf] = __builtin_amdgcn_mfma_f32_16x16x32_bf16(wb[nf], xa[mf], acc[nf][mf], 0, 0, 0);
;   }
;     ...
; #pragma unroll
;   for (int mf = 0; mf < 8; mf++) {
;     const int row = m0 + wm * 128 + mf * 16 + r16;
;     if (EPI == EPI_SWIGLU) {
; #pragma unroll
;       for (int nf = 0; nf < 2; nf++) {
;         const int hcol = (n0 >> 1) + wn * 32 + nf * 16 + quad * 4;
;         f32x4 g = acc[nf][mf], u = acc[nf + 2][mf];
;         u32x2 pk;
;         pk[0] = pack2(siluf_(g[0]) * u[0], siluf_(g[1]) * u[1]);
;         pk[1] = pack2(siluf_(g[2]) * u[2], siluf_(g[3]) * u[3]);
;         *(u32x2*)(outb + (size_t)row * DFF + hcol) = pk;
;       }
;     } else {
; #pragma unroll
;       for (int nf = 0; nf < 4; nf++) {
;         const int col = n0 + wn * 64 + nf * 16 + quad * 4;
;         f32x4 a = acc[nf][mf];
;         if (EPI == EPI_RESID || EPI == EPI_RESID_ATOMIC) {
;           f32x4 x = a;
;           if (EPI == EPI_RESID || kpart == 0) {
;             const u32x2 xr = *(const u32x2*)((const u16*)(p.ws + WS_XB) + (size_t)row * 1024 + col);
;             x[0] += ALPHA * blo(xr[0]); x[1] += ALPHA * bhi(xr[0]); x[2] += ALPHA * blo(xr[1]); x[3] += ALPHA * bhi(xr[1]);
;           }
;           if (EPI == EPI_RESID) *(f32x4*)((float*)(p.ws + WS_XF) + (size_t)row * 1024 + col) = x;
;           else *(f32x4*)((float*)(p.ws + WS_SLAB) + ((size_t)kpart * 512 + (row - T_P)) * 1024 + col) = x;
	s_nop 0
	v_mfma_f32_16x16x32_bf16 v[126:129], v[232:235], v[200:203], v[126:129]
	v_mfma_f32_16x16x32_bf16 v[122:125], v[232:235], v[204:207], v[122:125]
	v_mfma_f32_16x16x32_bf16 v[118:121], v[232:235], v[208:211], v[118:121]
	v_mfma_f32_16x16x32_bf16 v[114:117], v[232:235], v[212:215], v[114:117]
	v_mfma_f32_16x16x32_bf16 v[110:113], v[232:235], v[216:219], v[110:113]
	global_load_dwordx4 v[146:149], v[138:139], off offset:0
	v_mfma_f32_16x16x32_bf16 v[106:109], v[232:235], v[220:223], v[106:109]
	v_mfma_f32_16x16x32_bf16 v[102:105], v[232:235], v[224:227], v[102:105]
	global_load_dwordx4 v[152:155], v[138:139], off offset:128
	v_mfma_f32_16x16x32_bf16 v[98:101], v[232:235], v[228:231], v[98:101]
	v_lshl_add_u64 v[138:139], v[138:139], 0, s[4:5]
	v_mfma_f32_16x16x32_bf16 v[94:97], v[236:239], v[200:203], v[94:97]
	global_load_dwordx4 v[156:159], v[138:139], off offset:0
	v_mfma_f32_16x16x32_bf16 v[90:93], v[236:239], v[204:207], v[90:93]
	v_mfma_f32_16x16x32_bf16 v[86:89], v[236:239], v[208:211], v[86:89]
	global_load_dwordx4 v[162:165], v[138:139], off offset:128
	v_mfma_f32_16x16x32_bf16 v[82:85], v[236:239], v[212:215], v[82:85]
	v_lshl_add_u64 v[138:139], v[138:139], 0, s[4:5]
	v_mfma_f32_16x16x32_bf16 v[78:81], v[236:239], v[216:219], v[78:81]
	global_load_dwordx4 v[166:169], v[138:139], off offset:0
	v_mfma_f32_16x16x32_bf16 v[74:77], v[236:239], v[220:223], v[74:77]
	v_mfma_f32_16x16x32_bf16 v[70:73], v[236:239], v[224:227], v[70:73]
	global_load_dwordx4 v[170:173], v[138:139], off offset:128
	v_mfma_f32_16x16x32_bf16 v[66:69], v[236:239], v[228:231], v[66:69]
	v_lshl_add_u64 v[138:139], v[138:139], 0, s[4:5]
	v_mfma_f32_16x16x32_bf16 v[62:65], v[240:243], v[200:203], v[62:65]
	global_load_dwordx4 v[176:179], v[138:139], off offset:0
	v_mfma_f32_16x16x32_bf16 v[58:61], v[240:243], v[204:207], v[58:61]
	v_mfma_f32_16x16x32_bf16 v[54:57], v[240:243], v[208:211], v[54:57]
	global_load_dwordx4 v[180:183], v[138:139], off offset:128
	v_mfma_f32_16x16x32_bf16 v[50:53], v[240:243], v[212:215], v[50:53]
	v_lshl_add_u64 v[138:139], v[138:139], 0, s[4:5]
	v_mfma_f32_16x16x32_bf16 v[46:49], v[240:243], v[216:219], v[46:49]
	global_load_dwordx4 v[184:187], v[138:139], off offset:0
	v_mfma_f32_16x16x32_bf16 v[42:45], v[240:243], v[220:223], v[42:45]
	v_mfma_f32_16x16x32_bf16 v[38:41], v[240:243], v[224:227], v[38:41]
	global_load_dwordx4 v[188:191], v[138:139], off offset:128
	v_mfma_f32_16x16x32_bf16 v[34:37], v[240:243], v[228:231], v[34:37]
	v_lshl_add_u64 v[138:139], v[138:139], 0, s[4:5]
	v_mfma_f32_16x16x32_bf16 v[30:33], v[244:247], v[200:203], v[30:33]
	global_load_dwordx4 v[192:195], v[138:139], off offset:0
	v_mfma_f32_16x16x32_bf16 v[26:29], v[244:247], v[204:207], v[26:29]
	v_mfma_f32_16x16x32_bf16 v[22:25], v[244:247], v[208:211], v[22:25]
	global_load_dwordx4 v[196:199], v[138:139], off offset:128
	v_mfma_f32_16x16x32_bf16 v[18:21], v[244:247], v[212:215], v[18:21]
	v_lshl_add_u64 v[138:139], v[138:139], 0, s[4:5]
	v_mfma_f32_16x16x32_bf16 v[14:17], v[244:247], v[216:219], v[14:17]
	v_mfma_f32_16x16x32_bf16 v[10:13], v[244:247], v[220:223], v[10:13]
	v_mfma_f32_16x16x32_bf16 v[6:9], v[244:247], v[224:227], v[6:9]
	v_mfma_f32_16x16x32_bf16 v[2:5], v[244:247], v[228:231], v[2:5]
	s_mov_b32 m0, s44
	global_load_dwordx4 v[200:203], v[138:139], off offset:0
	global_load_dwordx4 v[204:207], v[138:139], off offset:128
	v_lshl_add_u64 v[138:139], v[138:139], 0, s[4:5]
	global_load_dwordx4 v[208:211], v[138:139], off offset:0
	global_load_dwordx4 v[212:215], v[138:139], off offset:128
	v_lshl_add_u64 v[138:139], v[138:139], 0, s[4:5]
	s_nop 7
	v_and_b32_e32 v228, 1, v145
	v_cmp_ne_u32_e32 vcc, 0, v228
	v_mov_b32_e32 v229, 0xfffff040
	v_cndmask_b32_e32 v230, 0, v229, vcc
	v_ashrrev_i32_e32 v231, 31, v230
	v_lshl_add_u64 v[140:141], v[140:141], 0, v[230:231]
	v_add_co_u32_e32 v142, vcc, 0x1000, v140
	s_nop 0
	v_addc_co_u32_e32 v143, vcc, 0, v141, vcc
	v_cmp_ne_u32_e32 vcc, 0, v228
	s_waitcnt vmcnt(15)
	v_permlane16_swap_b32_e32 v146, v148
	v_permlane16_swap_b32_e32 v147, v149
	v_lshlrev_b32_e32 v216, 16, v146
	v_and_b32_e32 v146, 0xffff0000, v146
	v_lshlrev_b32_e32 v217, 16, v147
	v_and_b32_e32 v147, 0xffff0000, v147
	v_fmac_f32_e32 v126, s45, v216
	v_fmac_f32_e32 v127, s45, v146
	v_fmac_f32_e32 v128, s45, v217
	v_fmac_f32_e32 v129, s45, v147
	v_lshlrev_b32_e32 v216, 16, v148
	v_and_b32_e32 v148, 0xffff0000, v148
	v_lshlrev_b32_e32 v217, 16, v149
	v_and_b32_e32 v149, 0xffff0000, v149
	v_fmac_f32_e32 v94, s45, v216
	v_fmac_f32_e32 v95, s45, v148
	v_fmac_f32_e32 v96, s45, v217
	v_fmac_f32_e32 v97, s45, v149
	v_mov_b32_dpp v220, v94 quad_perm:[1,0,3,2] row_mask:0xf bank_mask:0xf
	v_mov_b32_dpp v221, v95 quad_perm:[1,0,3,2] row_mask:0xf bank_mask:0xf
	v_mov_b32_dpp v222, v96 quad_perm:[1,0,3,2] row_mask:0xf bank_mask:0xf
	v_mov_b32_dpp v223, v97 quad_perm:[1,0,3,2] row_mask:0xf bank_mask:0xf
	v_mov_b32_dpp v224, v126 quad_perm:[1,0,3,2] row_mask:0xf bank_mask:0xf
	v_mov_b32_dpp v225, v127 quad_perm:[1,0,3,2] row_mask:0xf bank_mask:0xf
	v_mov_b32_dpp v226, v128 quad_perm:[1,0,3,2] row_mask:0xf bank_mask:0xf
	v_mov_b32_dpp v227, v129 quad_perm:[1,0,3,2] row_mask:0xf bank_mask:0xf
	v_cndmask_b32_e32 v94, v224, v94, vcc
	v_cndmask_b32_e32 v95, v225, v95, vcc
	v_cndmask_b32_e32 v96, v226, v96, vcc
	v_cndmask_b32_e32 v97, v227, v97, vcc
	v_cndmask_b32_e32 v126, v126, v220, vcc
	v_cndmask_b32_e32 v127, v127, v221, vcc
	v_cndmask_b32_e32 v128, v128, v222, vcc
	v_cndmask_b32_e32 v129, v129, v223, vcc
	global_store_dwordx4 v[140:141], v[126:129], off
	global_store_dwordx4 v[142:143], v[94:97], off
	s_waitcnt vmcnt(16)
; DEVI unsigned pack2(float a, float b) { return __builtin_bit_cast(unsigned, __builtin_convertvector((f32x2_t){a, b}, bf16x2_t)); }
; DEVI float blo(unsigned u) { return __uint_as_float(u << 16); }
; DEVI float bhi(unsigned u) { return __uint_as_float(u & 0xffff0000u); }
; DEVI float siluf_(float x) { return x * __builtin_amdgcn_rcpf(1.f + __expf(-x)); }
;     ...
; #pragma unroll
;   for (int mf = 0; mf < 8; mf++) {
;     const int row = m0 + wm * 128 + mf * 16 + r16;
;     if (EPI == EPI_SWIGLU) {
; #pragma unroll
;       for (int nf = 0; nf < 2; nf++) {
;         const int hcol = (n0 >> 1) + wn * 32 + nf * 16 + quad * 4;
;         f32x4 g = acc[nf][mf], u = acc[nf + 2][mf];
;         u32x2 pk;
;         pk[0] = pack2(siluf_(g[0]) * u[0], siluf_(g[1]) * u[1]);
;         pk[1] = pack2(siluf_(g[2]) * u[2], siluf_(g[3]) * u[3]);
;         *(u32x2*)(outb + (size_t)row * DFF + hcol) = pk;
;       }
;     } else {
; #pragma unroll
;       for (int nf = 0; nf < 4; nf++) {
;         const int col = n0 + wn * 64 + nf * 16 + quad * 4;
;         f32x4 a = acc[nf][mf];
;         if (EPI == EPI_RESID || EPI == EPI_RESID_ATOMIC) {
;           f32x4 x = a;
;           if (EPI == EPI_RESID || kpart == 0) {
;             const u32x2 xr = *(const u32x2*)((const u16*)(p.ws + WS_XB) + (size_t)row * 1024 + col);
;             x[0] += ALPHA * blo(xr[0]); x[1] += ALPHA * bhi(xr[0]); x[2] += ALPHA * blo(xr[1]); x[3] += ALPHA * bhi(xr[1]);
;           }
;           if (EPI == EPI_RESID) *(f32x4*)((float*)(p.ws + WS_XF) + (size_t)row * 1024 + col) = x;
;           else *(f32x4*)((float*)(p.ws + WS_SLAB) + ((size_t)kpart * 512 + (row - T_P)) * 1024 + col) = x;
	v_permlane16_swap_b32_e32 v152, v154
	v_permlane16_swap_b32_e32 v153, v155
	v_lshlrev_b32_e32 v216, 16, v152
	v_and_b32_e32 v152, 0xffff0000, v152
	v_lshlrev_b32_e32 v217, 16, v153
	v_and_b32_e32 v153, 0xffff0000, v153
	v_fmac_f32_e32 v62, s45, v216
	v_fmac_f32_e32 v63, s45, v152
	v_fmac_f32_e32 v64, s45, v217
	v_fmac_f32_e32 v65, s45, v153
	v_lshlrev_b32_e32 v216, 16, v154
	v_and_b32_e32 v154, 0xffff0000, v154
	v_lshlrev_b32_e32 v217, 16, v155
	v_and_b32_e32 v155, 0xffff0000, v155
	v_fmac_f32_e32 v30, s45, v216
	v_fmac_f32_e32 v31, s45, v154
	v_fmac_f32_e32 v32, s45, v217
	v_fmac_f32_e32 v33, s45, v155
	v_mov_b32_dpp v220, v30 quad_perm:[1,0,3,2] row_mask:0xf bank_mask:0xf
	v_mov_b32_dpp v221, v31 quad_perm:[1,0,3,2] row_mask:0xf bank_mask:0xf
	v_mov_b32_dpp v222, v32 quad_perm:[1,0,3,2] row_mask:0xf bank_mask:0xf
	v_mov_b32_dpp v223, v33 quad_perm:[1,0,3,2] row_mask:0xf bank_mask:0xf
	v_mov_b32_dpp v224, v62 quad_perm:[1,0,3,2] row_mask:0xf bank_mask:0xf
	v_mov_b32_dpp v225, v63 quad_perm:[1,0,3,2] row_mask:0xf bank_mask:0xf
	v_mov_b32_dpp v226, v64 quad_perm:[1,0,3,2] row_mask:0xf bank_mask:0xf
	v_mov_b32_dpp v227, v65 quad_perm:[1,0,3,2] row_mask:0xf bank_mask:0xf
	v_cndmask_b32_e32 v30, v224, v30, vcc
	v_cndmask_b32_e32 v31, v225, v31, vcc
	v_cndmask_b32_e32 v32, v226, v32, vcc
	v_cndmask_b32_e32 v33, v227, v33, vcc
	v_cndmask_b32_e32 v62, v62, v220, vcc
	v_cndmask_b32_e32 v63, v63, v221, vcc
	v_cndmask_b32_e32 v64, v64, v222, vcc
	v_cndmask_b32_e32 v65, v65, v223, vcc
	global_store_dwordx4 v[140:141], v[62:65], off offset:128
	global_store_dwordx4 v[142:143], v[30:33], off offset:128
	v_lshl_add_u64 v[140:141], v[140:141], 0, s[10:11]
	v_lshl_add_u64 v[142:143], v[142:143], 0, s[10:11]
	s_waitcnt vmcnt(17)
	v_permlane16_swap_b32_e32 v156, v158
	v_permlane16_swap_b32_e32 v157, v159
	v_lshlrev_b32_e32 v216, 16, v156
	v_and_b32_e32 v156, 0xffff0000, v156
	v_lshlrev_b32_e32 v217, 16, v157
	v_and_b32_e32 v157, 0xffff0000, v157
	v_fmac_f32_e32 v122, s45, v216
	v_fmac_f32_e32 v123, s45, v156
	v_fmac_f32_e32 v124, s45, v217
	v_fmac_f32_e32 v125, s45, v157
	v_lshlrev_b32_e32 v216, 16, v158
	v_and_b32_e32 v158, 0xffff0000, v158
	v_lshlrev_b32_e32 v217, 16, v159
	v_and_b32_e32 v159, 0xffff0000, v159
	v_fmac_f32_e32 v90, s45, v216
	v_fmac_f32_e32 v91, s45, v158
	v_fmac_f32_e32 v92, s45, v217
	v_fmac_f32_e32 v93, s45, v159
	v_mov_b32_dpp v220, v90 quad_perm:[1,0,3,2] row_mask:0xf bank_mask:0xf
	v_mov_b32_dpp v221, v91 quad_perm:[1,0,3,2] row_mask:0xf bank_mask:0xf
	v_mov_b32_dpp v222, v92 quad_perm:[1,0,3,2] row_mask:0xf bank_mask:0xf
	v_mov_b32_dpp v223, v93 quad_perm:[1,0,3,2] row_mask:0xf bank_mask:0xf
	v_mov_b32_dpp v224, v122 quad_perm:[1,0,3,2] row_mask:0xf bank_mask:0xf
	v_mov_b32_dpp v225, v123 quad_perm:[1,0,3,2] row_mask:0xf bank_mask:0xf
	v_mov_b32_dpp v226, v124 quad_perm:[1,0,3,2] row_mask:0xf bank_mask:0xf
	v_mov_b32_dpp v227, v125 quad_perm:[1,0,3,2] row_mask:0xf bank_mask:0xf
	v_cndmask_b32_e32 v90, v224, v90, vcc
	v_cndmask_b32_e32 v91, v225, v91, vcc
	v_cndmask_b32_e32 v92, v226, v92, vcc
	v_cndmask_b32_e32 v93, v227, v93, vcc
	v_cndmask_b32_e32 v122, v122, v220, vcc
	v_cndmask_b32_e32 v123, v123, v221, vcc
	v_cndmask_b32_e32 v124, v124, v222, vcc
	v_cndmask_b32_e32 v125, v125, v223, vcc
	global_store_dwordx4 v[140:141], v[122:125], off
	global_store_dwordx4 v[142:143], v[90:93], off
	s_waitcnt vmcnt(18)
	v_permlane16_swap_b32_e32 v162, v164
	v_permlane16_swap_b32_e32 v163, v165
	v_lshlrev_b32_e32 v216, 16, v162
	v_and_b32_e32 v162, 0xffff0000, v162
	v_lshlrev_b32_e32 v217, 16, v163
	v_and_b32_e32 v163, 0xffff0000, v163
	v_fmac_f32_e32 v58, s45, v216
	v_fmac_f32_e32 v59, s45, v162
	v_fmac_f32_e32 v60, s45, v217
	v_fmac_f32_e32 v61, s45, v163
	v_lshlrev_b32_e32 v216, 16, v164
	v_and_b32_e32 v164, 0xffff0000, v164
	v_lshlrev_b32_e32 v217, 16, v165
	v_and_b32_e32 v165, 0xffff0000, v165
	v_fmac_f32_e32 v26, s45, v216
	v_fmac_f32_e32 v27, s45, v164
	v_fmac_f32_e32 v28, s45, v217
	v_fmac_f32_e32 v29, s45, v165
	v_mov_b32_dpp v220, v26 quad_perm:[1,0,3,2] row_mask:0xf bank_mask:0xf
	v_mov_b32_dpp v221, v27 quad_perm:[1,0,3,2] row_mask:0xf bank_mask:0xf
	v_mov_b32_dpp v222, v28 quad_perm:[1,0,3,2] row_mask:0xf bank_mask:0xf
	v_mov_b32_dpp v223, v29 quad_perm:[1,0,3,2] row_mask:0xf bank_mask:0xf
	v_mov_b32_dpp v224, v58 quad_perm:[1,0,3,2] row_mask:0xf bank_mask:0xf
	v_mov_b32_dpp v225, v59 quad_perm:[1,0,3,2] row_mask:0xf bank_mask:0xf
	v_mov_b32_dpp v226, v60 quad_perm:[1,0,3,2] row_mask:0xf bank_mask:0xf
	v_mov_b32_dpp v227, v61 quad_perm:[1,0,3,2] row_mask:0xf bank_mask:0xf
	v_cndmask_b32_e32 v26, v224, v26, vcc
	v_cndmask_b32_e32 v27, v225, v27, vcc
	v_cndmask_b32_e32 v28, v226, v28, vcc
	v_cndmask_b32_e32 v29, v227, v29, vcc
	v_cndmask_b32_e32 v58, v58, v220, vcc
	v_cndmask_b32_e32 v59, v59, v221, vcc
	v_cndmask_b32_e32 v60, v60, v222, vcc
	v_cndmask_b32_e32 v61, v61, v223, vcc
	global_store_dwordx4 v[140:141], v[58:61], off offset:128
	global_store_dwordx4 v[142:143], v[26:29], off offset:128
	v_lshl_add_u64 v[140:141], v[140:141], 0, s[10:11]
	v_lshl_add_u64 v[142:143], v[142:143], 0, s[10:11]
	s_waitcnt vmcnt(19)
; DEVI unsigned pack2(float a, float b) { return __builtin_bit_cast(unsigned, __builtin_convertvector((f32x2_t){a, b}, bf16x2_t)); }
; DEVI float blo(unsigned u) { return __uint_as_float(u << 16); }
; DEVI float bhi(unsigned u) { return __uint_as_float(u & 0xffff0000u); }
; DEVI float siluf_(float x) { return x * __builtin_amdgcn_rcpf(1.f + __expf(-x)); }
;     ...
; #pragma unroll
;   for (int mf = 0; mf < 8; mf++) {
;     const int row = m0 + wm * 128 + mf * 16 + r16;
;     if (EPI == EPI_SWIGLU) {
; #pragma unroll
;       for (int nf = 0; nf < 2; nf++) {
;         const int hcol = (n0 >> 1) + wn * 32 + nf * 16 + quad * 4;
;         f32x4 g = acc[nf][mf], u = acc[nf + 2][mf];
;         u32x2 pk;
;         pk[0] = pack2(siluf_(g[0]) * u[0], siluf_(g[1]) * u[1]);
;         pk[1] = pack2(siluf_(g[2]) * u[2], siluf_(g[3]) * u[3]);
;         *(u32x2*)(outb + (size_t)row * DFF + hcol) = pk;
;       }
;     } else {
; #pragma unroll
;       for (int nf = 0; nf < 4; nf++) {
;         const int col = n0 + wn * 64 + nf * 16 + quad * 4;
;         f32x4 a = acc[nf][mf];
;         if (EPI == EPI_RESID || EPI == EPI_RESID_ATOMIC) {
;           f32x4 x = a;
;           if (EPI == EPI_RESID || kpart == 0) {
;             const u32x2 xr = *(const u32x2*)((const u16*)(p.ws + WS_XB) + (size_t)row * 1024 + col);
;             x[0] += ALPHA * blo(xr[0]); x[1] += ALPHA * bhi(xr[0]); x[2] += ALPHA * blo(xr[1]); x[3] += ALPHA * bhi(xr[1]);
;           }
;           if (EPI == EPI_RESID) *(f32x4*)((float*)(p.ws + WS_XF) + (size_t)row * 1024 + col) = x;
;           else *(f32x4*)((float*)(p.ws + WS_SLAB) + ((size_t)kpart * 512 + (row - T_P)) * 1024 + col) = x;
	v_permlane16_swap_b32_e32 v166, v168
	v_permlane16_swap_b32_e32 v167, v169
	v_lshlrev_b32_e32 v216, 16, v166
	v_and_b32_e32 v166, 0xffff0000, v166
	v_lshlrev_b32_e32 v217, 16, v167
	v_and_b32_e32 v167, 0xffff0000, v167
	v_fmac_f32_e32 v118, s45, v216
	v_fmac_f32_e32 v119, s45, v166
	v_fmac_f32_e32 v120, s45, v217
	v_fmac_f32_e32 v121, s45, v167
	v_lshlrev_b32_e32 v216, 16, v168
	v_and_b32_e32 v168, 0xffff0000, v168
	v_lshlrev_b32_e32 v217, 16, v169
	v_and_b32_e32 v169, 0xffff0000, v169
	v_fmac_f32_e32 v86, s45, v216
	v_fmac_f32_e32 v87, s45, v168
	v_fmac_f32_e32 v88, s45, v217
	v_fmac_f32_e32 v89, s45, v169
	v_mov_b32_dpp v220, v86 quad_perm:[1,0,3,2] row_mask:0xf bank_mask:0xf
	v_mov_b32_dpp v221, v87 quad_perm:[1,0,3,2] row_mask:0xf bank_mask:0xf
	v_mov_b32_dpp v222, v88 quad_perm:[1,0,3,2] row_mask:0xf bank_mask:0xf
	v_mov_b32_dpp v223, v89 quad_perm:[1,0,3,2] row_mask:0xf bank_mask:0xf
	v_mov_b32_dpp v224, v118 quad_perm:[1,0,3,2] row_mask:0xf bank_mask:0xf
	v_mov_b32_dpp v225, v119 quad_perm:[1,0,3,2] row_mask:0xf bank_mask:0xf
	v_mov_b32_dpp v226, v120 quad_perm:[1,0,3,2] row_mask:0xf bank_mask:0xf
	v_mov_b32_dpp v227, v121 quad_perm:[1,0,3,2] row_mask:0xf bank_mask:0xf
	v_cndmask_b32_e32 v86, v224, v86, vcc
	v_cndmask_b32_e32 v87, v225, v87, vcc
	v_cndmask_b32_e32 v88, v226, v88, vcc
	v_cndmask_b32_e32 v89, v227, v89, vcc
	v_cndmask_b32_e32 v118, v118, v220, vcc
	v_cndmask_b32_e32 v119, v119, v221, vcc
	v_cndmask_b32_e32 v120, v120, v222, vcc
	v_cndmask_b32_e32 v121, v121, v223, vcc
	global_store_dwordx4 v[140:141], v[118:121], off
	global_store_dwordx4 v[142:143], v[86:89], off
	s_waitcnt vmcnt(20)
	v_permlane16_swap_b32_e32 v170, v172
	v_permlane16_swap_b32_e32 v171, v173
	v_lshlrev_b32_e32 v216, 16, v170
	v_and_b32_e32 v170, 0xffff0000, v170
	v_lshlrev_b32_e32 v217, 16, v171
	v_and_b32_e32 v171, 0xffff0000, v171
	v_fmac_f32_e32 v54, s45, v216
	v_fmac_f32_e32 v55, s45, v170
	v_fmac_f32_e32 v56, s45, v217
	v_fmac_f32_e32 v57, s45, v171
	v_lshlrev_b32_e32 v216, 16, v172
	v_and_b32_e32 v172, 0xffff0000, v172
	v_lshlrev_b32_e32 v217, 16, v173
	v_and_b32_e32 v173, 0xffff0000, v173
	v_fmac_f32_e32 v22, s45, v216
	v_fmac_f32_e32 v23, s45, v172
	v_fmac_f32_e32 v24, s45, v217
	v_fmac_f32_e32 v25, s45, v173
	v_mov_b32_dpp v220, v22 quad_perm:[1,0,3,2] row_mask:0xf bank_mask:0xf
	v_mov_b32_dpp v221, v23 quad_perm:[1,0,3,2] row_mask:0xf bank_mask:0xf
	v_mov_b32_dpp v222, v24 quad_perm:[1,0,3,2] row_mask:0xf bank_mask:0xf
	v_mov_b32_dpp v223, v25 quad_perm:[1,0,3,2] row_mask:0xf bank_mask:0xf
	v_mov_b32_dpp v224, v54 quad_perm:[1,0,3,2] row_mask:0xf bank_mask:0xf
	v_mov_b32_dpp v225, v55 quad_perm:[1,0,3,2] row_mask:0xf bank_mask:0xf
	v_mov_b32_dpp v226, v56 quad_perm:[1,0,3,2] row_mask:0xf bank_mask:0xf
	v_mov_b32_dpp v227, v57 quad_perm:[1,0,3,2] row_mask:0xf bank_mask:0xf
	v_cndmask_b32_e32 v22, v224, v22, vcc
	v_cndmask_b32_e32 v23, v225, v23, vcc
	v_cndmask_b32_e32 v24, v226, v24, vcc
	v_cndmask_b32_e32 v25, v227, v25, vcc
	v_cndmask_b32_e32 v54, v54, v220, vcc
	v_cndmask_b32_e32 v55, v55, v221, vcc
	v_cndmask_b32_e32 v56, v56, v222, vcc
	v_cndmask_b32_e32 v57, v57, v223, vcc
	global_store_dwordx4 v[140:141], v[54:57], off offset:128
	global_store_dwordx4 v[142:143], v[22:25], off offset:128
	v_lshl_add_u64 v[140:141], v[140:141], 0, s[10:11]
	v_lshl_add_u64 v[142:143], v[142:143], 0, s[10:11]
	s_waitcnt vmcnt(21)
	v_permlane16_swap_b32_e32 v176, v178
	v_permlane16_swap_b32_e32 v177, v179
	v_lshlrev_b32_e32 v216, 16, v176
	v_and_b32_e32 v176, 0xffff0000, v176
	v_lshlrev_b32_e32 v217, 16, v177
	v_and_b32_e32 v177, 0xffff0000, v177
	v_fmac_f32_e32 v114, s45, v216
	v_fmac_f32_e32 v115, s45, v176
	v_fmac_f32_e32 v116, s45, v217
	v_fmac_f32_e32 v117, s45, v177
	v_lshlrev_b32_e32 v216, 16, v178
	v_and_b32_e32 v178, 0xffff0000, v178
	v_lshlrev_b32_e32 v217, 16, v179
	v_and_b32_e32 v179, 0xffff0000, v179
	v_fmac_f32_e32 v82, s45, v216
	v_fmac_f32_e32 v83, s45, v178
	v_fmac_f32_e32 v84, s45, v217
	v_fmac_f32_e32 v85, s45, v179
	v_mov_b32_dpp v220, v82 quad_perm:[1,0,3,2] row_mask:0xf bank_mask:0xf
	v_mov_b32_dpp v221, v83 quad_perm:[1,0,3,2] row_mask:0xf bank_mask:0xf
	v_mov_b32_dpp v222, v84 quad_perm:[1,0,3,2] row_mask:0xf bank_mask:0xf
	v_mov_b32_dpp v223, v85 quad_perm:[1,0,3,2] row_mask:0xf bank_mask:0xf
	v_mov_b32_dpp v224, v114 quad_perm:[1,0,3,2] row_mask:0xf bank_mask:0xf
	v_mov_b32_dpp v225, v115 quad_perm:[1,0,3,2] row_mask:0xf bank_mask:0xf
	v_mov_b32_dpp v226, v116 quad_perm:[1,0,3,2] row_mask:0xf bank_mask:0xf
	v_mov_b32_dpp v227, v117 quad_perm:[1,0,3,2] row_mask:0xf bank_mask:0xf
	v_cndmask_b32_e32 v82, v224, v82, vcc
	v_cndmask_b32_e32 v83, v225, v83, vcc
	v_cndmask_b32_e32 v84, v226, v84, vcc
	v_cndmask_b32_e32 v85, v227, v85, vcc
	v_cndmask_b32_e32 v114, v114, v220, vcc
	v_cndmask_b32_e32 v115, v115, v221, vcc
	v_cndmask_b32_e32 v116, v116, v222, vcc
	v_cndmask_b32_e32 v117, v117, v223, vcc
	global_store_dwordx4 v[140:141], v[114:117], off
	global_store_dwordx4 v[142:143], v[82:85], off
	s_waitcnt vmcnt(22)
; DEVI unsigned pack2(float a, float b) { return __builtin_bit_cast(unsigned, __builtin_convertvector((f32x2_t){a, b}, bf16x2_t)); }
; DEVI float blo(unsigned u) { return __uint_as_float(u << 16); }
; DEVI float bhi(unsigned u) { return __uint_as_float(u & 0xffff0000u); }
; DEVI float siluf_(float x) { return x * __builtin_amdgcn_rcpf(1.f + __expf(-x)); }
;     ...
; #pragma unroll
;   for (int mf = 0; mf < 8; mf++) {
;     const int row = m0 + wm * 128 + mf * 16 + r16;
;     if (EPI == EPI_SWIGLU) {
; #pragma unroll
;       for (int nf = 0; nf < 2; nf++) {
;         const int hcol = (n0 >> 1) + wn * 32 + nf * 16 + quad * 4;
;         f32x4 g = acc[nf][mf], u = acc[nf + 2][mf];
;         u32x2 pk;
;         pk[0] = pack2(siluf_(g[0]) * u[0], siluf_(g[1]) * u[1]);
;         pk[1] = pack2(siluf_(g[2]) * u[2], siluf_(g[3]) * u[3]);
;         *(u32x2*)(outb + (size_t)row * DFF + hcol) = pk;
;       }
;     } else {
; #pragma unroll
;       for (int nf = 0; nf < 4; nf++) {
;         const int col = n0 + wn * 64 + nf * 16 + quad * 4;
;         f32x4 a = acc[nf][mf];
;         if (EPI == EPI_RESID || EPI == EPI_RESID_ATOMIC) {
;           f32x4 x = a;
;           if (EPI == EPI_RESID || kpart == 0) {
;             const u32x2 xr = *(const u32x2*)((const u16*)(p.ws + WS_XB) + (size_t)row * 1024 + col);
;             x[0] += ALPHA * blo(xr[0]); x[1] += ALPHA * bhi(xr[0]); x[2] += ALPHA * blo(xr[1]); x[3] += ALPHA * bhi(xr[1]);
;           }
;           if (EPI == EPI_RESID) *(f32x4*)((float*)(p.ws + WS_XF) + (size_t)row * 1024 + col) = x;
;           else *(f32x4*)((float*)(p.ws + WS_SLAB) + ((size_t)kpart * 512 + (row - T_P)) * 1024 + col) = x;
	v_permlane16_swap_b32_e32 v180, v182
	v_permlane16_swap_b32_e32 v181, v183
	v_lshlrev_b32_e32 v216, 16, v180
	v_and_b32_e32 v180, 0xffff0000, v180
	v_lshlrev_b32_e32 v217, 16, v181
	v_and_b32_e32 v181, 0xffff0000, v181
	v_fmac_f32_e32 v50, s45, v216
	v_fmac_f32_e32 v51, s45, v180
	v_fmac_f32_e32 v52, s45, v217
	v_fmac_f32_e32 v53, s45, v181
	v_lshlrev_b32_e32 v216, 16, v182
	v_and_b32_e32 v182, 0xffff0000, v182
	v_lshlrev_b32_e32 v217, 16, v183
	v_and_b32_e32 v183, 0xffff0000, v183
	v_fmac_f32_e32 v18, s45, v216
	v_fmac_f32_e32 v19, s45, v182
	v_fmac_f32_e32 v20, s45, v217
	v_fmac_f32_e32 v21, s45, v183
	v_mov_b32_dpp v220, v18 quad_perm:[1,0,3,2] row_mask:0xf bank_mask:0xf
	v_mov_b32_dpp v221, v19 quad_perm:[1,0,3,2] row_mask:0xf bank_mask:0xf
	v_mov_b32_dpp v222, v20 quad_perm:[1,0,3,2] row_mask:0xf bank_mask:0xf
	v_mov_b32_dpp v223, v21 quad_perm:[1,0,3,2] row_mask:0xf bank_mask:0xf
	v_mov_b32_dpp v224, v50 quad_perm:[1,0,3,2] row_mask:0xf bank_mask:0xf
	v_mov_b32_dpp v225, v51 quad_perm:[1,0,3,2] row_mask:0xf bank_mask:0xf
	v_mov_b32_dpp v226, v52 quad_perm:[1,0,3,2] row_mask:0xf bank_mask:0xf
	v_mov_b32_dpp v227, v53 quad_perm:[1,0,3,2] row_mask:0xf bank_mask:0xf
	v_cndmask_b32_e32 v18, v224, v18, vcc
	v_cndmask_b32_e32 v19, v225, v19, vcc
	v_cndmask_b32_e32 v20, v226, v20, vcc
	v_cndmask_b32_e32 v21, v227, v21, vcc
	v_cndmask_b32_e32 v50, v50, v220, vcc
	v_cndmask_b32_e32 v51, v51, v221, vcc
	v_cndmask_b32_e32 v52, v52, v222, vcc
	v_cndmask_b32_e32 v53, v53, v223, vcc
	global_store_dwordx4 v[140:141], v[50:53], off offset:128
	global_store_dwordx4 v[142:143], v[18:21], off offset:128
	v_lshl_add_u64 v[140:141], v[140:141], 0, s[10:11]
	v_lshl_add_u64 v[142:143], v[142:143], 0, s[10:11]
	s_waitcnt vmcnt(23)
	v_permlane16_swap_b32_e32 v184, v186
	v_permlane16_swap_b32_e32 v185, v187
	v_lshlrev_b32_e32 v216, 16, v184
	v_and_b32_e32 v184, 0xffff0000, v184
	v_lshlrev_b32_e32 v217, 16, v185
	v_and_b32_e32 v185, 0xffff0000, v185
	v_fmac_f32_e32 v110, s45, v216
	v_fmac_f32_e32 v111, s45, v184
	v_fmac_f32_e32 v112, s45, v217
	v_fmac_f32_e32 v113, s45, v185
	v_lshlrev_b32_e32 v216, 16, v186
	v_and_b32_e32 v186, 0xffff0000, v186
	v_lshlrev_b32_e32 v217, 16, v187
	v_and_b32_e32 v187, 0xffff0000, v187
	v_fmac_f32_e32 v78, s45, v216
	v_fmac_f32_e32 v79, s45, v186
	v_fmac_f32_e32 v80, s45, v217
	v_fmac_f32_e32 v81, s45, v187
	v_mov_b32_dpp v220, v78 quad_perm:[1,0,3,2] row_mask:0xf bank_mask:0xf
	v_mov_b32_dpp v221, v79 quad_perm:[1,0,3,2] row_mask:0xf bank_mask:0xf
	v_mov_b32_dpp v222, v80 quad_perm:[1,0,3,2] row_mask:0xf bank_mask:0xf
	v_mov_b32_dpp v223, v81 quad_perm:[1,0,3,2] row_mask:0xf bank_mask:0xf
	v_mov_b32_dpp v224, v110 quad_perm:[1,0,3,2] row_mask:0xf bank_mask:0xf
	v_mov_b32_dpp v225, v111 quad_perm:[1,0,3,2] row_mask:0xf bank_mask:0xf
	v_mov_b32_dpp v226, v112 quad_perm:[1,0,3,2] row_mask:0xf bank_mask:0xf
	v_mov_b32_dpp v227, v113 quad_perm:[1,0,3,2] row_mask:0xf bank_mask:0xf
	v_cndmask_b32_e32 v78, v224, v78, vcc
	v_cndmask_b32_e32 v79, v225, v79, vcc
	v_cndmask_b32_e32 v80, v226, v80, vcc
	v_cndmask_b32_e32 v81, v227, v81, vcc
	v_cndmask_b32_e32 v110, v110, v220, vcc
	v_cndmask_b32_e32 v111, v111, v221, vcc
	v_cndmask_b32_e32 v112, v112, v222, vcc
	v_cndmask_b32_e32 v113, v113, v223, vcc
	global_store_dwordx4 v[140:141], v[110:113], off
	global_store_dwordx4 v[142:143], v[78:81], off
	s_waitcnt vmcnt(24)
	v_permlane16_swap_b32_e32 v188, v190
	v_permlane16_swap_b32_e32 v189, v191
	v_lshlrev_b32_e32 v216, 16, v188
	v_and_b32_e32 v188, 0xffff0000, v188
	v_lshlrev_b32_e32 v217, 16, v189
	v_and_b32_e32 v189, 0xffff0000, v189
	v_fmac_f32_e32 v46, s45, v216
	v_fmac_f32_e32 v47, s45, v188
	v_fmac_f32_e32 v48, s45, v217
	v_fmac_f32_e32 v49, s45, v189
	v_lshlrev_b32_e32 v216, 16, v190
	v_and_b32_e32 v190, 0xffff0000, v190
	v_lshlrev_b32_e32 v217, 16, v191
	v_and_b32_e32 v191, 0xffff0000, v191
	v_fmac_f32_e32 v14, s45, v216
	v_fmac_f32_e32 v15, s45, v190
	v_fmac_f32_e32 v16, s45, v217
	v_fmac_f32_e32 v17, s45, v191
	v_mov_b32_dpp v220, v14 quad_perm:[1,0,3,2] row_mask:0xf bank_mask:0xf
	v_mov_b32_dpp v221, v15 quad_perm:[1,0,3,2] row_mask:0xf bank_mask:0xf
	v_mov_b32_dpp v222, v16 quad_perm:[1,0,3,2] row_mask:0xf bank_mask:0xf
	v_mov_b32_dpp v223, v17 quad_perm:[1,0,3,2] row_mask:0xf bank_mask:0xf
	v_mov_b32_dpp v224, v46 quad_perm:[1,0,3,2] row_mask:0xf bank_mask:0xf
	v_mov_b32_dpp v225, v47 quad_perm:[1,0,3,2] row_mask:0xf bank_mask:0xf
	v_mov_b32_dpp v226, v48 quad_perm:[1,0,3,2] row_mask:0xf bank_mask:0xf
	v_mov_b32_dpp v227, v49 quad_perm:[1,0,3,2] row_mask:0xf bank_mask:0xf
	v_cndmask_b32_e32 v14, v224, v14, vcc
	v_cndmask_b32_e32 v15, v225, v15, vcc
	v_cndmask_b32_e32 v16, v226, v16, vcc
	v_cndmask_b32_e32 v17, v227, v17, vcc
	v_cndmask_b32_e32 v46, v46, v220, vcc
	v_cndmask_b32_e32 v47, v47, v221, vcc
	v_cndmask_b32_e32 v48, v48, v222, vcc
	v_cndmask_b32_e32 v49, v49, v223, vcc
	global_store_dwordx4 v[140:141], v[46:49], off offset:128
	global_store_dwordx4 v[142:143], v[14:17], off offset:128
	v_lshl_add_u64 v[140:141], v[140:141], 0, s[10:11]
	v_lshl_add_u64 v[142:143], v[142:143], 0, s[10:11]
	s_waitcnt vmcnt(25)
; DEVI unsigned pack2(float a, float b) { return __builtin_bit_cast(unsigned, __builtin_convertvector((f32x2_t){a, b}, bf16x2_t)); }
; DEVI float blo(unsigned u) { return __uint_as_float(u << 16); }
; DEVI float bhi(unsigned u) { return __uint_as_float(u & 0xffff0000u); }
; DEVI float siluf_(float x) { return x * __builtin_amdgcn_rcpf(1.f + __expf(-x)); }
;     ...
; #pragma unroll
;   for (int mf = 0; mf < 8; mf++) {
;     const int row = m0 + wm * 128 + mf * 16 + r16;
;     if (EPI == EPI_SWIGLU) {
; #pragma unroll
;       for (int nf = 0; nf < 2; nf++) {
;         const int hcol = (n0 >> 1) + wn * 32 + nf * 16 + quad * 4;
;         f32x4 g = acc[nf][mf], u = acc[nf + 2][mf];
;         u32x2 pk;
;         pk[0] = pack2(siluf_(g[0]) * u[0], siluf_(g[1]) * u[1]);
;         pk[1] = pack2(siluf_(g[2]) * u[2], siluf_(g[3]) * u[3]);
;         *(u32x2*)(outb + (size_t)row * DFF + hcol) = pk;
;       }
;     } else {
; #pragma unroll
;       for (int nf = 0; nf < 4; nf++) {
;         const int col = n0 + wn * 64 + nf * 16 + quad * 4;
;         f32x4 a = acc[nf][mf];
;         if (EPI == EPI_RESID || EPI == EPI_RESID_ATOMIC) {
;           f32x4 x = a;
;           if (EPI == EPI_RESID || kpart == 0) {
;             const u32x2 xr = *(const u32x2*)((const u16*)(p.ws + WS_XB) + (size_t)row * 1024 + col);
;             x[0] += ALPHA * blo(xr[0]); x[1] += ALPHA * bhi(xr[0]); x[2] += ALPHA * blo(xr[1]); x[3] += ALPHA * bhi(xr[1]);
;           }
;           if (EPI == EPI_RESID) *(f32x4*)((float*)(p.ws + WS_XF) + (size_t)row * 1024 + col) = x;
;           else *(f32x4*)((float*)(p.ws + WS_SLAB) + ((size_t)kpart * 512 + (row - T_P)) * 1024 + col) = x;
	v_permlane16_swap_b32_e32 v192, v194
	v_permlane16_swap_b32_e32 v193, v195
	v_lshlrev_b32_e32 v216, 16, v192
	v_and_b32_e32 v192, 0xffff0000, v192
	v_lshlrev_b32_e32 v217, 16, v193
	v_and_b32_e32 v193, 0xffff0000, v193
	v_fmac_f32_e32 v106, s45, v216
	v_fmac_f32_e32 v107, s45, v192
	v_fmac_f32_e32 v108, s45, v217
	v_fmac_f32_e32 v109, s45, v193
	v_lshlrev_b32_e32 v216, 16, v194
	v_and_b32_e32 v194, 0xffff0000, v194
	v_lshlrev_b32_e32 v217, 16, v195
	v_and_b32_e32 v195, 0xffff0000, v195
	v_fmac_f32_e32 v74, s45, v216
	v_fmac_f32_e32 v75, s45, v194
	v_fmac_f32_e32 v76, s45, v217
	v_fmac_f32_e32 v77, s45, v195
	v_mov_b32_dpp v220, v74 quad_perm:[1,0,3,2] row_mask:0xf bank_mask:0xf
	v_mov_b32_dpp v221, v75 quad_perm:[1,0,3,2] row_mask:0xf bank_mask:0xf
	v_mov_b32_dpp v222, v76 quad_perm:[1,0,3,2] row_mask:0xf bank_mask:0xf
	v_mov_b32_dpp v223, v77 quad_perm:[1,0,3,2] row_mask:0xf bank_mask:0xf
	v_mov_b32_dpp v224, v106 quad_perm:[1,0,3,2] row_mask:0xf bank_mask:0xf
	v_mov_b32_dpp v225, v107 quad_perm:[1,0,3,2] row_mask:0xf bank_mask:0xf
	v_mov_b32_dpp v226, v108 quad_perm:[1,0,3,2] row_mask:0xf bank_mask:0xf
	v_mov_b32_dpp v227, v109 quad_perm:[1,0,3,2] row_mask:0xf bank_mask:0xf
	v_cndmask_b32_e32 v74, v224, v74, vcc
	v_cndmask_b32_e32 v75, v225, v75, vcc
	v_cndmask_b32_e32 v76, v226, v76, vcc
	v_cndmask_b32_e32 v77, v227, v77, vcc
	v_cndmask_b32_e32 v106, v106, v220, vcc
	v_cndmask_b32_e32 v107, v107, v221, vcc
	v_cndmask_b32_e32 v108, v108, v222, vcc
	v_cndmask_b32_e32 v109, v109, v223, vcc
	global_store_dwordx4 v[140:141], v[106:109], off
	global_store_dwordx4 v[142:143], v[74:77], off
	s_waitcnt vmcnt(26)
	v_permlane16_swap_b32_e32 v196, v198
	v_permlane16_swap_b32_e32 v197, v199
	v_lshlrev_b32_e32 v216, 16, v196
	v_and_b32_e32 v196, 0xffff0000, v196
	v_lshlrev_b32_e32 v217, 16, v197
	v_and_b32_e32 v197, 0xffff0000, v197
	v_fmac_f32_e32 v42, s45, v216
	v_fmac_f32_e32 v43, s45, v196
	v_fmac_f32_e32 v44, s45, v217
	v_fmac_f32_e32 v45, s45, v197
	v_lshlrev_b32_e32 v216, 16, v198
	v_and_b32_e32 v198, 0xffff0000, v198
	v_lshlrev_b32_e32 v217, 16, v199
	v_and_b32_e32 v199, 0xffff0000, v199
	v_fmac_f32_e32 v10, s45, v216
	v_fmac_f32_e32 v11, s45, v198
	v_fmac_f32_e32 v12, s45, v217
	v_fmac_f32_e32 v13, s45, v199
	v_mov_b32_dpp v220, v10 quad_perm:[1,0,3,2] row_mask:0xf bank_mask:0xf
	v_mov_b32_dpp v221, v11 quad_perm:[1,0,3,2] row_mask:0xf bank_mask:0xf
	v_mov_b32_dpp v222, v12 quad_perm:[1,0,3,2] row_mask:0xf bank_mask:0xf
	v_mov_b32_dpp v223, v13 quad_perm:[1,0,3,2] row_mask:0xf bank_mask:0xf
	v_mov_b32_dpp v224, v42 quad_perm:[1,0,3,2] row_mask:0xf bank_mask:0xf
	v_mov_b32_dpp v225, v43 quad_perm:[1,0,3,2] row_mask:0xf bank_mask:0xf
	v_mov_b32_dpp v226, v44 quad_perm:[1,0,3,2] row_mask:0xf bank_mask:0xf
	v_mov_b32_dpp v227, v45 quad_perm:[1,0,3,2] row_mask:0xf bank_mask:0xf
	v_cndmask_b32_e32 v10, v224, v10, vcc
	v_cndmask_b32_e32 v11, v225, v11, vcc
	v_cndmask_b32_e32 v12, v226, v12, vcc
	v_cndmask_b32_e32 v13, v227, v13, vcc
	v_cndmask_b32_e32 v42, v42, v220, vcc
	v_cndmask_b32_e32 v43, v43, v221, vcc
	v_cndmask_b32_e32 v44, v44, v222, vcc
	v_cndmask_b32_e32 v45, v45, v223, vcc
	global_store_dwordx4 v[140:141], v[42:45], off offset:128
	global_store_dwordx4 v[142:143], v[10:13], off offset:128
	v_lshl_add_u64 v[140:141], v[140:141], 0, s[10:11]
	v_lshl_add_u64 v[142:143], v[142:143], 0, s[10:11]
	s_waitcnt vmcnt(27)
	v_permlane16_swap_b32_e32 v200, v202
	v_permlane16_swap_b32_e32 v201, v203
	v_lshlrev_b32_e32 v216, 16, v200
	v_and_b32_e32 v200, 0xffff0000, v200
	v_lshlrev_b32_e32 v217, 16, v201
	v_and_b32_e32 v201, 0xffff0000, v201
	v_fmac_f32_e32 v102, s45, v216
	v_fmac_f32_e32 v103, s45, v200
	v_fmac_f32_e32 v104, s45, v217
	v_fmac_f32_e32 v105, s45, v201
	v_lshlrev_b32_e32 v216, 16, v202
	v_and_b32_e32 v202, 0xffff0000, v202
	v_lshlrev_b32_e32 v217, 16, v203
	v_and_b32_e32 v203, 0xffff0000, v203
	v_fmac_f32_e32 v70, s45, v216
	v_fmac_f32_e32 v71, s45, v202
	v_fmac_f32_e32 v72, s45, v217
	v_fmac_f32_e32 v73, s45, v203
	v_mov_b32_dpp v220, v70 quad_perm:[1,0,3,2] row_mask:0xf bank_mask:0xf
	v_mov_b32_dpp v221, v71 quad_perm:[1,0,3,2] row_mask:0xf bank_mask:0xf
	v_mov_b32_dpp v222, v72 quad_perm:[1,0,3,2] row_mask:0xf bank_mask:0xf
	v_mov_b32_dpp v223, v73 quad_perm:[1,0,3,2] row_mask:0xf bank_mask:0xf
	v_mov_b32_dpp v224, v102 quad_perm:[1,0,3,2] row_mask:0xf bank_mask:0xf
	v_mov_b32_dpp v225, v103 quad_perm:[1,0,3,2] row_mask:0xf bank_mask:0xf
	v_mov_b32_dpp v226, v104 quad_perm:[1,0,3,2] row_mask:0xf bank_mask:0xf
	v_mov_b32_dpp v227, v105 quad_perm:[1,0,3,2] row_mask:0xf bank_mask:0xf
	v_cndmask_b32_e32 v70, v224, v70, vcc
	v_cndmask_b32_e32 v71, v225, v71, vcc
	v_cndmask_b32_e32 v72, v226, v72, vcc
	v_cndmask_b32_e32 v73, v227, v73, vcc
	v_cndmask_b32_e32 v102, v102, v220, vcc
	v_cndmask_b32_e32 v103, v103, v221, vcc
	v_cndmask_b32_e32 v104, v104, v222, vcc
	v_cndmask_b32_e32 v105, v105, v223, vcc
	global_store_dwordx4 v[140:141], v[102:105], off
	global_store_dwordx4 v[142:143], v[70:73], off
	s_waitcnt vmcnt(28)
; DEVI unsigned pack2(float a, float b) { return __builtin_bit_cast(unsigned, __builtin_convertvector((f32x2_t){a, b}, bf16x2_t)); }
; DEVI float blo(unsigned u) { return __uint_as_float(u << 16); }
; DEVI float bhi(unsigned u) { return __uint_as_float(u & 0xffff0000u); }
; DEVI float siluf_(float x) { return x * __builtin_amdgcn_rcpf(1.f + __expf(-x)); }
; DEVI int xcd_first_tile() { return (blockIdx.x & 7) * (gridDim.x >> 3) + (blockIdx.x >> 3); }
;     ...
; #pragma unroll
;   for (int mf = 0; mf < 8; mf++) {
;     const int row = m0 + wm * 128 + mf * 16 + r16;
;     if (EPI == EPI_SWIGLU) {
; #pragma unroll
;       for (int nf = 0; nf < 2; nf++) {
;         const int hcol = (n0 >> 1) + wn * 32 + nf * 16 + quad * 4;
;         f32x4 g = acc[nf][mf], u = acc[nf + 2][mf];
;         u32x2 pk;
;         pk[0] = pack2(siluf_(g[0]) * u[0], siluf_(g[1]) * u[1]);
;         pk[1] = pack2(siluf_(g[2]) * u[2], siluf_(g[3]) * u[3]);
;         *(u32x2*)(outb + (size_t)row * DFF + hcol) = pk;
;       }
;     } else {
; #pragma unroll
;       for (int nf = 0; nf < 4; nf++) {
;         const int col = n0 + wn * 64 + nf * 16 + quad * 4;
;         f32x4 a = acc[nf][mf];
;         if (EPI == EPI_RESID || EPI == EPI_RESID_ATOMIC) {
;           f32x4 x = a;
;           if (EPI == EPI_RESID || kpart == 0) {
;             const u32x2 xr = *(const u32x2*)((const u16*)(p.ws + WS_XB) + (size_t)row * 1024 + col);
;             x[0] += ALPHA * blo(xr[0]); x[1] += ALPHA * bhi(xr[0]); x[2] += ALPHA * blo(xr[1]); x[3] += ALPHA * bhi(xr[1]);
;           }
;           if (EPI == EPI_RESID) *(f32x4*)((float*)(p.ws + WS_XF) + (size_t)row * 1024 + col) = x;
;           else *(f32x4*)((float*)(p.ws + WS_SLAB) + ((size_t)kpart * 512 + (row - T_P)) * 1024 + col) = x;
; DEVI void run_phase(const Params& p, int ph, char* smem) {
;     ...
;       for (int t = xcd_first_tile(); t < 512 + 16 * 11; t += xcd_tile_step()) {
;         if (t < 512) {
;           int mt_, nt_; tile_coords(t, 64, 8, mt_, nt_);
;           gemm_tile256<EPI_RESID>(p, hb, DFF, Bt, DFF, mt_ * 256, nt_ * 128, nullptr, 0, smem);
;         } else {
;           const int u_ = t - 512, tl_ = u_ / 11, q_ = u_ - tl_ * 11;
;           gemm_tile256<EPI_RESID_ATOMIC>(p, hb, DFF, Bt, DFF, (64 + (tl_ & 1)) * 256, (tl_ >> 1) * 128, nullptr, 0, smem, q_ * 256, 8, q_);
;         }
;       }
	v_permlane16_swap_b32_e32 v204, v206
	v_permlane16_swap_b32_e32 v205, v207
	v_lshlrev_b32_e32 v216, 16, v204
	v_and_b32_e32 v204, 0xffff0000, v204
	v_lshlrev_b32_e32 v217, 16, v205
	v_and_b32_e32 v205, 0xffff0000, v205
	v_fmac_f32_e32 v38, s45, v216
	v_fmac_f32_e32 v39, s45, v204
	v_fmac_f32_e32 v40, s45, v217
	v_fmac_f32_e32 v41, s45, v205
	v_lshlrev_b32_e32 v216, 16, v206
	v_and_b32_e32 v206, 0xffff0000, v206
	v_lshlrev_b32_e32 v217, 16, v207
	v_and_b32_e32 v207, 0xffff0000, v207
	v_fmac_f32_e32 v6, s45, v216
	v_fmac_f32_e32 v7, s45, v206
	v_fmac_f32_e32 v8, s45, v217
	v_fmac_f32_e32 v9, s45, v207
	v_mov_b32_dpp v220, v6 quad_perm:[1,0,3,2] row_mask:0xf bank_mask:0xf
	v_mov_b32_dpp v221, v7 quad_perm:[1,0,3,2] row_mask:0xf bank_mask:0xf
	v_mov_b32_dpp v222, v8 quad_perm:[1,0,3,2] row_mask:0xf bank_mask:0xf
	v_mov_b32_dpp v223, v9 quad_perm:[1,0,3,2] row_mask:0xf bank_mask:0xf
	v_mov_b32_dpp v224, v38 quad_perm:[1,0,3,2] row_mask:0xf bank_mask:0xf
	v_mov_b32_dpp v225, v39 quad_perm:[1,0,3,2] row_mask:0xf bank_mask:0xf
	v_mov_b32_dpp v226, v40 quad_perm:[1,0,3,2] row_mask:0xf bank_mask:0xf
	v_mov_b32_dpp v227, v41 quad_perm:[1,0,3,2] row_mask:0xf bank_mask:0xf
	v_cndmask_b32_e32 v6, v224, v6, vcc
	v_cndmask_b32_e32 v7, v225, v7, vcc
	v_cndmask_b32_e32 v8, v226, v8, vcc
	v_cndmask_b32_e32 v9, v227, v9, vcc
	v_cndmask_b32_e32 v38, v38, v220, vcc
	v_cndmask_b32_e32 v39, v39, v221, vcc
	v_cndmask_b32_e32 v40, v40, v222, vcc
	v_cndmask_b32_e32 v41, v41, v223, vcc
	global_store_dwordx4 v[140:141], v[38:41], off offset:128
	global_store_dwordx4 v[142:143], v[6:9], off offset:128
	v_lshl_add_u64 v[140:141], v[140:141], 0, s[10:11]
	v_lshl_add_u64 v[142:143], v[142:143], 0, s[10:11]
	s_waitcnt vmcnt(29)
	v_permlane16_swap_b32_e32 v208, v210
	v_permlane16_swap_b32_e32 v209, v211
	v_lshlrev_b32_e32 v216, 16, v208
	v_and_b32_e32 v208, 0xffff0000, v208
	v_lshlrev_b32_e32 v217, 16, v209
	v_and_b32_e32 v209, 0xffff0000, v209
	v_fmac_f32_e32 v98, s45, v216
	v_fmac_f32_e32 v99, s45, v208
	v_fmac_f32_e32 v100, s45, v217
	v_fmac_f32_e32 v101, s45, v209
	v_lshlrev_b32_e32 v216, 16, v210
	v_and_b32_e32 v210, 0xffff0000, v210
	v_lshlrev_b32_e32 v217, 16, v211
	v_and_b32_e32 v211, 0xffff0000, v211
	v_fmac_f32_e32 v66, s45, v216
	v_fmac_f32_e32 v67, s45, v210
	v_fmac_f32_e32 v68, s45, v217
	v_fmac_f32_e32 v69, s45, v211
	v_mov_b32_dpp v220, v66 quad_perm:[1,0,3,2] row_mask:0xf bank_mask:0xf
	v_mov_b32_dpp v221, v67 quad_perm:[1,0,3,2] row_mask:0xf bank_mask:0xf
	v_mov_b32_dpp v222, v68 quad_perm:[1,0,3,2] row_mask:0xf bank_mask:0xf
	v_mov_b32_dpp v223, v69 quad_perm:[1,0,3,2] row_mask:0xf bank_mask:0xf
	v_mov_b32_dpp v224, v98 quad_perm:[1,0,3,2] row_mask:0xf bank_mask:0xf
	v_mov_b32_dpp v225, v99 quad_perm:[1,0,3,2] row_mask:0xf bank_mask:0xf
	v_mov_b32_dpp v226, v100 quad_perm:[1,0,3,2] row_mask:0xf bank_mask:0xf
	v_mov_b32_dpp v227, v101 quad_perm:[1,0,3,2] row_mask:0xf bank_mask:0xf
	v_cndmask_b32_e32 v66, v224, v66, vcc
	v_cndmask_b32_e32 v67, v225, v67, vcc
	v_cndmask_b32_e32 v68, v226, v68, vcc
	v_cndmask_b32_e32 v69, v227, v69, vcc
	v_cndmask_b32_e32 v98, v98, v220, vcc
	v_cndmask_b32_e32 v99, v99, v221, vcc
	v_cndmask_b32_e32 v100, v100, v222, vcc
	v_cndmask_b32_e32 v101, v101, v223, vcc
	global_store_dwordx4 v[140:141], v[98:101], off
	global_store_dwordx4 v[142:143], v[66:69], off
	s_waitcnt vmcnt(30)
	v_permlane16_swap_b32_e32 v212, v214
	v_permlane16_swap_b32_e32 v213, v215
	v_lshlrev_b32_e32 v216, 16, v212
	v_and_b32_e32 v212, 0xffff0000, v212
	v_lshlrev_b32_e32 v217, 16, v213
	v_and_b32_e32 v213, 0xffff0000, v213
	v_fmac_f32_e32 v34, s45, v216
	v_fmac_f32_e32 v35, s45, v212
	v_fmac_f32_e32 v36, s45, v217
	v_fmac_f32_e32 v37, s45, v213
	v_lshlrev_b32_e32 v216, 16, v214
	v_and_b32_e32 v214, 0xffff0000, v214
	v_lshlrev_b32_e32 v217, 16, v215
	v_and_b32_e32 v215, 0xffff0000, v215
	v_fmac_f32_e32 v2, s45, v216
	v_fmac_f32_e32 v3, s45, v214
	v_fmac_f32_e32 v4, s45, v217
	v_fmac_f32_e32 v5, s45, v215
	v_mov_b32_dpp v220, v2 quad_perm:[1,0,3,2] row_mask:0xf bank_mask:0xf
	v_mov_b32_dpp v221, v3 quad_perm:[1,0,3,2] row_mask:0xf bank_mask:0xf
	v_mov_b32_dpp v222, v4 quad_perm:[1,0,3,2] row_mask:0xf bank_mask:0xf
	v_mov_b32_dpp v223, v5 quad_perm:[1,0,3,2] row_mask:0xf bank_mask:0xf
	v_mov_b32_dpp v224, v34 quad_perm:[1,0,3,2] row_mask:0xf bank_mask:0xf
	v_mov_b32_dpp v225, v35 quad_perm:[1,0,3,2] row_mask:0xf bank_mask:0xf
	v_mov_b32_dpp v226, v36 quad_perm:[1,0,3,2] row_mask:0xf bank_mask:0xf
	v_mov_b32_dpp v227, v37 quad_perm:[1,0,3,2] row_mask:0xf bank_mask:0xf
	v_cndmask_b32_e32 v2, v224, v2, vcc
	v_cndmask_b32_e32 v3, v225, v3, vcc
	v_cndmask_b32_e32 v4, v226, v4, vcc
	v_cndmask_b32_e32 v5, v227, v5, vcc
	v_cndmask_b32_e32 v34, v34, v220, vcc
	v_cndmask_b32_e32 v35, v35, v221, vcc
	v_cndmask_b32_e32 v36, v36, v222, vcc
	v_cndmask_b32_e32 v37, v37, v223, vcc
	global_store_dwordx4 v[140:141], v[34:37], off offset:128
	global_store_dwordx4 v[142:143], v[2:5], off offset:128
	v_readlane_b32 s40, v250, 7
	s_cmpk_lg_u32 s40, 0x200
	s_cbranch_scc1 .LBB0_757
	v_readlane_b32 s41, v250, 0
	s_lshr_b32 s42, s41, 3
	s_and_b32 s41, s41, 7
	s_mul_i32 s41, s41, 16
	s_add_i32 s41, s41, s42
	s_cmp_lt_u32 s42, 16
	s_movk_i32 s39, 0x4000
	s_branch .LBB0_757
